# gate loops: row loads software-pipelined one row ahead (no store-ack in the wait chain); mlstm_scan n-state recurrence with hoisted loads; ssd_local conv tap prefetch
# speedup vs baseline: 1.0883x; 1.0354x over previous
.LBB0_220:
	s_andn2_saveexec_b64 s[12:13], s[12:13]
	v_lshl_add_u32 v8, v16, 3, s71
	s_or_b64 exec, exec, s[12:13]
	v_ashrrev_i32_e32 v9, 31, v8
	v_lshlrev_b64 v[10:11], 2, v[8:9]
	v_lshl_add_u64 v[0:1], s[78:79], 0, v[10:11]
	global_load_dwordx4 v[4:7], v[0:1], off
	s_nop 0
	global_load_dwordx4 v[0:3], v[0:1], off offset:16
	v_mov_b64_e32 v[12:13], s[6:7]
	v_mad_i64_i32 v[12:13], s[12:13], v15, s54, v[12:13]
	v_add_u32_e32 v17, s68, v15
	v_lshl_add_u64 v[10:11], s[92:93], 0, v[10:11]
	v_lshl_add_u64 v[12:13], v[8:9], 1, v[12:13]
	v_add_co_u32_e32 v248, vcc, 0x2800, v12
	s_nop 1
	v_addc_co_u32_e32 v249, vcc, 0, v13, vcc
	global_load_dwordx4 v[244:247], v[248:249], off
	v_add_co_u32_e32 v248, vcc, 0xffffca00, v248
	s_nop 1
	v_addc_co_u32_e32 v249, vcc, -1, v249, vcc
	global_load_dwordx4 v[244:247], v[248:249], off
	v_add_co_u32_e32 v248, vcc, 0xffffca00, v248
	s_nop 1
	v_addc_co_u32_e32 v249, vcc, -1, v249, vcc
	global_load_dwordx4 v[244:247], v[248:249], off
	v_add_co_u32_e32 v248, vcc, 0xffffca00, v248
	s_nop 1
	v_addc_co_u32_e32 v249, vcc, -1, v249, vcc
	global_load_dwordx4 v[244:247], v[248:249], off
	v_cmp_lt_i32_e32 vcc, 2, v17
	s_and_saveexec_b64 s[12:13], vcc
	s_cbranch_execnz .LBB0_232
	s_or_b64 exec, exec, s[12:13]
	v_cmp_lt_i32_e32 vcc, 1, v17
	s_and_saveexec_b64 s[12:13], vcc
	s_cbranch_execnz .LBB0_233

.LBB0_496:
	v_add_co_u32_e32 v0, vcc, 0xf3da0000, v36
	v_mov_b32_e32 v33, s3
	s_nop 0
	v_addc_co_u32_e32 v1, vcc, -1, v37, vcc
	global_load_dwordx4 v[46:49], v[0:1], off
	v_add_co_u32_e32 v0, vcc, 0xf3dc0000, v36
	s_mov_b32 s6, 0xfff20000
	s_nop 0
	v_addc_co_u32_e32 v1, vcc, -1, v37, vcc
	global_load_dwordx4 v[28:31], v[0:1], off
	v_add_co_u32_e32 v0, vcc, 0xf3de0000, v36
	s_add_i32 s2, s2, 8
	s_nop 0
	v_addc_co_u32_e32 v1, vcc, -1, v37, vcc
	global_load_dwordx4 v[24:27], v[0:1], off
	v_add_co_u32_e32 v0, vcc, 0xf3e00000, v36
	s_add_i32 s3, s3, 32
	s_nop 0
	v_addc_co_u32_e32 v1, vcc, -1, v37, vcc
	global_load_dwordx4 v[20:23], v[0:1], off
	v_add_co_u32_e32 v0, vcc, 0xf3e20000, v36
	s_cmp_gt_u32 s2, 23
	s_nop 0
	v_addc_co_u32_e32 v1, vcc, -1, v37, vcc
	global_load_dwordx4 v[16:19], v[0:1], off
	v_add_co_u32_e32 v0, vcc, 0xf3e40000, v36
	s_waitcnt vmcnt(4)
	v_lshlrev_b32_e32 v58, 16, v46
	v_addc_co_u32_e32 v1, vcc, -1, v37, vcc
	global_load_dwordx4 v[8:11], v[0:1], off
	v_add_co_u32_e32 v0, vcc, 0xf3e60000, v36
	v_and_b32_e32 v59, 0xffff0000, v46
	s_nop 0
	v_addc_co_u32_e32 v1, vcc, -1, v37, vcc
	global_load_dwordx4 v[4:7], v[0:1], off
	v_add_co_u32_e32 v0, vcc, 0xf3e80000, v36
	v_lshlrev_b32_e32 v46, 16, v47
	s_nop 0
	v_addc_co_u32_e32 v1, vcc, -1, v37, vcc
	global_load_dwordx4 v[0:3], v[0:1], off
	ds_read_b128 v[50:53], v33
	ds_read_b128 v[12:15], v33 offset:16
	ds_read_b128 v[54:57], v33 offset:128
	v_and_b32_e32 v47, 0xffff0000, v47
	v_lshlrev_b32_e32 v60, 16, v48
	v_and_b32_e32 v61, 0xffff0000, v48
	v_lshlrev_b32_e32 v48, 16, v49
	s_waitcnt lgkmcnt(0)
	v_pk_mul_f32 v[46:47], v[54:55], v[46:47] op_sel_hi:[0,1]
	v_and_b32_e32 v49, 0xffff0000, v49
	v_pk_fma_f32 v[44:45], v[44:45], v[50:51], v[46:47] op_sel_hi:[1,0,1]
	v_pk_mul_f32 v[46:47], v[54:55], v[60:61] op_sel_hi:[0,1]
	v_pk_mul_f32 v[58:59], v[54:55], v[58:59] op_sel_hi:[0,1]
	v_pk_fma_f32 v[46:47], v[40:41], v[50:51], v[46:47] op_sel_hi:[1,0,1]
	v_pk_mul_f32 v[40:41], v[54:55], v[48:49] op_sel_hi:[0,1]
	v_pk_fma_f32 v[42:43], v[42:43], v[50:51], v[58:59] op_sel_hi:[1,0,1]
	v_pk_fma_f32 v[48:49], v[38:39], v[50:51], v[40:41] op_sel_hi:[1,0,1]
	v_add_co_u32_e32 v58, vcc, s6, v36
	v_cvt_pk_bf16_f32 v38, v42, v43
	v_cvt_pk_bf16_f32 v39, v44, v45
	v_cvt_pk_bf16_f32 v40, v46, v47
	v_cvt_pk_bf16_f32 v41, v48, v49
	v_addc_co_u32_e32 v59, vcc, -1, v37, vcc
	global_store_dwordx4 v[58:59], v[38:41], off
	s_mov_b32 s6, 0xfff40000
	s_waitcnt vmcnt(7)
	v_lshlrev_b32_e32 v38, 16, v28
	v_and_b32_e32 v39, 0xffff0000, v28
	v_lshlrev_b32_e32 v28, 16, v29
	v_and_b32_e32 v29, 0xffff0000, v29
	v_lshlrev_b32_e32 v40, 16, v30
	v_and_b32_e32 v41, 0xffff0000, v30
	v_pk_mul_f32 v[38:39], v[54:55], v[38:39] op_sel:[1,0]
	v_pk_mul_f32 v[28:29], v[54:55], v[28:29] op_sel:[1,0]
	v_lshlrev_b32_e32 v30, 16, v31
	v_and_b32_e32 v31, 0xffff0000, v31
	v_pk_fma_f32 v[38:39], v[50:51], v[42:43], v[38:39] op_sel:[1,0,0]
	v_pk_fma_f32 v[42:43], v[50:51], v[44:45], v[28:29] op_sel:[1,0,0]
	v_pk_mul_f32 v[28:29], v[54:55], v[40:41] op_sel:[1,0]
	s_nop 0
	v_pk_fma_f32 v[40:41], v[50:51], v[46:47], v[28:29] op_sel:[1,0,0]
	v_pk_mul_f32 v[28:29], v[54:55], v[30:31] op_sel:[1,0]
	v_add_co_u32_e32 v46, vcc, s6, v36
	v_pk_fma_f32 v[44:45], v[50:51], v[48:49], v[28:29] op_sel:[1,0,0]
	v_cvt_pk_bf16_f32 v28, v38, v39
	v_cvt_pk_bf16_f32 v29, v42, v43
	v_cvt_pk_bf16_f32 v30, v40, v41
	v_cvt_pk_bf16_f32 v31, v44, v45
	v_addc_co_u32_e32 v47, vcc, -1, v37, vcc
	global_store_dwordx4 v[46:47], v[28:31], off
	s_mov_b32 s6, 0xfff60000
	s_waitcnt vmcnt(6)
	v_lshlrev_b32_e32 v47, 16, v23
	v_lshlrev_b32_e32 v28, 16, v24
	v_and_b32_e32 v29, 0xffff0000, v24
	v_lshlrev_b32_e32 v24, 16, v25
	v_and_b32_e32 v25, 0xffff0000, v25
	v_lshlrev_b32_e32 v30, 16, v26
	v_and_b32_e32 v31, 0xffff0000, v26
	v_lshlrev_b32_e32 v26, 16, v27
	v_pk_mul_f32 v[28:29], v[56:57], v[28:29] op_sel_hi:[0,1]
	v_pk_mul_f32 v[24:25], v[56:57], v[24:25] op_sel_hi:[0,1]
	v_and_b32_e32 v27, 0xffff0000, v27
	v_pk_fma_f32 v[28:29], v[52:53], v[38:39], v[28:29] op_sel_hi:[0,1,1]
	v_pk_fma_f32 v[38:39], v[52:53], v[42:43], v[24:25] op_sel_hi:[0,1,1]
	v_pk_mul_f32 v[24:25], v[56:57], v[30:31] op_sel_hi:[0,1]
	v_mul_f32_e32 v30, v56, v26
	v_mov_b32_e32 v42, v52
	v_mov_b32_e32 v43, v56
	v_mov_b32_e32 v26, v45
	v_pk_mul_f32 v[26:27], v[42:43], v[26:27]
	v_pk_fma_f32 v[40:41], v[52:53], v[40:41], v[24:25] op_sel_hi:[0,1,1]
	v_mul_f32_e32 v24, v52, v44
	v_mov_b32_e32 v25, v26
	v_mov_b32_e32 v31, v27
	v_pk_add_f32 v[42:43], v[24:25], v[30:31]
	v_add_co_u32_e32 v30, vcc, s6, v36
	v_cvt_pk_bf16_f32 v24, v28, v29
	v_cvt_pk_bf16_f32 v25, v38, v39
	v_cvt_pk_bf16_f32 v26, v40, v41
	v_cvt_pk_bf16_f32 v27, v42, v43
	v_addc_co_u32_e32 v31, vcc, -1, v37, vcc
	global_store_dwordx4 v[30:31], v[24:27], off
	v_mov_b32_e32 v46, v57
	v_lshlrev_b32_e32 v44, 16, v22
	v_lshlrev_b32_e32 v24, 16, v20
	v_and_b32_e32 v25, 0xffff0000, v20
	v_lshlrev_b32_e32 v20, 16, v21
	v_and_b32_e32 v21, 0xffff0000, v21
	v_and_b32_e32 v45, 0xffff0000, v22
	v_and_b32_e32 v23, 0xffff0000, v23
	v_mov_b32_e32 v22, v53
	v_pk_mul_f32 v[20:21], v[46:47], v[20:21] op_sel_hi:[0,1]
	v_pk_mul_f32 v[24:25], v[46:47], v[24:25] op_sel_hi:[0,1]
	v_pk_fma_f32 v[26:27], v[22:23], v[38:39], v[20:21] op_sel_hi:[0,1,1]
	v_pk_mul_f32 v[20:21], v[46:47], v[44:45] op_sel_hi:[0,1]
	v_pk_fma_f32 v[30:31], v[22:23], v[28:29], v[24:25] op_sel_hi:[0,1,1]
	v_pk_fma_f32 v[24:25], v[22:23], v[40:41], v[20:21] op_sel_hi:[0,1,1]
	v_mov_b32_e32 v56, v53
	v_mov_b32_e32 v22, v43
	v_pk_mul_f32 v[22:23], v[56:57], v[22:23]
	v_mul_f32_e32 v20, v53, v42
	v_mul_f32_e32 v28, v57, v47
	v_mov_b32_e32 v21, v22
	v_mov_b32_e32 v29, v23
	s_mov_b32 s6, 0xfff80000
	v_pk_add_f32 v[28:29], v[20:21], v[28:29]
	v_add_co_u32_e32 v38, vcc, s6, v36
	v_cvt_pk_bf16_f32 v20, v30, v31
	v_cvt_pk_bf16_f32 v21, v26, v27
	v_cvt_pk_bf16_f32 v22, v24, v25
	v_cvt_pk_bf16_f32 v23, v28, v29
	v_addc_co_u32_e32 v39, vcc, -1, v37, vcc
	global_store_dwordx4 v[38:39], v[20:23], off
	ds_read_b128 v[20:23], v33 offset:144
	s_waitcnt vmcnt(7)
	v_lshlrev_b32_e32 v38, 16, v16
	v_and_b32_e32 v39, 0xffff0000, v16
	v_lshlrev_b32_e32 v16, 16, v17
	v_and_b32_e32 v17, 0xffff0000, v17
	v_lshlrev_b32_e32 v40, 16, v18
	v_and_b32_e32 v41, 0xffff0000, v18
	s_waitcnt lgkmcnt(0)
	v_pk_mul_f32 v[16:17], v[20:21], v[16:17] op_sel_hi:[0,1]
	v_lshlrev_b32_e32 v18, 16, v19
	v_pk_mul_f32 v[38:39], v[20:21], v[38:39] op_sel_hi:[0,1]
	v_pk_fma_f32 v[26:27], v[12:13], v[26:27], v[16:17] op_sel_hi:[0,1,1]
	v_pk_mul_f32 v[16:17], v[20:21], v[40:41] op_sel_hi:[0,1]
	v_and_b32_e32 v19, 0xffff0000, v19
	v_pk_fma_f32 v[30:31], v[12:13], v[30:31], v[38:39] op_sel_hi:[0,1,1]
	v_pk_fma_f32 v[24:25], v[12:13], v[24:25], v[16:17] op_sel_hi:[0,1,1]
	v_mul_f32_e32 v16, v12, v28
	v_mul_f32_e32 v28, v20, v18
	v_mov_b32_e32 v38, v12
	v_mov_b32_e32 v39, v20
	v_mov_b32_e32 v18, v29
	v_pk_mul_f32 v[18:19], v[38:39], v[18:19]
	s_mov_b32 s6, 0xfffa0000
	v_mov_b32_e32 v17, v18
	v_mov_b32_e32 v29, v19
	v_pk_add_f32 v[28:29], v[16:17], v[28:29]
	v_add_co_u32_e32 v38, vcc, s6, v36
	v_cvt_pk_bf16_f32 v16, v30, v31
	v_cvt_pk_bf16_f32 v17, v26, v27
	v_cvt_pk_bf16_f32 v18, v24, v25
	v_cvt_pk_bf16_f32 v19, v28, v29
	v_addc_co_u32_e32 v39, vcc, -1, v37, vcc
	global_store_dwordx4 v[38:39], v[16:19], off
	s_mov_b32 s6, 0xfffc0000
	s_waitcnt vmcnt(7)
	v_lshlrev_b32_e32 v16, 16, v8
	v_and_b32_e32 v17, 0xffff0000, v8
	v_lshlrev_b32_e32 v8, 16, v9
	v_and_b32_e32 v9, 0xffff0000, v9
	v_lshlrev_b32_e32 v18, 16, v10
	v_and_b32_e32 v19, 0xffff0000, v10
	v_pk_mul_f32 v[8:9], v[20:21], v[8:9] op_sel:[1,0]
	v_lshlrev_b32_e32 v10, 16, v11
	v_pk_mul_f32 v[16:17], v[20:21], v[16:17] op_sel:[1,0]
	v_pk_fma_f32 v[26:27], v[12:13], v[26:27], v[8:9] op_sel:[1,0,0]
	v_pk_mul_f32 v[8:9], v[20:21], v[18:19] op_sel:[1,0]
	v_and_b32_e32 v11, 0xffff0000, v11
	v_pk_fma_f32 v[16:17], v[12:13], v[30:31], v[16:17] op_sel:[1,0,0]
	v_pk_fma_f32 v[18:19], v[12:13], v[24:25], v[8:9] op_sel:[1,0,0]
	v_mul_f32_e32 v12, v21, v10
	v_mov_b32_e32 v20, v13
	v_mov_b32_e32 v10, v29
	v_pk_mul_f32 v[10:11], v[20:21], v[10:11]
	v_mul_f32_e32 v8, v13, v28
	v_mov_b32_e32 v9, v10
	v_mov_b32_e32 v13, v11
	v_pk_add_f32 v[12:13], v[8:9], v[12:13]
	v_add_co_u32_e32 v20, vcc, s6, v36
	v_cvt_pk_bf16_f32 v8, v16, v17
	v_cvt_pk_bf16_f32 v9, v26, v27
	v_cvt_pk_bf16_f32 v10, v18, v19
	v_cvt_pk_bf16_f32 v11, v12, v13
	v_addc_co_u32_e32 v21, vcc, -1, v37, vcc
	global_store_dwordx4 v[20:21], v[8:11], off
	s_mov_b32 s6, 0xfffe0000
	s_waitcnt vmcnt(7)
	v_lshlrev_b32_e32 v8, 16, v4
	v_and_b32_e32 v9, 0xffff0000, v4
	v_lshlrev_b32_e32 v4, 16, v5
	v_and_b32_e32 v5, 0xffff0000, v5
	v_lshlrev_b32_e32 v10, 16, v6
	v_and_b32_e32 v11, 0xffff0000, v6
	v_pk_mul_f32 v[8:9], v[22:23], v[8:9] op_sel_hi:[0,1]
	v_pk_mul_f32 v[4:5], v[22:23], v[4:5] op_sel_hi:[0,1]
	v_lshlrev_b32_e32 v6, 16, v7
	v_pk_fma_f32 v[8:9], v[14:15], v[16:17], v[8:9] op_sel_hi:[0,1,1]
	v_pk_fma_f32 v[16:17], v[14:15], v[26:27], v[4:5] op_sel_hi:[0,1,1]
	v_pk_mul_f32 v[4:5], v[22:23], v[10:11] op_sel_hi:[0,1]
	v_and_b32_e32 v7, 0xffff0000, v7
	v_pk_fma_f32 v[10:11], v[14:15], v[18:19], v[4:5] op_sel_hi:[0,1,1]
	v_mul_f32_e32 v4, v14, v12
	v_mul_f32_e32 v12, v22, v6
	v_mov_b32_e32 v18, v14
	v_mov_b32_e32 v19, v22
	v_mov_b32_e32 v6, v13
	v_pk_mul_f32 v[6:7], v[18:19], v[6:7]
	v_add_co_u32_e32 v18, vcc, s6, v36
	v_mov_b32_e32 v5, v6
	v_mov_b32_e32 v13, v7
	v_pk_add_f32 v[12:13], v[4:5], v[12:13]
	v_cvt_pk_bf16_f32 v4, v8, v9
	v_cvt_pk_bf16_f32 v5, v16, v17
	v_cvt_pk_bf16_f32 v6, v10, v11
	v_cvt_pk_bf16_f32 v7, v12, v13
	v_addc_co_u32_e32 v19, vcc, -1, v37, vcc
	global_store_dwordx4 v[18:19], v[4:7], off
	v_mov_b32_e32 v14, v23
	s_waitcnt vmcnt(7)
	v_lshlrev_b32_e32 v18, 16, v3
	v_lshlrev_b32_e32 v4, 16, v0
	v_and_b32_e32 v5, 0xffff0000, v0
	v_lshlrev_b32_e32 v0, 16, v1
	v_and_b32_e32 v1, 0xffff0000, v1
	v_lshlrev_b32_e32 v6, 16, v2
	v_and_b32_e32 v7, 0xffff0000, v2
	v_and_b32_e32 v3, 0xffff0000, v3
	v_mov_b32_e32 v2, v15
	v_pk_mul_f32 v[0:1], v[14:15], v[0:1] op_sel_hi:[0,1]
	v_pk_mul_f32 v[4:5], v[14:15], v[4:5] op_sel_hi:[0,1]
	v_pk_fma_f32 v[44:45], v[2:3], v[16:17], v[0:1] op_sel_hi:[0,1,1]
	v_pk_mul_f32 v[0:1], v[14:15], v[6:7] op_sel_hi:[0,1]
	v_pk_fma_f32 v[42:43], v[2:3], v[8:9], v[4:5] op_sel_hi:[0,1,1]
	v_pk_fma_f32 v[40:41], v[2:3], v[10:11], v[0:1] op_sel_hi:[0,1,1]
	v_mov_b32_e32 v22, v15
	v_mov_b32_e32 v2, v13
	v_pk_mul_f32 v[2:3], v[22:23], v[2:3]
	v_mul_f32_e32 v0, v15, v12
	v_mul_f32_e32 v4, v23, v18
	v_mov_b32_e32 v1, v2
	v_mov_b32_e32 v5, v3
	v_pk_add_f32 v[38:39], v[0:1], v[4:5]
	v_cvt_pk_bf16_f32 v0, v42, v43
	v_cvt_pk_bf16_f32 v1, v44, v45
	v_cvt_pk_bf16_f32 v2, v40, v41
	v_cvt_pk_bf16_f32 v3, v38, v39
	s_mov_b64 s[6:7], 0x100000
	global_store_dwordx4 v[36:37], v[0:3], off
	v_lshl_add_u64 v[36:37], v[36:37], 0, s[6:7]
	s_cbranch_scc0 .LBB0_496
	s_lshl_b32 s30, s70, 12
	v_lshl_add_u64 v[0:1], v[34:35], 0, s[30:31]
	s_add_i32 s2, s4, s96
	s_ashr_i32 s3, s2, 31
	v_alignbit_b32 v0, v1, v0, 8
	v_lshlrev_b32_e32 v1, 11, v32
	s_lshl_b64 s[6:7], s[2:3], 18
	v_readlane_b32 s8, v240, 48
	v_and_b32_e32 v1, 0xf800, v1
	s_add_u32 s6, s8, s6
	v_readlane_b32 s8, v240, 49
	v_add_u32_e32 v0, v1, v0
	s_addc_u32 s7, s8, s7
	v_ashrrev_i32_e32 v1, 31, v0
	v_lshl_add_u64 v[2:3], v[0:1], 2, s[6:7]
	global_store_dword v[2:3], v42, off
	global_store_dword v[2:3], v43, off offset:1024
	global_store_dword v[2:3], v44, off offset:2048
	global_store_dword v[2:3], v45, off offset:3072
	v_add_u32_e32 v2, 0x400, v0
	v_ashrrev_i32_e32 v3, 31, v2
	v_lshl_add_u64 v[2:3], v[2:3], 2, s[6:7]
	global_store_dword v[2:3], v40, off
	v_add_u32_e32 v2, 0x500, v0
	v_ashrrev_i32_e32 v3, 31, v2
	v_lshl_add_u64 v[2:3], v[2:3], 2, s[6:7]
	global_store_dword v[2:3], v41, off
	v_add_u32_e32 v2, 0x600, v0
	v_add_u32_e32 v0, 0x700, v0
	v_ashrrev_i32_e32 v3, 31, v2
	v_ashrrev_i32_e32 v1, 31, v0
	s_cmp_eq_u32 s70, 0
	s_movk_i32 s8, 0x100
	v_lshl_add_u64 v[2:3], v[2:3], 2, s[6:7]
	v_lshl_add_u64 v[0:1], v[0:1], 2, s[6:7]
	s_cselect_b64 s[6:7], -1, 0
	v_cmp_gt_i32_e32 vcc, s8, v32
	s_and_b64 s[8:9], s[6:7], vcc
	global_store_dword v[2:3], v38, off
	global_store_dword v[0:1], v39, off
	s_and_saveexec_b64 s[6:7], s[8:9]
	s_cbranch_execz .LBB0_427
	s_lshl_b64 s[4:5], s[4:5], 15
	v_readlane_b32 s8, v240, 28
	s_add_u32 s8, s8, s4
	v_readlane_b32 s9, v240, 29
	v_ashrrev_i32_e32 v33, 31, v32
	s_addc_u32 s9, s9, s5
	v_lshlrev_b64 v[8:9], 2, v[32:33]
	v_lshl_add_u64 v[12:13], s[8:9], 0, v[8:9]
	global_load_dword v0, v[12:13], off
	global_load_dword v1, v[12:13], off offset:1024
	global_load_dword v2, v[12:13], off offset:2048
	global_load_dword v3, v[12:13], off offset:3072
	v_add_co_u32_e32 v254, vcc, 0x1000, v12
	s_nop 1
	v_addc_co_u32_e32 v255, vcc, 0, v13, vcc
	global_load_dword v4, v[254:255], off
	global_load_dword v5, v[254:255], off offset:1024
	global_load_dword v6, v[254:255], off offset:2048
	global_load_dword v7, v[254:255], off offset:3072
	v_add_co_u32_e32 v254, vcc, 0x2000, v12
	s_nop 1
	v_addc_co_u32_e32 v255, vcc, 0, v13, vcc
	global_load_dword v14, v[254:255], off
	global_load_dword v15, v[254:255], off offset:1024
	global_load_dword v16, v[254:255], off offset:2048
	global_load_dword v17, v[254:255], off offset:3072
	v_add_co_u32_e32 v254, vcc, 0x3000, v12
	s_nop 1
	v_addc_co_u32_e32 v255, vcc, 0, v13, vcc
	global_load_dword v18, v[254:255], off
	global_load_dword v19, v[254:255], off offset:1024
	global_load_dword v20, v[254:255], off offset:2048
	global_load_dword v21, v[254:255], off offset:3072
	v_readlane_b32 s8, v240, 50
	s_add_u32 s4, s8, s4
	v_readlane_b32 s8, v240, 51
	s_addc_u32 s5, s8, s5
	v_lshl_add_u64 v[10:11], s[4:5], 0, v[8:9]
	s_lshl_b64 s[2:3], s[2:3], 10
	v_readlane_b32 s42, v241, 7
	v_readlane_b32 s43, v241, 8
	s_add_u32 s2, s42, s2
	s_addc_u32 s3, s43, s3
	v_mov_b32_e32 v252, 0
	s_waitcnt vmcnt(8)
	ds_read_b128 v[244:247], v169
	ds_read_b128 v[248:251], v169 offset:128
	s_waitcnt lgkmcnt(0)
	v_mul_f32_e32 v253, v248, v0
	v_fmac_f32_e32 v253, v252, v244
	v_mov_b32_e32 v252, v253
	v_mov_b32_e32 v254, v10
	v_mov_b32_e32 v255, v11
	global_store_dword v[254:255], v252, off
	v_mul_f32_e32 v253, v249, v1
	v_fmac_f32_e32 v253, v252, v245
	v_mov_b32_e32 v252, v253
	global_store_dword v[254:255], v252, off offset:1024
	v_mul_f32_e32 v253, v250, v2
	v_fmac_f32_e32 v253, v252, v246
	v_mov_b32_e32 v252, v253
	global_store_dword v[254:255], v252, off offset:2048
	v_mul_f32_e32 v253, v251, v3
	v_fmac_f32_e32 v253, v252, v247
	v_mov_b32_e32 v252, v253
	global_store_dword v[254:255], v252, off offset:3072
	ds_read_b128 v[244:247], v169 offset:16
	ds_read_b128 v[248:251], v169 offset:144
	s_waitcnt lgkmcnt(0)
	v_mul_f32_e32 v253, v248, v4
	v_fmac_f32_e32 v253, v252, v244
	v_mov_b32_e32 v252, v253
	v_add_co_u32_e32 v254, vcc, 0x1000, v10
	s_nop 1
	v_addc_co_u32_e32 v255, vcc, 0, v11, vcc
	global_store_dword v[254:255], v252, off
	v_mul_f32_e32 v253, v249, v5
	v_fmac_f32_e32 v253, v252, v245
	v_mov_b32_e32 v252, v253
	global_store_dword v[254:255], v252, off offset:1024
	v_mul_f32_e32 v253, v250, v6
	v_fmac_f32_e32 v253, v252, v246
	v_mov_b32_e32 v252, v253
	global_store_dword v[254:255], v252, off offset:2048
	v_mul_f32_e32 v253, v251, v7
	v_fmac_f32_e32 v253, v252, v247
	v_mov_b32_e32 v252, v253
	global_store_dword v[254:255], v252, off offset:3072
	s_nop 0
	v_add_co_u32_e32 v254, vcc, 0x4000, v12
	s_nop 1
	v_addc_co_u32_e32 v255, vcc, 0, v13, vcc
	global_load_dword v0, v[254:255], off
	global_load_dword v1, v[254:255], off offset:1024
	global_load_dword v2, v[254:255], off offset:2048
	global_load_dword v3, v[254:255], off offset:3072
	v_add_co_u32_e32 v254, vcc, 0x5000, v12
	s_nop 1
	v_addc_co_u32_e32 v255, vcc, 0, v13, vcc
	global_load_dword v4, v[254:255], off
	global_load_dword v5, v[254:255], off offset:1024
	global_load_dword v6, v[254:255], off offset:2048
	global_load_dword v7, v[254:255], off offset:3072
	s_waitcnt vmcnt(16)
	ds_read_b128 v[244:247], v169 offset:32
	ds_read_b128 v[248:251], v169 offset:160
	s_waitcnt lgkmcnt(0)
	v_mul_f32_e32 v253, v248, v14
	v_fmac_f32_e32 v253, v252, v244
	v_mov_b32_e32 v252, v253
	v_add_co_u32_e32 v254, vcc, 0x2000, v10
	s_nop 1
	v_addc_co_u32_e32 v255, vcc, 0, v11, vcc
	global_store_dword v[254:255], v252, off
	v_mul_f32_e32 v253, v249, v15
	v_fmac_f32_e32 v253, v252, v245
	v_mov_b32_e32 v252, v253
	global_store_dword v[254:255], v252, off offset:1024
	v_mul_f32_e32 v253, v250, v16
	v_fmac_f32_e32 v253, v252, v246
	v_mov_b32_e32 v252, v253
	global_store_dword v[254:255], v252, off offset:2048
	v_mul_f32_e32 v253, v251, v17
	v_fmac_f32_e32 v253, v252, v247
	v_mov_b32_e32 v252, v253
	global_store_dword v[254:255], v252, off offset:3072
	ds_read_b128 v[244:247], v169 offset:48
	ds_read_b128 v[248:251], v169 offset:176
	s_waitcnt lgkmcnt(0)
	v_mul_f32_e32 v253, v248, v18
	v_fmac_f32_e32 v253, v252, v244
	v_mov_b32_e32 v252, v253
	v_add_co_u32_e32 v254, vcc, 0x3000, v10
	s_nop 1
	v_addc_co_u32_e32 v255, vcc, 0, v11, vcc
	global_store_dword v[254:255], v252, off
	v_mul_f32_e32 v253, v249, v19
	v_fmac_f32_e32 v253, v252, v245
	v_mov_b32_e32 v252, v253
	global_store_dword v[254:255], v252, off offset:1024
	v_mul_f32_e32 v253, v250, v20
	v_fmac_f32_e32 v253, v252, v246
	v_mov_b32_e32 v252, v253
	global_store_dword v[254:255], v252, off offset:2048
	v_mul_f32_e32 v253, v251, v21
	v_fmac_f32_e32 v253, v252, v247
	v_mov_b32_e32 v252, v253
	global_store_dword v[254:255], v252, off offset:3072
	s_nop 0
	v_add_co_u32_e32 v254, vcc, 0x6000, v12
	s_nop 1
	v_addc_co_u32_e32 v255, vcc, 0, v13, vcc
	global_load_dword v14, v[254:255], off
	global_load_dword v15, v[254:255], off offset:1024
	global_load_dword v16, v[254:255], off offset:2048
	global_load_dword v17, v[254:255], off offset:3072
	v_add_co_u32_e32 v254, vcc, 0x7000, v12
	s_nop 1
	v_addc_co_u32_e32 v255, vcc, 0, v13, vcc
	global_load_dword v18, v[254:255], off
	global_load_dword v19, v[254:255], off offset:1024
	global_load_dword v20, v[254:255], off offset:2048
	global_load_dword v21, v[254:255], off offset:3072
	s_waitcnt vmcnt(16)
	ds_read_b128 v[244:247], v169 offset:64
	ds_read_b128 v[248:251], v169 offset:192
	s_waitcnt lgkmcnt(0)
	v_mul_f32_e32 v253, v248, v0
	v_fmac_f32_e32 v253, v252, v244
	v_mov_b32_e32 v252, v253
	v_add_co_u32_e32 v254, vcc, 0x4000, v10
	s_nop 1
	v_addc_co_u32_e32 v255, vcc, 0, v11, vcc
	global_store_dword v[254:255], v252, off
	v_mul_f32_e32 v253, v249, v1
	v_fmac_f32_e32 v253, v252, v245
	v_mov_b32_e32 v252, v253
	global_store_dword v[254:255], v252, off offset:1024
	v_mul_f32_e32 v253, v250, v2
	v_fmac_f32_e32 v253, v252, v246
	v_mov_b32_e32 v252, v253
	global_store_dword v[254:255], v252, off offset:2048
	v_mul_f32_e32 v253, v251, v3
	v_fmac_f32_e32 v253, v252, v247
	v_mov_b32_e32 v252, v253
	global_store_dword v[254:255], v252, off offset:3072
	ds_read_b128 v[244:247], v169 offset:80
	ds_read_b128 v[248:251], v169 offset:208
	s_waitcnt lgkmcnt(0)
	v_mul_f32_e32 v253, v248, v4
	v_fmac_f32_e32 v253, v252, v244
	v_mov_b32_e32 v252, v253
	v_add_co_u32_e32 v254, vcc, 0x5000, v10
	s_nop 1
	v_addc_co_u32_e32 v255, vcc, 0, v11, vcc
	global_store_dword v[254:255], v252, off
	v_mul_f32_e32 v253, v249, v5
	v_fmac_f32_e32 v253, v252, v245
	v_mov_b32_e32 v252, v253
	global_store_dword v[254:255], v252, off offset:1024
	v_mul_f32_e32 v253, v250, v6
	v_fmac_f32_e32 v253, v252, v246
	v_mov_b32_e32 v252, v253
	global_store_dword v[254:255], v252, off offset:2048
	v_mul_f32_e32 v253, v251, v7
	v_fmac_f32_e32 v253, v252, v247
	v_mov_b32_e32 v252, v253
	global_store_dword v[254:255], v252, off offset:3072
	s_waitcnt vmcnt(8)
	ds_read_b128 v[244:247], v169 offset:96
	ds_read_b128 v[248:251], v169 offset:224
	s_waitcnt lgkmcnt(0)
	v_mul_f32_e32 v253, v248, v14
	v_fmac_f32_e32 v253, v252, v244
	v_mov_b32_e32 v252, v253
	v_add_co_u32_e32 v254, vcc, 0x6000, v10
	s_nop 1
	v_addc_co_u32_e32 v255, vcc, 0, v11, vcc
	global_store_dword v[254:255], v252, off
	v_mul_f32_e32 v253, v249, v15
	v_fmac_f32_e32 v253, v252, v245
	v_mov_b32_e32 v252, v253
	global_store_dword v[254:255], v252, off offset:1024
	v_mul_f32_e32 v253, v250, v16
	v_fmac_f32_e32 v253, v252, v246
	v_mov_b32_e32 v252, v253
	global_store_dword v[254:255], v252, off offset:2048
	v_mul_f32_e32 v253, v251, v17
	v_fmac_f32_e32 v253, v252, v247
	v_mov_b32_e32 v252, v253
	global_store_dword v[254:255], v252, off offset:3072
	ds_read_b128 v[244:247], v169 offset:112
	ds_read_b128 v[248:251], v169 offset:240
	s_waitcnt lgkmcnt(0)
	v_mul_f32_e32 v253, v248, v18
	v_fmac_f32_e32 v253, v252, v244
	v_mov_b32_e32 v252, v253
	v_add_co_u32_e32 v254, vcc, 0x7000, v10
	s_nop 1
	v_addc_co_u32_e32 v255, vcc, 0, v11, vcc
	global_store_dword v[254:255], v252, off
	v_mul_f32_e32 v253, v249, v19
	v_fmac_f32_e32 v253, v252, v245
	v_mov_b32_e32 v252, v253
	global_store_dword v[254:255], v252, off offset:1024
	v_mul_f32_e32 v253, v250, v20
	v_fmac_f32_e32 v253, v252, v246
	v_mov_b32_e32 v252, v253
	global_store_dword v[254:255], v252, off offset:2048
	v_mul_f32_e32 v253, v251, v21
	v_fmac_f32_e32 v253, v252, v247
	v_mov_b32_e32 v252, v253
	global_store_dword v[254:255], v252, off offset:3072
	v_lshl_add_u64 v[0:1], s[2:3], 0, v[8:9]
	v_add_co_u32_e32 v0, vcc, 0x5000000, v0
	s_nop 1
	v_addc_co_u32_e32 v1, vcc, 0, v1, vcc
	global_store_dword v[0:1], v252, off
	s_branch .LBB0_427

.LBB0_1272:
	s_or_b64 exec, exec, s[14:15]
	v_readlane_b32 s2, v240, 46
	v_readlane_b32 s3, v240, 47
	v_mov_b64_e32 v[100:101], s[94:95]
	s_movk_i32 s15, 0x5600
	v_lshl_add_u64 v[98:99], s[2:3], 0, v[96:97]
	v_mad_i64_i32 v[102:103], s[2:3], v138, s15, v[100:101]
	v_lshl_add_u64 v[112:113], v[102:103], 0, v[96:97]
	global_load_dwordx4 v[106:109], v[112:113], off
	v_mov_b32_e32 v252, v112
	v_mov_b32_e32 v253, v113
	s_waitcnt vmcnt(3)
	v_pk_fma_f32 v[92:93], v[40:41], v[92:93], v[60:61]
	s_waitcnt vmcnt(1)
	v_pk_fma_f32 v[88:89], v[32:33], v[88:89], v[56:57]
	v_pk_fma_f32 v[92:93], v[48:49], v[68:69], v[92:93]
	v_pk_fma_f32 v[88:89], v[36:37], v[76:77], v[88:89]
	v_pk_fma_f32 v[90:91], v[34:35], v[90:91], v[58:59]
	v_pk_fma_f32 v[84:85], v[8:9], v[84:85], v[28:29]
	v_pk_fma_f32 v[90:91], v[38:39], v[78:79], v[90:91]
	v_pk_fma_f32 v[84:85], v[16:17], v[64:65], v[84:85]
	v_pk_fma_f32 v[80:81], v[0:1], v[80:81], v[24:25]
	v_pk_fma_f32 v[82:83], v[2:3], v[82:83], v[26:27]
	v_pk_fma_f32 v[80:81], v[4:5], v[72:73], v[80:81]
	v_pk_fma_f32 v[82:83], v[6:7], v[74:75], v[82:83]
	s_movk_i32 s14, 0x2b00
	v_pk_fma_f32 v[68:69], v[40:41], v[68:69], v[60:61]
	v_pk_fma_f32 v[76:77], v[32:33], v[76:77], v[56:57]
	v_pk_fma_f32 v[64:65], v[8:9], v[64:65], v[28:29]
	v_pk_fma_f32 v[72:73], v[0:1], v[72:73], v[24:25]
	v_pk_fma_f32 v[78:79], v[34:35], v[78:79], v[58:59]
	v_pk_fma_f32 v[74:75], v[2:3], v[74:75], v[26:27]
	v_add_u32_e32 v137, s58, v137
	v_add_u32_e32 v136, s68, v136
	s_waitcnt vmcnt(0)
	v_lshlrev_b32_e32 v104, 16, v108
	v_and_b32_e32 v105, 0xffff0000, v108
	v_add_co_u32_e32 v108, vcc, s75, v112
	v_lshlrev_b32_e32 v102, 16, v109
	v_and_b32_e32 v103, 0xffff0000, v109
	v_addc_co_u32_e32 v109, vcc, 0, v113, vcc
	global_load_dwordx4 v[118:121], v[108:109], off offset:2816
	v_add_co_u32_e32 v252, vcc, 0x5600, v252
	s_nop 1
	v_addc_co_u32_e32 v253, vcc, 0, v253, vcc
	global_load_dwordx4 v[244:247], v[252:253], off
	v_add_co_u32_e32 v248, vcc, 0x2b00, v252
	s_nop 1
	v_addc_co_u32_e32 v249, vcc, 0, v253, vcc
	global_load_dwordx4 v[248:251], v[248:249], off
	v_lshlrev_b32_e32 v110, 16, v106
	v_and_b32_e32 v111, 0xffff0000, v106
	v_pk_fma_f32 v[92:93], v[52:53], v[110:111], v[92:93]
	v_lshlrev_b32_e32 v106, 16, v107
	v_and_b32_e32 v107, 0xffff0000, v107
	v_pk_fma_f32 v[84:85], v[20:21], v[104:105], v[84:85]
	v_pk_fma_f32 v[68:69], v[48:49], v[110:111], v[68:69]
	v_pk_fma_f32 v[64:65], v[16:17], v[104:105], v[64:65]
	s_waitcnt vmcnt(0)
	v_lshlrev_b32_e32 v116, 16, v118
	v_and_b32_e32 v117, 0xffff0000, v118
	v_lshlrev_b32_e32 v114, 16, v119
	v_and_b32_e32 v115, 0xffff0000, v119
	v_mul_f32_e32 v118, 0xbfb8aa3b, v92
	v_mul_f32_e32 v119, 0xbfb8aa3b, v93
	v_exp_f32_e32 v118, v118
	v_exp_f32_e32 v119, v119
	v_pk_fma_f32 v[88:89], v[44:45], v[116:117], v[88:89]
	v_pk_fma_f32 v[90:91], v[46:47], v[114:115], v[90:91]
	v_add_f32_e32 v118, 1.0, v118
	v_add_f32_e32 v119, 1.0, v119
	v_rcp_f32_e32 v118, v118
	v_rcp_f32_e32 v119, v119
	v_lshlrev_b32_e32 v112, 16, v120
	v_and_b32_e32 v113, 0xffff0000, v120
	v_pk_fma_f32 v[80:81], v[12:13], v[112:113], v[80:81]
	v_pk_mul_f32 v[92:93], v[92:93], v[118:119]
	v_lshlrev_b32_e32 v108, 16, v121
	v_pk_mul_f32 v[88:89], v[88:89], v[92:93]
	v_pk_fma_f32 v[92:93], v[42:43], v[94:95], v[62:63]
	v_and_b32_e32 v109, 0xffff0000, v121
	v_pk_fma_f32 v[92:93], v[50:51], v[70:71], v[92:93]
	v_pk_fma_f32 v[82:83], v[14:15], v[108:109], v[82:83]
	v_pk_fma_f32 v[92:93], v[54:55], v[106:107], v[92:93]
	v_pk_fma_f32 v[70:71], v[42:43], v[70:71], v[62:63]
	v_mul_f32_e32 v94, 0xbfb8aa3b, v92
	v_mul_f32_e32 v95, 0xbfb8aa3b, v93
	v_exp_f32_e32 v94, v94
	v_exp_f32_e32 v95, v95
	v_pk_fma_f32 v[76:77], v[36:37], v[116:117], v[76:77]
	v_pk_fma_f32 v[70:71], v[50:51], v[106:107], v[70:71]
	v_add_f32_e32 v94, 1.0, v94
	v_add_f32_e32 v95, 1.0, v95
	v_rcp_f32_e32 v94, v94
	v_rcp_f32_e32 v95, v95
	v_pk_fma_f32 v[72:73], v[4:5], v[112:113], v[72:73]
	v_pk_fma_f32 v[78:79], v[38:39], v[114:115], v[78:79]
	v_pk_fma_f32 v[74:75], v[6:7], v[108:109], v[74:75]
	v_pk_mul_f32 v[92:93], v[92:93], v[94:95]
	v_or_b32_e32 v94, 1, v138
	v_pk_mul_f32 v[90:91], v[90:91], v[92:93]
	v_mul_f32_e32 v92, 0xbfb8aa3b, v84
	v_mul_f32_e32 v93, 0xbfb8aa3b, v85
	v_exp_f32_e32 v92, v92
	v_exp_f32_e32 v93, v93
	v_add_f32_e32 v92, 1.0, v92
	v_add_f32_e32 v93, 1.0, v93
	v_rcp_f32_e32 v92, v92
	v_rcp_f32_e32 v93, v93
	s_nop 0
	v_pk_mul_f32 v[84:85], v[84:85], v[92:93]
	s_nop 0
	v_pk_mul_f32 v[84:85], v[80:81], v[84:85]
	v_pk_fma_f32 v[80:81], v[10:11], v[86:87], v[30:31]
	s_nop 0
	v_pk_fma_f32 v[80:81], v[18:19], v[66:67], v[80:81]
	s_nop 0
	v_pk_fma_f32 v[80:81], v[22:23], v[102:103], v[80:81]
	s_nop 0
	v_mul_f32_e32 v86, 0xbfb8aa3b, v80
	v_mul_f32_e32 v87, 0xbfb8aa3b, v81
	v_exp_f32_e32 v86, v86
	v_exp_f32_e32 v87, v87
	v_add_f32_e32 v86, 1.0, v86
	v_add_f32_e32 v87, 1.0, v87
	v_rcp_f32_e32 v86, v86
	v_rcp_f32_e32 v87, v87
	s_nop 0
	v_pk_mul_f32 v[80:81], v[80:81], v[86:87]
	s_nop 0
	v_pk_mul_f32 v[86:87], v[82:83], v[80:81]
	v_cvt_pk_bf16_f32 v80, v88, v89
	v_cvt_pk_bf16_f32 v81, v90, v91
	v_cvt_pk_bf16_f32 v82, v84, v85
	v_cvt_pk_bf16_f32 v83, v86, v87
	v_mad_i64_i32 v[84:85], s[2:3], v138, s14, v[98:99]
	global_store_dwordx4 v[84:85], v[80:83], off
	s_nop 1
	v_mad_i64_i32 v[80:81], s[2:3], v94, s15, v[100:101]
	v_lshl_add_u64 v[92:93], v[80:81], 0, v[96:97]
	s_waitcnt vmcnt(1)
	v_mov_b32_e32 v80, v244
	v_mov_b32_e32 v81, v245
	v_mov_b32_e32 v82, v246
	v_mov_b32_e32 v83, v247
	v_lshlrev_b32_e32 v90, 16, v80
	v_and_b32_e32 v91, 0xffff0000, v80
	v_add_co_u32_e32 v80, vcc, s75, v92
	v_lshlrev_b32_e32 v88, 16, v81
	v_and_b32_e32 v89, 0xffff0000, v81
	v_addc_co_u32_e32 v81, vcc, 0, v93, vcc
	v_lshlrev_b32_e32 v86, 16, v82
	v_and_b32_e32 v87, 0xffff0000, v82
	v_lshlrev_b32_e32 v84, 16, v83
	v_and_b32_e32 v85, 0xffff0000, v83
	v_mov_b32_e32 v80, v248
	v_mov_b32_e32 v81, v249
	v_mov_b32_e32 v82, v250
	v_mov_b32_e32 v83, v251
	v_pk_fma_f32 v[68:69], v[52:53], v[90:91], v[68:69]
	v_pk_fma_f32 v[70:71], v[54:55], v[88:89], v[70:71]
	v_pk_fma_f32 v[64:65], v[20:21], v[86:87], v[64:65]
	v_or_b32_e32 v92, 2, v138
	v_add_co_u32_e32 v252, vcc, 0x5600, v252
	s_nop 1
	v_addc_co_u32_e32 v253, vcc, 0, v253, vcc
	global_load_dwordx4 v[244:247], v[252:253], off
	v_add_co_u32_e32 v248, vcc, 0x2b00, v252
	s_nop 1
	v_addc_co_u32_e32 v249, vcc, 0, v253, vcc
	global_load_dwordx4 v[248:251], v[248:249], off
	v_lshlrev_b32_e32 v132, 16, v80
	v_and_b32_e32 v133, 0xffff0000, v80
	v_lshlrev_b32_e32 v128, 16, v81
	v_and_b32_e32 v129, 0xffff0000, v81
	v_mul_f32_e32 v80, 0xbfb8aa3b, v68
	v_mul_f32_e32 v81, 0xbfb8aa3b, v69
	v_exp_f32_e32 v80, v80
	v_exp_f32_e32 v81, v81
	v_pk_fma_f32 v[76:77], v[44:45], v[132:133], v[76:77]
	v_lshlrev_b32_e32 v124, 16, v82
	v_add_f32_e32 v80, 1.0, v80
	v_add_f32_e32 v81, 1.0, v81
	v_rcp_f32_e32 v80, v80
	v_rcp_f32_e32 v81, v81
	v_and_b32_e32 v125, 0xffff0000, v82
	v_pk_fma_f32 v[72:73], v[12:13], v[124:125], v[72:73]
	v_lshlrev_b32_e32 v120, 16, v83
	v_pk_mul_f32 v[68:69], v[68:69], v[80:81]
	v_and_b32_e32 v121, 0xffff0000, v83
	v_pk_mul_f32 v[68:69], v[76:77], v[68:69]
	v_mul_f32_e32 v76, 0xbfb8aa3b, v70
	v_mul_f32_e32 v77, 0xbfb8aa3b, v71
	v_exp_f32_e32 v76, v76
	v_exp_f32_e32 v77, v77
	v_pk_fma_f32 v[78:79], v[46:47], v[128:129], v[78:79]
	v_pk_fma_f32 v[74:75], v[14:15], v[120:121], v[74:75]
	v_add_f32_e32 v76, 1.0, v76
	v_add_f32_e32 v77, 1.0, v77
	v_rcp_f32_e32 v76, v76
	v_rcp_f32_e32 v77, v77
	v_pk_fma_f32 v[80:81], v[2:3], v[108:109], v[26:27]
	v_pk_mul_f32 v[70:71], v[70:71], v[76:77]
	v_mul_f32_e32 v76, 0xbfb8aa3b, v64
	v_mul_f32_e32 v77, 0xbfb8aa3b, v65
	v_exp_f32_e32 v76, v76
	v_exp_f32_e32 v77, v77
	v_pk_mul_f32 v[70:71], v[78:79], v[70:71]
	v_pk_fma_f32 v[80:81], v[6:7], v[120:121], v[80:81]
	v_add_f32_e32 v76, 1.0, v76
	v_add_f32_e32 v77, 1.0, v77
	v_rcp_f32_e32 v76, v76
	v_rcp_f32_e32 v77, v77
	s_nop 0
	v_pk_mul_f32 v[64:65], v[64:65], v[76:77]
	s_nop 0
	v_pk_mul_f32 v[72:73], v[72:73], v[64:65]
	v_pk_fma_f32 v[64:65], v[10:11], v[66:67], v[30:31]
	s_nop 0
	v_pk_fma_f32 v[64:65], v[18:19], v[102:103], v[64:65]
	s_nop 0
	v_pk_fma_f32 v[64:65], v[22:23], v[84:85], v[64:65]
	s_nop 0
	v_mul_f32_e32 v66, 0xbfb8aa3b, v64
	v_mul_f32_e32 v67, 0xbfb8aa3b, v65
	v_exp_f32_e32 v66, v66
	v_exp_f32_e32 v67, v67
	v_add_f32_e32 v66, 1.0, v66
	v_add_f32_e32 v67, 1.0, v67
	v_rcp_f32_e32 v66, v66
	v_rcp_f32_e32 v67, v67
	s_nop 0
	v_pk_mul_f32 v[64:65], v[64:65], v[66:67]
	s_nop 0
	v_pk_mul_f32 v[74:75], v[74:75], v[64:65]
	v_cvt_pk_bf16_f32 v64, v68, v69
	v_cvt_pk_bf16_f32 v65, v70, v71
	v_cvt_pk_bf16_f32 v66, v72, v73
	v_cvt_pk_bf16_f32 v67, v74, v75
	v_mad_i64_i32 v[68:69], s[2:3], v94, s14, v[98:99]
	global_store_dwordx4 v[68:69], v[64:67], off
	v_pk_fma_f32 v[70:71], v[34:35], v[114:115], v[58:59]
	v_pk_fma_f32 v[72:73], v[0:1], v[112:113], v[24:25]
	v_mad_i64_i32 v[64:65], s[2:3], v92, s15, v[100:101]
	v_lshl_add_u64 v[68:69], v[64:65], 0, v[96:97]
	s_waitcnt vmcnt(1)
	v_mov_b32_e32 v64, v244
	v_mov_b32_e32 v65, v245
	v_mov_b32_e32 v66, v246
	v_mov_b32_e32 v67, v247
	v_pk_fma_f32 v[70:71], v[38:39], v[128:129], v[70:71]
	v_pk_fma_f32 v[72:73], v[4:5], v[124:125], v[72:73]
	v_or_b32_e32 v114, 4, v138
	v_lshlrev_b32_e32 v82, 16, v64
	v_and_b32_e32 v83, 0xffff0000, v64
	v_add_co_u32_e32 v64, vcc, s75, v68
	v_lshlrev_b32_e32 v78, 16, v65
	v_and_b32_e32 v79, 0xffff0000, v65
	v_addc_co_u32_e32 v65, vcc, 0, v69, vcc
	v_lshlrev_b32_e32 v76, 16, v66
	v_and_b32_e32 v77, 0xffff0000, v66
	v_lshlrev_b32_e32 v74, 16, v67
	v_and_b32_e32 v75, 0xffff0000, v67
	v_mov_b32_e32 v64, v248
	v_mov_b32_e32 v65, v249
	v_mov_b32_e32 v66, v250
	v_mov_b32_e32 v67, v251
	v_pk_fma_f32 v[68:69], v[32:33], v[116:117], v[56:57]
	v_add_co_u32_e32 v252, vcc, 0x5600, v252
	s_nop 1
	v_addc_co_u32_e32 v253, vcc, 0, v253, vcc
	global_load_dwordx4 v[244:247], v[252:253], off
	v_add_co_u32_e32 v248, vcc, 0x2b00, v252
	s_nop 1
	v_addc_co_u32_e32 v249, vcc, 0, v253, vcc
	global_load_dwordx4 v[248:251], v[248:249], off
	v_lshlrev_b32_e32 v130, 16, v64
	v_and_b32_e32 v131, 0xffff0000, v64
	v_lshlrev_b32_e32 v126, 16, v65
	v_and_b32_e32 v127, 0xffff0000, v65
	v_pk_fma_f32 v[64:65], v[40:41], v[110:111], v[60:61]
	v_lshlrev_b32_e32 v122, 16, v66
	v_pk_fma_f32 v[64:65], v[48:49], v[90:91], v[64:65]
	v_and_b32_e32 v123, 0xffff0000, v66
	v_pk_fma_f32 v[64:65], v[52:53], v[82:83], v[64:65]
	v_lshlrev_b32_e32 v118, 16, v67
	v_and_b32_e32 v119, 0xffff0000, v67
	v_mul_f32_e32 v66, 0xbfb8aa3b, v64
	v_mul_f32_e32 v67, 0xbfb8aa3b, v65
	v_exp_f32_e32 v66, v66
	v_exp_f32_e32 v67, v67
	v_pk_fma_f32 v[68:69], v[36:37], v[132:133], v[68:69]
	v_pk_fma_f32 v[70:71], v[46:47], v[126:127], v[70:71]
	v_add_f32_e32 v66, 1.0, v66
	v_add_f32_e32 v67, 1.0, v67
	v_rcp_f32_e32 v66, v66
	v_rcp_f32_e32 v67, v67
	v_pk_fma_f32 v[68:69], v[44:45], v[130:131], v[68:69]
	v_pk_fma_f32 v[72:73], v[12:13], v[122:123], v[72:73]
	v_pk_fma_f32 v[80:81], v[14:15], v[118:119], v[80:81]
	v_pk_mul_f32 v[64:65], v[64:65], v[66:67]
	v_pk_fma_f32 v[66:67], v[42:43], v[106:107], v[62:63]
	v_pk_mul_f32 v[64:65], v[68:69], v[64:65]
	v_pk_fma_f32 v[66:67], v[50:51], v[88:89], v[66:67]
	v_cvt_pk_bf16_f32 v64, v64, v65
	v_pk_fma_f32 v[66:67], v[54:55], v[78:79], v[66:67]
	v_or_b32_e32 v106, 3, v138
	v_mul_f32_e32 v68, 0xbfb8aa3b, v66
	v_mul_f32_e32 v69, 0xbfb8aa3b, v67
	v_exp_f32_e32 v68, v68
	v_exp_f32_e32 v69, v69
	v_add_f32_e32 v68, 1.0, v68
	v_add_f32_e32 v69, 1.0, v69
	v_rcp_f32_e32 v68, v68
	v_rcp_f32_e32 v69, v69
	s_nop 0
	v_pk_mul_f32 v[66:67], v[66:67], v[68:69]
	v_pk_fma_f32 v[68:69], v[8:9], v[104:105], v[28:29]
	v_pk_mul_f32 v[66:67], v[70:71], v[66:67]
	v_pk_fma_f32 v[68:69], v[16:17], v[86:87], v[68:69]
	v_cvt_pk_bf16_f32 v65, v66, v67
	v_pk_fma_f32 v[68:69], v[20:21], v[76:77], v[68:69]
	v_pk_fma_f32 v[86:87], v[8:9], v[86:87], v[28:29]
	v_mul_f32_e32 v70, 0xbfb8aa3b, v68
	v_mul_f32_e32 v71, 0xbfb8aa3b, v69
	v_exp_f32_e32 v70, v70
	v_exp_f32_e32 v71, v71
	v_pk_fma_f32 v[86:87], v[16:17], v[76:77], v[86:87]
	v_pk_fma_f32 v[76:77], v[8:9], v[76:77], v[28:29]
	v_add_f32_e32 v70, 1.0, v70
	v_add_f32_e32 v71, 1.0, v71
	v_rcp_f32_e32 v70, v70
	v_rcp_f32_e32 v71, v71
	s_nop 0
	v_pk_mul_f32 v[68:69], v[68:69], v[70:71]
	v_pk_fma_f32 v[70:71], v[10:11], v[102:103], v[30:31]
	v_pk_mul_f32 v[68:69], v[72:73], v[68:69]
	v_pk_fma_f32 v[70:71], v[18:19], v[84:85], v[70:71]
	v_cvt_pk_bf16_f32 v66, v68, v69
	v_pk_fma_f32 v[70:71], v[22:23], v[74:75], v[70:71]
	v_mad_i64_i32 v[68:69], s[2:3], v92, s14, v[98:99]
	v_mul_f32_e32 v72, 0xbfb8aa3b, v70
	v_mul_f32_e32 v73, 0xbfb8aa3b, v71
	v_exp_f32_e32 v72, v72
	v_exp_f32_e32 v73, v73
	v_pk_fma_f32 v[84:85], v[10:11], v[84:85], v[30:31]
	v_add_f32_e32 v72, 1.0, v72
	v_add_f32_e32 v73, 1.0, v73
	v_rcp_f32_e32 v72, v72
	v_rcp_f32_e32 v73, v73
	v_pk_fma_f32 v[84:85], v[18:19], v[74:75], v[84:85]
	v_pk_fma_f32 v[74:75], v[10:11], v[74:75], v[30:31]
	v_pk_mul_f32 v[70:71], v[70:71], v[72:73]
	s_nop 0
	v_pk_mul_f32 v[70:71], v[80:81], v[70:71]
	s_nop 0
	v_cvt_pk_bf16_f32 v67, v70, v71
	global_store_dwordx4 v[68:69], v[64:67], off
	s_nop 1
	v_mad_i64_i32 v[64:65], s[2:3], v106, s15, v[100:101]
	v_lshl_add_u64 v[92:93], v[64:65], 0, v[96:97]
	s_waitcnt vmcnt(1)
	v_mov_b32_e32 v64, v244
	v_mov_b32_e32 v65, v245
	v_mov_b32_e32 v66, v246
	v_mov_b32_e32 v67, v247
	v_lshlrev_b32_e32 v80, 16, v64
	v_and_b32_e32 v81, 0xffff0000, v64
	v_add_co_u32_e32 v64, vcc, s75, v92
	v_lshlrev_b32_e32 v72, 16, v65
	v_and_b32_e32 v73, 0xffff0000, v65
	v_addc_co_u32_e32 v65, vcc, 0, v93, vcc
	v_lshlrev_b32_e32 v70, 16, v66
	v_and_b32_e32 v71, 0xffff0000, v66
	v_lshlrev_b32_e32 v68, 16, v67
	v_and_b32_e32 v69, 0xffff0000, v67
	v_mov_b32_e32 v64, v248
	v_mov_b32_e32 v65, v249
	v_mov_b32_e32 v66, v250
	v_mov_b32_e32 v67, v251
	v_pk_fma_f32 v[86:87], v[20:21], v[70:71], v[86:87]
	v_pk_fma_f32 v[84:85], v[22:23], v[68:69], v[84:85]
	v_pk_fma_f32 v[76:77], v[16:17], v[70:71], v[76:77]
	v_pk_fma_f32 v[74:75], v[18:19], v[68:69], v[74:75]
	v_pk_fma_f32 v[70:71], v[8:9], v[70:71], v[28:29]
	v_pk_fma_f32 v[68:69], v[10:11], v[68:69], v[30:31]
	v_add_co_u32_e32 v252, vcc, 0x5600, v252
	s_nop 1
	v_addc_co_u32_e32 v253, vcc, 0, v253, vcc
	global_load_dwordx4 v[244:247], v[252:253], off
	v_add_co_u32_e32 v248, vcc, 0x2b00, v252
	s_nop 1
	v_addc_co_u32_e32 v249, vcc, 0, v253, vcc
	global_load_dwordx4 v[248:251], v[248:249], off
	v_lshlrev_b32_e32 v104, 16, v64
	v_and_b32_e32 v105, 0xffff0000, v64
	v_lshlrev_b32_e32 v102, 16, v65
	v_and_b32_e32 v103, 0xffff0000, v65
	v_pk_fma_f32 v[64:65], v[40:41], v[90:91], v[60:61]
	v_lshlrev_b32_e32 v94, 16, v66
	v_pk_fma_f32 v[64:65], v[48:49], v[82:83], v[64:65]
	v_and_b32_e32 v95, 0xffff0000, v66
	v_pk_fma_f32 v[64:65], v[52:53], v[80:81], v[64:65]
	v_lshlrev_b32_e32 v92, 16, v67
	v_and_b32_e32 v93, 0xffff0000, v67
	v_mul_f32_e32 v66, 0xbfb8aa3b, v64
	v_mul_f32_e32 v67, 0xbfb8aa3b, v65
	v_exp_f32_e32 v66, v66
	v_exp_f32_e32 v67, v67
	v_pk_fma_f32 v[90:91], v[32:33], v[132:133], v[56:57]
	v_add_f32_e32 v66, 1.0, v66
	v_add_f32_e32 v67, 1.0, v67
	v_rcp_f32_e32 v66, v66
	v_rcp_f32_e32 v67, v67
	v_pk_fma_f32 v[90:91], v[36:37], v[130:131], v[90:91]
	v_pk_mul_f32 v[64:65], v[64:65], v[66:67]
	v_pk_fma_f32 v[66:67], v[42:43], v[88:89], v[62:63]
	v_pk_fma_f32 v[90:91], v[44:45], v[104:105], v[90:91]
	v_pk_fma_f32 v[66:67], v[50:51], v[78:79], v[66:67]
	v_pk_mul_f32 v[64:65], v[90:91], v[64:65]
	v_pk_fma_f32 v[66:67], v[54:55], v[72:73], v[66:67]
	v_pk_fma_f32 v[90:91], v[34:35], v[128:129], v[58:59]
	v_mul_f32_e32 v88, 0xbfb8aa3b, v66
	v_mul_f32_e32 v89, 0xbfb8aa3b, v67
	v_exp_f32_e32 v88, v88
	v_exp_f32_e32 v89, v89
	v_pk_fma_f32 v[90:91], v[38:39], v[126:127], v[90:91]
	v_cvt_pk_bf16_f32 v64, v64, v65
	v_add_f32_e32 v88, 1.0, v88
	v_add_f32_e32 v89, 1.0, v89
	v_rcp_f32_e32 v88, v88
	v_rcp_f32_e32 v89, v89
	v_pk_fma_f32 v[90:91], v[46:47], v[102:103], v[90:91]
	v_pk_mul_f32 v[66:67], v[66:67], v[88:89]
	v_mul_f32_e32 v88, 0xbfb8aa3b, v86
	v_mul_f32_e32 v89, 0xbfb8aa3b, v87
	v_exp_f32_e32 v88, v88
	v_exp_f32_e32 v89, v89
	v_pk_mul_f32 v[66:67], v[90:91], v[66:67]
	v_pk_fma_f32 v[90:91], v[0:1], v[124:125], v[24:25]
	v_add_f32_e32 v88, 1.0, v88
	v_add_f32_e32 v89, 1.0, v89
	v_rcp_f32_e32 v88, v88
	v_rcp_f32_e32 v89, v89
	v_pk_fma_f32 v[90:91], v[4:5], v[122:123], v[90:91]
	v_cvt_pk_bf16_f32 v65, v66, v67
	v_pk_fma_f32 v[90:91], v[12:13], v[94:95], v[90:91]
	v_pk_mul_f32 v[86:87], v[86:87], v[88:89]
	v_mul_f32_e32 v88, 0xbfb8aa3b, v84
	v_mul_f32_e32 v89, 0xbfb8aa3b, v85
	v_exp_f32_e32 v88, v88
	v_exp_f32_e32 v89, v89
	v_pk_mul_f32 v[86:87], v[90:91], v[86:87]
	v_pk_fma_f32 v[90:91], v[2:3], v[120:121], v[26:27]
	v_add_f32_e32 v88, 1.0, v88
	v_add_f32_e32 v89, 1.0, v89
	v_rcp_f32_e32 v88, v88
	v_rcp_f32_e32 v89, v89
	v_pk_fma_f32 v[90:91], v[6:7], v[118:119], v[90:91]
	v_cvt_pk_bf16_f32 v66, v86, v87
	v_pk_fma_f32 v[90:91], v[14:15], v[92:93], v[90:91]
	v_pk_mul_f32 v[84:85], v[84:85], v[88:89]
	v_or_b32_e32 v120, 5, v138
	v_pk_mul_f32 v[84:85], v[90:91], v[84:85]
	v_or_b32_e32 v124, 6, v138
	v_cvt_pk_bf16_f32 v67, v84, v85
	v_mad_i64_i32 v[84:85], s[2:3], v106, s14, v[98:99]
	global_store_dwordx4 v[84:85], v[64:67], off
	s_nop 1
	v_mad_i64_i32 v[64:65], s[2:3], v114, s15, v[100:101]
	v_lshl_add_u64 v[106:107], v[64:65], 0, v[96:97]
	s_waitcnt vmcnt(1)
	v_mov_b32_e32 v64, v244
	v_mov_b32_e32 v65, v245
	v_mov_b32_e32 v66, v246
	v_mov_b32_e32 v67, v247
	v_lshlrev_b32_e32 v90, 16, v64
	v_and_b32_e32 v91, 0xffff0000, v64
	v_add_co_u32_e32 v64, vcc, s75, v106
	v_lshlrev_b32_e32 v88, 16, v65
	v_and_b32_e32 v89, 0xffff0000, v65
	v_addc_co_u32_e32 v65, vcc, 0, v107, vcc
	v_lshlrev_b32_e32 v86, 16, v66
	v_and_b32_e32 v87, 0xffff0000, v66
	v_lshlrev_b32_e32 v84, 16, v67
	v_and_b32_e32 v85, 0xffff0000, v67
	v_mov_b32_e32 v64, v248
	v_mov_b32_e32 v65, v249
	v_mov_b32_e32 v66, v250
	v_mov_b32_e32 v67, v251
	v_pk_fma_f32 v[76:77], v[20:21], v[86:87], v[76:77]
	v_pk_fma_f32 v[74:75], v[22:23], v[84:85], v[74:75]
	v_pk_fma_f32 v[70:71], v[16:17], v[86:87], v[70:71]
	v_pk_fma_f32 v[68:69], v[18:19], v[84:85], v[68:69]
	v_pk_fma_f32 v[86:87], v[8:9], v[86:87], v[28:29]
	v_pk_fma_f32 v[84:85], v[10:11], v[84:85], v[30:31]
	v_add_co_u32_e32 v252, vcc, 0x5600, v252
	s_nop 1
	v_addc_co_u32_e32 v253, vcc, 0, v253, vcc
	global_load_dwordx4 v[244:247], v[252:253], off
	v_add_co_u32_e32 v248, vcc, 0x2b00, v252
	s_nop 1
	v_addc_co_u32_e32 v249, vcc, 0, v253, vcc
	global_load_dwordx4 v[248:251], v[248:249], off
	v_lshlrev_b32_e32 v112, 16, v64
	v_and_b32_e32 v113, 0xffff0000, v64
	v_lshlrev_b32_e32 v110, 16, v65
	v_and_b32_e32 v111, 0xffff0000, v65
	v_pk_fma_f32 v[64:65], v[40:41], v[82:83], v[60:61]
	v_lshlrev_b32_e32 v108, 16, v66
	v_pk_fma_f32 v[64:65], v[48:49], v[80:81], v[64:65]
	v_and_b32_e32 v109, 0xffff0000, v66
	v_pk_fma_f32 v[64:65], v[52:53], v[90:91], v[64:65]
	v_lshlrev_b32_e32 v106, 16, v67
	v_and_b32_e32 v107, 0xffff0000, v67
	v_mul_f32_e32 v66, 0xbfb8aa3b, v64
	v_mul_f32_e32 v67, 0xbfb8aa3b, v65
	v_exp_f32_e32 v66, v66
	v_exp_f32_e32 v67, v67
	v_pk_fma_f32 v[82:83], v[32:33], v[130:131], v[56:57]
	v_add_f32_e32 v66, 1.0, v66
	v_add_f32_e32 v67, 1.0, v67
	v_rcp_f32_e32 v66, v66
	v_rcp_f32_e32 v67, v67
	v_pk_fma_f32 v[82:83], v[36:37], v[104:105], v[82:83]
	v_pk_fma_f32 v[104:105], v[32:33], v[104:105], v[56:57]
	v_pk_fma_f32 v[82:83], v[44:45], v[112:113], v[82:83]
	v_pk_mul_f32 v[64:65], v[64:65], v[66:67]
	v_pk_fma_f32 v[66:67], v[42:43], v[78:79], v[62:63]
	v_pk_mul_f32 v[64:65], v[82:83], v[64:65]
	v_pk_fma_f32 v[66:67], v[50:51], v[72:73], v[66:67]
	v_pk_fma_f32 v[82:83], v[34:35], v[126:127], v[58:59]
	v_pk_fma_f32 v[66:67], v[54:55], v[88:89], v[66:67]
	v_pk_fma_f32 v[82:83], v[38:39], v[102:103], v[82:83]
	v_mul_f32_e32 v78, 0xbfb8aa3b, v66
	v_mul_f32_e32 v79, 0xbfb8aa3b, v67
	v_exp_f32_e32 v78, v78
	v_exp_f32_e32 v79, v79
	v_pk_fma_f32 v[82:83], v[46:47], v[110:111], v[82:83]
	v_cvt_pk_bf16_f32 v64, v64, v65
	v_add_f32_e32 v78, 1.0, v78
	v_add_f32_e32 v79, 1.0, v79
	v_rcp_f32_e32 v78, v78
	v_rcp_f32_e32 v79, v79
	v_pk_fma_f32 v[72:73], v[42:43], v[72:73], v[62:63]
	v_pk_fma_f32 v[102:103], v[34:35], v[102:103], v[58:59]
	v_pk_fma_f32 v[72:73], v[50:51], v[88:89], v[72:73]
	v_pk_mul_f32 v[66:67], v[66:67], v[78:79]
	v_mul_f32_e32 v78, 0xbfb8aa3b, v76
	v_mul_f32_e32 v79, 0xbfb8aa3b, v77
	v_exp_f32_e32 v78, v78
	v_exp_f32_e32 v79, v79
	v_pk_mul_f32 v[66:67], v[82:83], v[66:67]
	v_pk_fma_f32 v[82:83], v[0:1], v[122:123], v[24:25]
	v_add_f32_e32 v78, 1.0, v78
	v_add_f32_e32 v79, 1.0, v79
	v_rcp_f32_e32 v78, v78
	v_rcp_f32_e32 v79, v79
	v_pk_fma_f32 v[82:83], v[4:5], v[94:95], v[82:83]
	v_cvt_pk_bf16_f32 v65, v66, v67
	v_pk_fma_f32 v[82:83], v[12:13], v[108:109], v[82:83]
	v_pk_mul_f32 v[76:77], v[76:77], v[78:79]
	v_mul_f32_e32 v78, 0xbfb8aa3b, v74
	v_mul_f32_e32 v79, 0xbfb8aa3b, v75
	v_exp_f32_e32 v78, v78
	v_exp_f32_e32 v79, v79
	v_pk_mul_f32 v[76:77], v[82:83], v[76:77]
	v_pk_fma_f32 v[82:83], v[2:3], v[118:119], v[26:27]
	v_add_f32_e32 v78, 1.0, v78
	v_add_f32_e32 v79, 1.0, v79
	v_rcp_f32_e32 v78, v78
	v_rcp_f32_e32 v79, v79
	v_pk_fma_f32 v[82:83], v[6:7], v[92:93], v[82:83]
	v_cvt_pk_bf16_f32 v66, v76, v77
	v_pk_fma_f32 v[82:83], v[14:15], v[106:107], v[82:83]
	v_pk_mul_f32 v[74:75], v[74:75], v[78:79]
	v_pk_fma_f32 v[94:95], v[0:1], v[94:95], v[24:25]
	v_pk_mul_f32 v[74:75], v[82:83], v[74:75]
	v_pk_fma_f32 v[92:93], v[2:3], v[92:93], v[26:27]
	v_cvt_pk_bf16_f32 v67, v74, v75
	v_mad_i64_i32 v[74:75], s[2:3], v114, s14, v[98:99]
	global_store_dwordx4 v[74:75], v[64:67], off
	v_pk_fma_f32 v[104:105], v[36:37], v[112:113], v[104:105]
	v_pk_fma_f32 v[102:103], v[38:39], v[110:111], v[102:103]
	v_mad_i64_i32 v[64:65], s[2:3], v120, s15, v[100:101]
	v_lshl_add_u64 v[114:115], v[64:65], 0, v[96:97]
	s_waitcnt vmcnt(1)
	v_mov_b32_e32 v64, v244
	v_mov_b32_e32 v65, v245
	v_mov_b32_e32 v66, v246
	v_mov_b32_e32 v67, v247
	v_pk_fma_f32 v[94:95], v[4:5], v[108:109], v[94:95]
	v_pk_fma_f32 v[92:93], v[6:7], v[106:107], v[92:93]
	v_pk_fma_f32 v[88:89], v[42:43], v[88:89], v[62:63]
	v_pk_fma_f32 v[112:113], v[32:33], v[112:113], v[56:57]
	v_pk_fma_f32 v[110:111], v[34:35], v[110:111], v[58:59]
	v_pk_fma_f32 v[108:109], v[0:1], v[108:109], v[24:25]
	v_pk_fma_f32 v[106:107], v[2:3], v[106:107], v[26:27]
	v_lshlrev_b32_e32 v82, 16, v64
	v_and_b32_e32 v83, 0xffff0000, v64
	v_add_co_u32_e32 v64, vcc, s75, v114
	v_lshlrev_b32_e32 v78, 16, v65
	v_and_b32_e32 v79, 0xffff0000, v65
	v_addc_co_u32_e32 v65, vcc, 0, v115, vcc
	v_lshlrev_b32_e32 v76, 16, v66
	v_and_b32_e32 v77, 0xffff0000, v66
	v_lshlrev_b32_e32 v74, 16, v67
	v_and_b32_e32 v75, 0xffff0000, v67
	v_mov_b32_e32 v64, v248
	v_mov_b32_e32 v65, v249
	v_mov_b32_e32 v66, v250
	v_mov_b32_e32 v67, v251
	v_pk_fma_f32 v[72:73], v[54:55], v[78:79], v[72:73]
	v_pk_fma_f32 v[70:71], v[20:21], v[76:77], v[70:71]
	v_pk_fma_f32 v[68:69], v[22:23], v[74:75], v[68:69]
	v_pk_fma_f32 v[88:89], v[50:51], v[78:79], v[88:89]
	v_pk_fma_f32 v[86:87], v[16:17], v[76:77], v[86:87]
	v_pk_fma_f32 v[84:85], v[18:19], v[74:75], v[84:85]
	v_pk_fma_f32 v[8:9], v[8:9], v[76:77], v[28:29]
	v_add_co_u32_e32 v252, vcc, 0x5600, v252
	s_nop 1
	v_addc_co_u32_e32 v253, vcc, 0, v253, vcc
	global_load_dwordx4 v[244:247], v[252:253], off
	v_add_co_u32_e32 v248, vcc, 0x2b00, v252
	s_nop 1
	v_addc_co_u32_e32 v249, vcc, 0, v253, vcc
	global_load_dwordx4 v[248:251], v[248:249], off
	v_lshlrev_b32_e32 v118, 16, v64
	v_and_b32_e32 v119, 0xffff0000, v64
	v_lshlrev_b32_e32 v116, 16, v65
	v_and_b32_e32 v117, 0xffff0000, v65
	v_lshlrev_b32_e32 v114, 16, v66
	v_and_b32_e32 v115, 0xffff0000, v66
	v_lshlrev_b32_e32 v64, 16, v67
	v_and_b32_e32 v65, 0xffff0000, v67
	v_pk_fma_f32 v[66:67], v[40:41], v[80:81], v[60:61]
	v_pk_fma_f32 v[104:105], v[44:45], v[118:119], v[104:105]
	v_pk_fma_f32 v[66:67], v[48:49], v[90:91], v[66:67]
	v_pk_fma_f32 v[102:103], v[46:47], v[116:117], v[102:103]
	v_pk_fma_f32 v[66:67], v[52:53], v[82:83], v[66:67]
	v_pk_fma_f32 v[94:95], v[12:13], v[114:115], v[94:95]
	v_mul_f32_e32 v80, 0xbfb8aa3b, v66
	v_mul_f32_e32 v81, 0xbfb8aa3b, v67
	v_exp_f32_e32 v80, v80
	v_exp_f32_e32 v81, v81
	v_pk_fma_f32 v[92:93], v[14:15], v[64:65], v[92:93]
	v_pk_fma_f32 v[90:91], v[40:41], v[90:91], v[60:61]
	v_add_f32_e32 v80, 1.0, v80
	v_add_f32_e32 v81, 1.0, v81
	v_rcp_f32_e32 v80, v80
	v_rcp_f32_e32 v81, v81
	v_pk_fma_f32 v[90:91], v[48:49], v[82:83], v[90:91]
	v_pk_fma_f32 v[112:113], v[36:37], v[118:119], v[112:113]
	v_pk_fma_f32 v[110:111], v[38:39], v[116:117], v[110:111]
	v_pk_mul_f32 v[66:67], v[66:67], v[80:81]
	v_mul_f32_e32 v80, 0xbfb8aa3b, v72
	v_mul_f32_e32 v81, 0xbfb8aa3b, v73
	v_exp_f32_e32 v80, v80
	v_exp_f32_e32 v81, v81
	v_pk_mul_f32 v[66:67], v[104:105], v[66:67]
	v_pk_fma_f32 v[108:109], v[4:5], v[114:115], v[108:109]
	v_add_f32_e32 v80, 1.0, v80
	v_add_f32_e32 v81, 1.0, v81
	v_rcp_f32_e32 v80, v80
	v_rcp_f32_e32 v81, v81
	v_cvt_pk_bf16_f32 v66, v66, v67
	v_pk_fma_f32 v[106:107], v[6:7], v[64:65], v[106:107]
	v_pk_fma_f32 v[40:41], v[40:41], v[82:83], v[60:61]
	v_pk_mul_f32 v[72:73], v[72:73], v[80:81]
	v_mul_f32_e32 v80, 0xbfb8aa3b, v70
	v_mul_f32_e32 v81, 0xbfb8aa3b, v71
	v_exp_f32_e32 v80, v80
	v_exp_f32_e32 v81, v81
	v_pk_mul_f32 v[72:73], v[102:103], v[72:73]
	v_pk_fma_f32 v[0:1], v[0:1], v[114:115], v[24:25]
	v_add_f32_e32 v80, 1.0, v80
	v_add_f32_e32 v81, 1.0, v81
	v_rcp_f32_e32 v80, v80
	v_rcp_f32_e32 v81, v81
	v_cvt_pk_bf16_f32 v67, v72, v73
	v_pk_fma_f32 v[32:33], v[32:33], v[118:119], v[56:57]
	v_pk_fma_f32 v[2:3], v[2:3], v[64:65], v[26:27]
	v_pk_mul_f32 v[70:71], v[70:71], v[80:81]
	v_mul_f32_e32 v80, 0xbfb8aa3b, v68
	v_mul_f32_e32 v81, 0xbfb8aa3b, v69
	v_exp_f32_e32 v80, v80
	v_exp_f32_e32 v81, v81
	v_pk_mul_f32 v[70:71], v[94:95], v[70:71]
	v_pk_fma_f32 v[34:35], v[34:35], v[116:117], v[58:59]
	v_add_f32_e32 v80, 1.0, v80
	v_add_f32_e32 v81, 1.0, v81
	v_rcp_f32_e32 v80, v80
	v_rcp_f32_e32 v81, v81
	s_nop 0
	v_pk_mul_f32 v[68:69], v[68:69], v[80:81]
	s_nop 0
	v_pk_mul_f32 v[80:81], v[92:93], v[68:69]
	v_cvt_pk_bf16_f32 v68, v70, v71
	v_cvt_pk_bf16_f32 v69, v80, v81
	v_mad_i64_i32 v[70:71], s[2:3], v120, s14, v[98:99]
	global_store_dwordx4 v[70:71], v[66:69], off
	s_nop 1
	v_mad_i64_i32 v[66:67], s[2:3], v124, s15, v[100:101]
	v_lshl_add_u64 v[80:81], v[66:67], 0, v[96:97]
	s_waitcnt vmcnt(1)
	v_mov_b32_e32 v68, v244
	v_mov_b32_e32 v69, v245
	v_mov_b32_e32 v70, v246
	v_mov_b32_e32 v71, v247
	v_lshlrev_b32_e32 v92, 16, v68
	v_and_b32_e32 v93, 0xffff0000, v68
	v_lshlrev_b32_e32 v72, 16, v69
	v_and_b32_e32 v73, 0xffff0000, v69
	v_lshlrev_b32_e32 v68, 16, v70
	v_and_b32_e32 v69, 0xffff0000, v70
	v_add_co_u32_e32 v70, vcc, s75, v80
	v_lshlrev_b32_e32 v66, 16, v71
	v_and_b32_e32 v67, 0xffff0000, v71
	v_addc_co_u32_e32 v71, vcc, 0, v81, vcc
	v_mov_b32_e32 v120, v248
	v_mov_b32_e32 v121, v249
	v_mov_b32_e32 v122, v250
	v_mov_b32_e32 v123, v251
	v_pk_fma_f32 v[90:91], v[52:53], v[92:93], v[90:91]
	v_pk_fma_f32 v[88:89], v[54:55], v[72:73], v[88:89]
	v_mul_f32_e32 v104, 0xbfb8aa3b, v90
	v_mul_f32_e32 v105, 0xbfb8aa3b, v91
	v_exp_f32_e32 v104, v104
	v_exp_f32_e32 v105, v105
	v_pk_fma_f32 v[86:87], v[20:21], v[68:69], v[86:87]
	v_pk_fma_f32 v[84:85], v[22:23], v[66:67], v[84:85]
	v_add_f32_e32 v104, 1.0, v104
	v_add_f32_e32 v105, 1.0, v105
	v_rcp_f32_e32 v104, v104
	v_rcp_f32_e32 v105, v105
	v_pk_fma_f32 v[8:9], v[16:17], v[68:69], v[8:9]
	v_pk_fma_f32 v[40:41], v[48:49], v[92:93], v[40:41]
	v_pk_mul_f32 v[90:91], v[90:91], v[104:105]
	v_mul_f32_e32 v104, 0xbfb8aa3b, v88
	v_mul_f32_e32 v105, 0xbfb8aa3b, v89
	v_exp_f32_e32 v104, v104
	v_exp_f32_e32 v105, v105
	v_add_f32_e32 v104, 1.0, v104
	v_add_f32_e32 v105, 1.0, v105
	v_rcp_f32_e32 v104, v104
	v_rcp_f32_e32 v105, v105
	v_add_co_u32_e32 v252, vcc, 0x5600, v252
	s_nop 1
	v_addc_co_u32_e32 v253, vcc, 0, v253, vcc
	global_load_dwordx4 v[244:247], v[252:253], off
	v_add_co_u32_e32 v248, vcc, 0x2b00, v252
	s_nop 1
	v_addc_co_u32_e32 v249, vcc, 0, v253, vcc
	global_load_dwordx4 v[248:251], v[248:249], off
	v_lshlrev_b32_e32 v102, 16, v120
	v_pk_mul_f32 v[88:89], v[88:89], v[104:105]
	v_mul_f32_e32 v104, 0xbfb8aa3b, v86
	v_mul_f32_e32 v105, 0xbfb8aa3b, v87
	v_exp_f32_e32 v104, v104
	v_exp_f32_e32 v105, v105
	v_and_b32_e32 v103, 0xffff0000, v120
	v_lshlrev_b32_e32 v94, 16, v121
	v_add_f32_e32 v104, 1.0, v104
	v_add_f32_e32 v105, 1.0, v105
	v_rcp_f32_e32 v104, v104
	v_rcp_f32_e32 v105, v105
	v_and_b32_e32 v95, 0xffff0000, v121
	v_lshlrev_b32_e32 v80, 16, v122
	v_and_b32_e32 v81, 0xffff0000, v122
	v_pk_mul_f32 v[86:87], v[86:87], v[104:105]
	v_mul_f32_e32 v104, 0xbfb8aa3b, v84
	v_mul_f32_e32 v105, 0xbfb8aa3b, v85
	v_exp_f32_e32 v104, v104
	v_exp_f32_e32 v105, v105
	v_lshlrev_b32_e32 v70, 16, v123
	v_and_b32_e32 v71, 0xffff0000, v123
	v_add_f32_e32 v104, 1.0, v104
	v_add_f32_e32 v105, 1.0, v105
	v_rcp_f32_e32 v104, v104
	v_rcp_f32_e32 v105, v105
	v_pk_fma_f32 v[112:113], v[44:45], v[102:103], v[112:113]
	v_pk_fma_f32 v[110:111], v[46:47], v[94:95], v[110:111]
	v_pk_fma_f32 v[108:109], v[12:13], v[80:81], v[108:109]
	v_pk_fma_f32 v[106:107], v[14:15], v[70:71], v[106:107]
	v_pk_mul_f32 v[84:85], v[84:85], v[104:105]
	v_pk_mul_f32 v[90:91], v[112:113], v[90:91]
	v_pk_mul_f32 v[88:89], v[110:111], v[88:89]
	v_pk_mul_f32 v[86:87], v[108:109], v[86:87]
	v_pk_mul_f32 v[104:105], v[106:107], v[84:85]
	v_cvt_pk_bf16_f32 v84, v90, v91
	v_cvt_pk_bf16_f32 v85, v88, v89
	v_cvt_pk_bf16_f32 v86, v86, v87
	v_cvt_pk_bf16_f32 v87, v104, v105
	v_mad_i64_i32 v[88:89], s[2:3], v124, s14, v[98:99]
	v_or_b32_e32 v108, 7, v138
	global_store_dwordx4 v[88:89], v[84:87], off
	v_pk_fma_f32 v[0:1], v[4:5], v[80:81], v[0:1]
	v_pk_fma_f32 v[32:33], v[36:37], v[102:103], v[32:33]
	v_mad_i64_i32 v[84:85], s[2:3], v108, s15, v[100:101]
	v_lshl_add_u64 v[88:89], v[84:85], 0, v[96:97]
	s_waitcnt vmcnt(1)
	v_mov_b32_e32 v84, v244
	v_mov_b32_e32 v85, v245
	v_mov_b32_e32 v86, v246
	v_mov_b32_e32 v87, v247
	v_pk_fma_f32 v[2:3], v[6:7], v[70:71], v[2:3]
	v_pk_fma_f32 v[34:35], v[38:39], v[94:95], v[34:35]
	v_lshlrev_b32_e32 v100, 16, v86
	v_and_b32_e32 v101, 0xffff0000, v86
	v_add_co_u32_e32 v86, vcc, s75, v88
	v_lshlrev_b32_e32 v90, 16, v84
	v_and_b32_e32 v91, 0xffff0000, v84
	v_lshlrev_b32_e32 v96, 16, v85
	v_and_b32_e32 v97, 0xffff0000, v85
	v_lshlrev_b32_e32 v84, 16, v87
	v_and_b32_e32 v85, 0xffff0000, v87
	v_addc_co_u32_e32 v87, vcc, 0, v89, vcc
	v_mov_b32_e32 v86, v248
	v_mov_b32_e32 v87, v249
	v_mov_b32_e32 v88, v250
	v_mov_b32_e32 v89, v251
	v_pk_fma_f32 v[8:9], v[20:21], v[100:101], v[8:9]
	v_pk_fma_f32 v[40:41], v[52:53], v[90:91], v[40:41]
	v_mul_f32_e32 v16, 0xbfb8aa3b, v8
	v_mul_f32_e32 v4, 0xbfb8aa3b, v9
	v_exp_f32_e32 v16, v16
	v_exp_f32_e32 v4, v4
	v_mul_f32_e32 v48, 0xbfb8aa3b, v40
	v_mul_f32_e32 v36, 0xbfb8aa3b, v41
	v_exp_f32_e32 v48, v48
	v_exp_f32_e32 v36, v36
	v_add_f32_e32 v16, 1.0, v16
	v_add_f32_e32 v4, 1.0, v4
	v_rcp_f32_e32 v16, v16
	v_rcp_f32_e32 v17, v4
	v_add_f32_e32 v48, 1.0, v48
	v_add_f32_e32 v36, 1.0, v36
	v_rcp_f32_e32 v48, v48
	v_rcp_f32_e32 v49, v36
	v_pk_mul_f32 v[4:5], v[8:9], v[16:17]
	v_pk_mul_f32 v[36:37], v[40:41], v[48:49]
	v_lshlrev_b32_e32 v106, 16, v88
	v_and_b32_e32 v107, 0xffff0000, v88
	v_pk_fma_f32 v[0:1], v[12:13], v[106:107], v[0:1]
	v_lshlrev_b32_e32 v104, 16, v86
	v_and_b32_e32 v105, 0xffff0000, v86
	v_pk_mul_f32 v[4:5], v[0:1], v[4:5]
	v_pk_fma_f32 v[0:1], v[10:11], v[74:75], v[30:31]
	v_pk_fma_f32 v[32:33], v[44:45], v[104:105], v[32:33]
	v_pk_fma_f32 v[0:1], v[18:19], v[66:67], v[0:1]
	v_pk_mul_f32 v[32:33], v[32:33], v[36:37]
	v_pk_fma_f32 v[36:37], v[42:43], v[78:79], v[62:63]
	v_pk_fma_f32 v[0:1], v[22:23], v[84:85], v[0:1]
	v_pk_fma_f32 v[36:37], v[50:51], v[72:73], v[36:37]
	v_mul_f32_e32 v8, 0xbfb8aa3b, v0
	v_mul_f32_e32 v6, 0xbfb8aa3b, v1
	v_pk_fma_f32 v[36:37], v[54:55], v[96:97], v[36:37]
	v_exp_f32_e32 v8, v8
	v_exp_f32_e32 v6, v6
	v_mul_f32_e32 v40, 0xbfb8aa3b, v36
	v_mul_f32_e32 v38, 0xbfb8aa3b, v37
	v_exp_f32_e32 v40, v40
	v_exp_f32_e32 v38, v38
	v_add_f32_e32 v8, 1.0, v8
	v_add_f32_e32 v6, 1.0, v6
	v_rcp_f32_e32 v8, v8
	v_rcp_f32_e32 v9, v6
	v_add_f32_e32 v40, 1.0, v40
	v_add_f32_e32 v38, 1.0, v38
	v_rcp_f32_e32 v40, v40
	v_rcp_f32_e32 v41, v38
	v_lshlrev_b32_e32 v88, 16, v89
	v_and_b32_e32 v89, 0xffff0000, v89
	v_pk_fma_f32 v[2:3], v[14:15], v[88:89], v[2:3]
	v_pk_mul_f32 v[0:1], v[0:1], v[8:9]
	v_lshlrev_b32_e32 v86, 16, v87
	v_and_b32_e32 v87, 0xffff0000, v87
	v_pk_mul_f32 v[6:7], v[2:3], v[0:1]
	v_cvt_pk_bf16_f32 v2, v4, v5
	v_mad_i64_i32 v[4:5], s[2:3], v108, s14, v[98:99]
	v_pk_fma_f32 v[34:35], v[46:47], v[86:87], v[34:35]
	v_pk_mul_f32 v[36:37], v[36:37], v[40:41]
	s_mov_b32 s2, 0xc17ff
	v_pk_mul_f32 v[34:35], v[34:35], v[36:37]
	v_cmp_lt_i32_e32 vcc, s2, v137
	v_cvt_pk_bf16_f32 v0, v32, v33
	v_cvt_pk_bf16_f32 v1, v34, v35
	v_cvt_pk_bf16_f32 v3, v6, v7
	s_or_b64 s[90:91], vcc, s[90:91]
	global_store_dwordx4 v[4:5], v[0:3], off
	s_andn2_b64 exec, exec, s[90:91]
	s_cbranch_execz .LBB0_1278

.LBB0_1404:
	s_or_b64 exec, exec, s[6:7]
	v_readlane_b32 s6, v240, 46
	v_readlane_b32 s7, v240, 47
	v_mov_b64_e32 v[72:73], s[94:95]
	s_waitcnt vmcnt(2)
	v_pk_fma_f32 v[112:113], v[36:37], v[112:113], v[60:61]
	v_lshl_add_u64 v[68:69], s[6:7], 0, v[70:71]
	v_mad_i64_i32 v[74:75], s[6:7], v126, s40, v[72:73]
	v_lshl_add_u64 v[92:93], v[74:75], 0, v[70:71]
	global_load_dwordx4 v[100:103], v[92:93], off
	v_mov_b32_e32 v252, v92
	v_mov_b32_e32 v253, v93
	v_add_co_u32_e32 v92, vcc, s75, v92
	v_pk_fma_f32 v[112:113], v[44:45], v[118:119], v[112:113]
	s_nop 0
	v_addc_co_u32_e32 v93, vcc, 0, v93, vcc
	global_load_dwordx4 v[128:131], v[92:93], off offset:2816
	v_add_co_u32_e32 v252, vcc, 0x5600, v252
	s_nop 1
	v_addc_co_u32_e32 v253, vcc, 0, v253, vcc
	global_load_dwordx4 v[244:247], v[252:253], off
	v_add_co_u32_e32 v248, vcc, 0x2b00, v252
	s_nop 1
	v_addc_co_u32_e32 v249, vcc, 0, v253, vcc
	global_load_dwordx4 v[248:251], v[248:249], off
	s_waitcnt vmcnt(2)
	v_pk_fma_f32 v[108:109], v[32:33], v[108:109], v[56:57]
	v_pk_fma_f32 v[96:97], v[38:39], v[96:97], v[62:63]
	v_pk_fma_f32 v[108:109], v[40:41], v[114:115], v[108:109]
	v_pk_fma_f32 v[96:97], v[46:47], v[106:107], v[96:97]
	v_pk_fma_f32 v[90:91], v[34:35], v[90:91], v[58:59]
	v_pk_fma_f32 v[86:87], v[4:5], v[86:87], v[28:29]
	v_pk_fma_f32 v[90:91], v[42:43], v[110:111], v[90:91]
	v_pk_fma_f32 v[86:87], v[12:13], v[88:89], v[86:87]
	v_pk_fma_f32 v[82:83], v[0:1], v[82:83], v[24:25]
	v_pk_fma_f32 v[66:67], v[6:7], v[66:67], v[30:31]
	v_pk_fma_f32 v[82:83], v[8:9], v[94:95], v[82:83]
	v_pk_fma_f32 v[66:67], v[14:15], v[80:81], v[66:67]
	v_pk_fma_f32 v[64:65], v[2:3], v[64:65], v[26:27]
	s_movk_i32 s12, 0x2b00
	v_pk_fma_f32 v[64:65], v[10:11], v[84:85], v[64:65]
	v_or_b32_e32 v127, 1, v126
	v_pk_fma_f32 v[88:89], v[4:5], v[88:89], v[28:29]
	v_pk_fma_f32 v[94:95], v[0:1], v[94:95], v[24:25]
	v_pk_fma_f32 v[80:81], v[6:7], v[80:81], v[30:31]
	v_pk_fma_f32 v[114:115], v[32:33], v[114:115], v[56:57]
	v_pk_fma_f32 v[110:111], v[34:35], v[110:111], v[58:59]
	v_pk_fma_f32 v[84:85], v[2:3], v[84:85], v[26:27]
	v_add_u32_e32 v124, 0xf4000, v124
	s_waitcnt vmcnt(1)
	v_lshlrev_b32_e32 v98, 16, v100
	v_and_b32_e32 v99, 0xffff0000, v100
	v_pk_fma_f32 v[112:113], v[52:53], v[98:99], v[112:113]
	v_lshlrev_b32_e32 v78, 16, v101
	v_mul_f32_e32 v116, 0xbfb8aa3b, v112
	v_mul_f32_e32 v117, 0xbfb8aa3b, v113
	v_exp_f32_e32 v116, v116
	v_exp_f32_e32 v117, v117
	v_and_b32_e32 v79, 0xffff0000, v101
	s_waitcnt vmcnt(0)
	v_lshlrev_b32_e32 v104, 16, v128
	v_add_f32_e32 v116, 1.0, v116
	v_add_f32_e32 v117, 1.0, v117
	v_rcp_f32_e32 v116, v116
	v_rcp_f32_e32 v117, v117
	v_and_b32_e32 v105, 0xffff0000, v128
	v_pk_fma_f32 v[108:109], v[48:49], v[104:105], v[108:109]
	v_pk_fma_f32 v[96:97], v[54:55], v[78:79], v[96:97]
	v_pk_mul_f32 v[112:113], v[112:113], v[116:117]
	v_lshlrev_b32_e32 v76, 16, v102
	v_pk_mul_f32 v[108:109], v[108:109], v[112:113]
	v_mul_f32_e32 v112, 0xbfb8aa3b, v96
	v_mul_f32_e32 v113, 0xbfb8aa3b, v97
	v_exp_f32_e32 v112, v112
	v_exp_f32_e32 v113, v113
	v_and_b32_e32 v77, 0xffff0000, v102
	v_lshlrev_b32_e32 v74, 16, v103
	v_add_f32_e32 v112, 1.0, v112
	v_add_f32_e32 v113, 1.0, v113
	v_rcp_f32_e32 v112, v112
	v_rcp_f32_e32 v113, v113
	v_and_b32_e32 v75, 0xffff0000, v103
	v_lshlrev_b32_e32 v102, 16, v129
	v_and_b32_e32 v103, 0xffff0000, v129
	v_pk_fma_f32 v[90:91], v[50:51], v[102:103], v[90:91]
	v_pk_mul_f32 v[96:97], v[96:97], v[112:113]
	v_pk_fma_f32 v[86:87], v[20:21], v[76:77], v[86:87]
	v_pk_mul_f32 v[90:91], v[90:91], v[96:97]
	v_mul_f32_e32 v96, 0xbfb8aa3b, v86
	v_mul_f32_e32 v97, 0xbfb8aa3b, v87
	v_exp_f32_e32 v96, v96
	v_exp_f32_e32 v97, v97
	v_lshlrev_b32_e32 v100, 16, v130
	v_and_b32_e32 v101, 0xffff0000, v130
	v_add_f32_e32 v96, 1.0, v96
	v_add_f32_e32 v97, 1.0, v97
	v_rcp_f32_e32 v96, v96
	v_rcp_f32_e32 v97, v97
	v_pk_fma_f32 v[82:83], v[16:17], v[100:101], v[82:83]
	v_pk_fma_f32 v[66:67], v[22:23], v[74:75], v[66:67]
	v_lshlrev_b32_e32 v92, 16, v131
	v_pk_mul_f32 v[86:87], v[86:87], v[96:97]
	v_and_b32_e32 v93, 0xffff0000, v131
	v_pk_mul_f32 v[82:83], v[82:83], v[86:87]
	v_mul_f32_e32 v86, 0xbfb8aa3b, v66
	v_mul_f32_e32 v87, 0xbfb8aa3b, v67
	v_exp_f32_e32 v86, v86
	v_exp_f32_e32 v87, v87
	v_pk_fma_f32 v[64:65], v[18:19], v[92:93], v[64:65]
	v_pk_fma_f32 v[88:89], v[12:13], v[76:77], v[88:89]
	v_add_f32_e32 v86, 1.0, v86
	v_add_f32_e32 v87, 1.0, v87
	v_rcp_f32_e32 v86, v86
	v_rcp_f32_e32 v87, v87
	v_pk_fma_f32 v[94:95], v[8:9], v[100:101], v[94:95]
	v_pk_fma_f32 v[80:81], v[14:15], v[74:75], v[80:81]
	v_pk_fma_f32 v[114:115], v[40:41], v[104:105], v[114:115]
	v_pk_mul_f32 v[66:67], v[66:67], v[86:87]
	v_pk_fma_f32 v[110:111], v[42:43], v[102:103], v[110:111]
	v_pk_mul_f32 v[86:87], v[64:65], v[66:67]
	v_cvt_pk_bf16_f32 v64, v108, v109
	v_cvt_pk_bf16_f32 v65, v90, v91
	v_cvt_pk_bf16_f32 v66, v82, v83
	v_cvt_pk_bf16_f32 v67, v86, v87
	v_mad_i64_i32 v[82:83], s[6:7], v126, s12, v[68:69]
	global_store_dwordx4 v[82:83], v[64:67], off
	v_pk_fma_f32 v[84:85], v[10:11], v[92:93], v[84:85]
	v_pk_fma_f32 v[76:77], v[4:5], v[76:77], v[28:29]
	v_mad_i64_i32 v[64:65], s[6:7], v127, s40, v[72:73]
	v_lshl_add_u64 v[108:109], v[64:65], 0, v[70:71]
	s_waitcnt vmcnt(1)
	v_mov_b32_e32 v64, v244
	v_mov_b32_e32 v65, v245
	v_mov_b32_e32 v66, v246
	v_mov_b32_e32 v67, v247
	v_pk_fma_f32 v[74:75], v[6:7], v[74:75], v[30:31]
	v_pk_fma_f32 v[92:93], v[2:3], v[92:93], v[26:27]
	v_lshlrev_b32_e32 v96, 16, v64
	v_and_b32_e32 v97, 0xffff0000, v64
	v_add_co_u32_e32 v64, vcc, s75, v108
	v_lshlrev_b32_e32 v90, 16, v65
	v_and_b32_e32 v91, 0xffff0000, v65
	v_addc_co_u32_e32 v65, vcc, 0, v109, vcc
	v_lshlrev_b32_e32 v86, 16, v66
	v_and_b32_e32 v87, 0xffff0000, v66
	v_lshlrev_b32_e32 v82, 16, v67
	v_and_b32_e32 v83, 0xffff0000, v67
	v_mov_b32_e32 v64, v248
	v_mov_b32_e32 v65, v249
	v_mov_b32_e32 v66, v250
	v_mov_b32_e32 v67, v251
	v_pk_fma_f32 v[88:89], v[20:21], v[86:87], v[88:89]
	v_pk_fma_f32 v[80:81], v[22:23], v[82:83], v[80:81]
	v_pk_fma_f32 v[76:77], v[12:13], v[86:87], v[76:77]
	v_pk_fma_f32 v[74:75], v[14:15], v[82:83], v[74:75]
	v_pk_fma_f32 v[86:87], v[4:5], v[86:87], v[28:29]
	v_pk_fma_f32 v[82:83], v[6:7], v[82:83], v[30:31]
	v_add_co_u32_e32 v252, vcc, 0x5600, v252
	s_nop 1
	v_addc_co_u32_e32 v253, vcc, 0, v253, vcc
	global_load_dwordx4 v[244:247], v[252:253], off
	v_add_co_u32_e32 v248, vcc, 0x2b00, v252
	s_nop 1
	v_addc_co_u32_e32 v249, vcc, 0, v253, vcc
	global_load_dwordx4 v[248:251], v[248:249], off
	v_lshlrev_b32_e32 v120, 16, v64
	v_and_b32_e32 v121, 0xffff0000, v64
	v_lshlrev_b32_e32 v116, 16, v65
	v_and_b32_e32 v117, 0xffff0000, v65
	v_pk_fma_f32 v[64:65], v[36:37], v[118:119], v[60:61]
	v_lshlrev_b32_e32 v112, 16, v66
	v_pk_fma_f32 v[64:65], v[44:45], v[98:99], v[64:65]
	v_and_b32_e32 v113, 0xffff0000, v66
	v_pk_fma_f32 v[64:65], v[52:53], v[96:97], v[64:65]
	v_lshlrev_b32_e32 v108, 16, v67
	v_and_b32_e32 v109, 0xffff0000, v67
	v_mul_f32_e32 v66, 0xbfb8aa3b, v64
	v_mul_f32_e32 v67, 0xbfb8aa3b, v65
	v_exp_f32_e32 v66, v66
	v_exp_f32_e32 v67, v67
	v_pk_fma_f32 v[94:95], v[16:17], v[112:113], v[94:95]
	v_pk_fma_f32 v[114:115], v[48:49], v[120:121], v[114:115]
	v_add_f32_e32 v66, 1.0, v66
	v_add_f32_e32 v67, 1.0, v67
	v_rcp_f32_e32 v66, v66
	v_rcp_f32_e32 v67, v67
	v_pk_fma_f32 v[110:111], v[50:51], v[116:117], v[110:111]
	v_pk_fma_f32 v[84:85], v[18:19], v[108:109], v[84:85]
	v_pk_fma_f32 v[92:93], v[10:11], v[108:109], v[92:93]
	v_pk_mul_f32 v[64:65], v[64:65], v[66:67]
	v_pk_fma_f32 v[66:67], v[38:39], v[106:107], v[62:63]
	v_pk_mul_f32 v[64:65], v[114:115], v[64:65]
	v_pk_fma_f32 v[66:67], v[46:47], v[78:79], v[66:67]
	v_cvt_pk_bf16_f32 v64, v64, v65
	v_pk_fma_f32 v[66:67], v[54:55], v[90:91], v[66:67]
	s_nop 0
	v_mul_f32_e32 v106, 0xbfb8aa3b, v66
	v_mul_f32_e32 v107, 0xbfb8aa3b, v67
	v_exp_f32_e32 v106, v106
	v_exp_f32_e32 v107, v107
	v_add_f32_e32 v106, 1.0, v106
	v_add_f32_e32 v107, 1.0, v107
	v_rcp_f32_e32 v106, v106
	v_rcp_f32_e32 v107, v107
	s_nop 0
	v_pk_mul_f32 v[66:67], v[66:67], v[106:107]
	v_mul_f32_e32 v106, 0xbfb8aa3b, v88
	v_mul_f32_e32 v107, 0xbfb8aa3b, v89
	v_exp_f32_e32 v106, v106
	v_exp_f32_e32 v107, v107
	v_pk_mul_f32 v[66:67], v[110:111], v[66:67]
	v_add_f32_e32 v106, 1.0, v106
	v_add_f32_e32 v107, 1.0, v107
	v_rcp_f32_e32 v106, v106
	v_rcp_f32_e32 v107, v107
	v_cvt_pk_bf16_f32 v65, v66, v67
	v_pk_mul_f32 v[88:89], v[88:89], v[106:107]
	s_nop 0
	v_pk_mul_f32 v[88:89], v[94:95], v[88:89]
	v_mul_f32_e32 v94, 0xbfb8aa3b, v80
	v_mul_f32_e32 v95, 0xbfb8aa3b, v81
	v_exp_f32_e32 v94, v94
	v_exp_f32_e32 v95, v95
	v_cvt_pk_bf16_f32 v66, v88, v89
	v_add_f32_e32 v94, 1.0, v94
	v_add_f32_e32 v95, 1.0, v95
	v_rcp_f32_e32 v94, v94
	v_rcp_f32_e32 v95, v95
	s_nop 0
	v_pk_mul_f32 v[80:81], v[80:81], v[94:95]
	s_nop 0
	v_pk_mul_f32 v[80:81], v[84:85], v[80:81]
	s_nop 0
	v_cvt_pk_bf16_f32 v67, v80, v81
	v_mad_i64_i32 v[80:81], s[6:7], v127, s12, v[68:69]
	v_or_b32_e32 v127, 2, v126
	global_store_dwordx4 v[80:81], v[64:67], off
	s_nop 1
	v_mad_i64_i32 v[64:65], s[6:7], v127, s40, v[72:73]
	v_lshl_add_u64 v[106:107], v[64:65], 0, v[70:71]
	s_waitcnt vmcnt(1)
	v_mov_b32_e32 v64, v244
	v_mov_b32_e32 v65, v245
	v_mov_b32_e32 v66, v246
	v_mov_b32_e32 v67, v247
	v_lshlrev_b32_e32 v94, 16, v64
	v_and_b32_e32 v95, 0xffff0000, v64
	v_add_co_u32_e32 v64, vcc, s75, v106
	v_lshlrev_b32_e32 v88, 16, v65
	v_and_b32_e32 v89, 0xffff0000, v65
	v_addc_co_u32_e32 v65, vcc, 0, v107, vcc
	v_lshlrev_b32_e32 v84, 16, v66
	v_and_b32_e32 v85, 0xffff0000, v66
	v_lshlrev_b32_e32 v80, 16, v67
	v_and_b32_e32 v81, 0xffff0000, v67
	v_mov_b32_e32 v64, v248
	v_mov_b32_e32 v65, v249
	v_mov_b32_e32 v66, v250
	v_mov_b32_e32 v67, v251
	v_pk_fma_f32 v[76:77], v[20:21], v[84:85], v[76:77]
	v_pk_fma_f32 v[74:75], v[22:23], v[80:81], v[74:75]
	v_pk_fma_f32 v[86:87], v[12:13], v[84:85], v[86:87]
	v_pk_fma_f32 v[82:83], v[14:15], v[80:81], v[82:83]
	v_pk_fma_f32 v[84:85], v[4:5], v[84:85], v[28:29]
	v_pk_fma_f32 v[80:81], v[6:7], v[80:81], v[30:31]
	v_add_co_u32_e32 v252, vcc, 0x5600, v252
	s_nop 1
	v_addc_co_u32_e32 v253, vcc, 0, v253, vcc
	global_load_dwordx4 v[244:247], v[252:253], off
	v_add_co_u32_e32 v248, vcc, 0x2b00, v252
	s_nop 1
	v_addc_co_u32_e32 v249, vcc, 0, v253, vcc
	global_load_dwordx4 v[248:251], v[248:249], off
	v_lshlrev_b32_e32 v118, 16, v64
	v_and_b32_e32 v119, 0xffff0000, v64
	v_lshlrev_b32_e32 v114, 16, v65
	v_and_b32_e32 v115, 0xffff0000, v65
	v_pk_fma_f32 v[64:65], v[36:37], v[98:99], v[60:61]
	v_lshlrev_b32_e32 v110, 16, v66
	v_pk_fma_f32 v[64:65], v[44:45], v[96:97], v[64:65]
	v_and_b32_e32 v111, 0xffff0000, v66
	v_pk_fma_f32 v[64:65], v[52:53], v[94:95], v[64:65]
	v_lshlrev_b32_e32 v106, 16, v67
	v_and_b32_e32 v107, 0xffff0000, v67
	v_mul_f32_e32 v66, 0xbfb8aa3b, v64
	v_mul_f32_e32 v67, 0xbfb8aa3b, v65
	v_exp_f32_e32 v66, v66
	v_exp_f32_e32 v67, v67
	v_pk_fma_f32 v[98:99], v[32:33], v[104:105], v[56:57]
	v_pk_fma_f32 v[92:93], v[18:19], v[106:107], v[92:93]
	v_add_f32_e32 v66, 1.0, v66
	v_add_f32_e32 v67, 1.0, v67
	v_rcp_f32_e32 v66, v66
	v_rcp_f32_e32 v67, v67
	v_pk_fma_f32 v[98:99], v[40:41], v[120:121], v[98:99]
	v_pk_mul_f32 v[64:65], v[64:65], v[66:67]
	v_pk_fma_f32 v[66:67], v[38:39], v[78:79], v[62:63]
	v_pk_fma_f32 v[98:99], v[48:49], v[118:119], v[98:99]
	v_pk_fma_f32 v[66:67], v[46:47], v[90:91], v[66:67]
	v_pk_mul_f32 v[64:65], v[98:99], v[64:65]
	v_pk_fma_f32 v[66:67], v[54:55], v[88:89], v[66:67]
	v_pk_fma_f32 v[98:99], v[34:35], v[102:103], v[58:59]
	v_mul_f32_e32 v78, 0xbfb8aa3b, v66
	v_mul_f32_e32 v79, 0xbfb8aa3b, v67
	v_exp_f32_e32 v78, v78
	v_exp_f32_e32 v79, v79
	v_pk_fma_f32 v[98:99], v[42:43], v[116:117], v[98:99]
	v_cvt_pk_bf16_f32 v64, v64, v65
	v_add_f32_e32 v78, 1.0, v78
	v_add_f32_e32 v79, 1.0, v79
	v_rcp_f32_e32 v78, v78
	v_rcp_f32_e32 v79, v79
	v_pk_fma_f32 v[98:99], v[50:51], v[114:115], v[98:99]
	v_pk_mul_f32 v[66:67], v[66:67], v[78:79]
	v_mul_f32_e32 v78, 0xbfb8aa3b, v76
	v_mul_f32_e32 v79, 0xbfb8aa3b, v77
	v_exp_f32_e32 v78, v78
	v_exp_f32_e32 v79, v79
	v_pk_mul_f32 v[66:67], v[98:99], v[66:67]
	v_pk_fma_f32 v[98:99], v[0:1], v[100:101], v[24:25]
	v_add_f32_e32 v78, 1.0, v78
	v_add_f32_e32 v79, 1.0, v79
	v_rcp_f32_e32 v78, v78
	v_rcp_f32_e32 v79, v79
	v_pk_fma_f32 v[98:99], v[8:9], v[112:113], v[98:99]
	v_cvt_pk_bf16_f32 v65, v66, v67
	v_pk_fma_f32 v[98:99], v[16:17], v[110:111], v[98:99]
	v_pk_mul_f32 v[76:77], v[76:77], v[78:79]
	v_mul_f32_e32 v78, 0xbfb8aa3b, v74
	v_mul_f32_e32 v79, 0xbfb8aa3b, v75
	v_exp_f32_e32 v78, v78
	v_exp_f32_e32 v79, v79
	v_pk_mul_f32 v[76:77], v[98:99], v[76:77]
	v_add_f32_e32 v78, 1.0, v78
	v_add_f32_e32 v79, 1.0, v79
	v_rcp_f32_e32 v78, v78
	v_rcp_f32_e32 v79, v79
	v_cvt_pk_bf16_f32 v66, v76, v77
	v_pk_mul_f32 v[74:75], v[74:75], v[78:79]
	s_nop 0
	v_pk_mul_f32 v[74:75], v[92:93], v[74:75]
	s_nop 0
	v_cvt_pk_bf16_f32 v67, v74, v75
	v_mad_i64_i32 v[74:75], s[6:7], v127, s12, v[68:69]
	v_or_b32_e32 v127, 3, v126
	global_store_dwordx4 v[74:75], v[64:67], off
	s_nop 1
	v_mad_i64_i32 v[64:65], s[6:7], v127, s40, v[72:73]
	v_lshl_add_u64 v[98:99], v[64:65], 0, v[70:71]
	s_waitcnt vmcnt(1)
	v_mov_b32_e32 v64, v244
	v_mov_b32_e32 v65, v245
	v_mov_b32_e32 v66, v246
	v_mov_b32_e32 v67, v247
	v_lshlrev_b32_e32 v92, 16, v64
	v_and_b32_e32 v93, 0xffff0000, v64
	v_add_co_u32_e32 v64, vcc, s75, v98
	v_lshlrev_b32_e32 v78, 16, v65
	v_and_b32_e32 v79, 0xffff0000, v65
	v_addc_co_u32_e32 v65, vcc, 0, v99, vcc
	v_lshlrev_b32_e32 v76, 16, v66
	v_and_b32_e32 v77, 0xffff0000, v66
	v_lshlrev_b32_e32 v74, 16, v67
	v_and_b32_e32 v75, 0xffff0000, v67
	v_mov_b32_e32 v64, v248
	v_mov_b32_e32 v65, v249
	v_mov_b32_e32 v66, v250
	v_mov_b32_e32 v67, v251
	v_pk_fma_f32 v[86:87], v[20:21], v[76:77], v[86:87]
	v_pk_fma_f32 v[82:83], v[22:23], v[74:75], v[82:83]
	v_pk_fma_f32 v[84:85], v[12:13], v[76:77], v[84:85]
	v_pk_fma_f32 v[80:81], v[14:15], v[74:75], v[80:81]
	v_pk_fma_f32 v[76:77], v[4:5], v[76:77], v[28:29]
	v_pk_fma_f32 v[74:75], v[6:7], v[74:75], v[30:31]
	v_add_co_u32_e32 v252, vcc, 0x5600, v252
	s_nop 1
	v_addc_co_u32_e32 v253, vcc, 0, v253, vcc
	global_load_dwordx4 v[244:247], v[252:253], off
	v_add_co_u32_e32 v248, vcc, 0x2b00, v252
	s_nop 1
	v_addc_co_u32_e32 v249, vcc, 0, v253, vcc
	global_load_dwordx4 v[248:251], v[248:249], off
	v_lshlrev_b32_e32 v104, 16, v64
	v_and_b32_e32 v105, 0xffff0000, v64
	v_lshlrev_b32_e32 v102, 16, v65
	v_and_b32_e32 v103, 0xffff0000, v65
	v_pk_fma_f32 v[64:65], v[36:37], v[96:97], v[60:61]
	v_lshlrev_b32_e32 v100, 16, v66
	v_pk_fma_f32 v[64:65], v[44:45], v[94:95], v[64:65]
	v_and_b32_e32 v101, 0xffff0000, v66
	v_pk_fma_f32 v[64:65], v[52:53], v[92:93], v[64:65]
	v_lshlrev_b32_e32 v98, 16, v67
	v_and_b32_e32 v99, 0xffff0000, v67
	v_mul_f32_e32 v66, 0xbfb8aa3b, v64
	v_mul_f32_e32 v67, 0xbfb8aa3b, v65
	v_exp_f32_e32 v66, v66
	v_exp_f32_e32 v67, v67
	v_pk_fma_f32 v[96:97], v[32:33], v[120:121], v[56:57]
	v_add_f32_e32 v66, 1.0, v66
	v_add_f32_e32 v67, 1.0, v67
	v_rcp_f32_e32 v66, v66
	v_rcp_f32_e32 v67, v67
	v_pk_fma_f32 v[96:97], v[40:41], v[118:119], v[96:97]
	v_pk_mul_f32 v[64:65], v[64:65], v[66:67]
	v_pk_fma_f32 v[66:67], v[38:39], v[90:91], v[62:63]
	v_pk_fma_f32 v[96:97], v[48:49], v[104:105], v[96:97]
	v_pk_fma_f32 v[66:67], v[46:47], v[88:89], v[66:67]
	v_pk_mul_f32 v[64:65], v[96:97], v[64:65]
	v_pk_fma_f32 v[66:67], v[54:55], v[78:79], v[66:67]
	v_pk_fma_f32 v[96:97], v[34:35], v[116:117], v[58:59]
	v_mul_f32_e32 v90, 0xbfb8aa3b, v66
	v_mul_f32_e32 v91, 0xbfb8aa3b, v67
	v_exp_f32_e32 v90, v90
	v_exp_f32_e32 v91, v91
	v_pk_fma_f32 v[96:97], v[42:43], v[114:115], v[96:97]
	v_cvt_pk_bf16_f32 v64, v64, v65
	v_add_f32_e32 v90, 1.0, v90
	v_add_f32_e32 v91, 1.0, v91
	v_rcp_f32_e32 v90, v90
	v_rcp_f32_e32 v91, v91
	v_pk_fma_f32 v[96:97], v[50:51], v[102:103], v[96:97]
	v_pk_mul_f32 v[66:67], v[66:67], v[90:91]
	v_mul_f32_e32 v90, 0xbfb8aa3b, v86
	v_mul_f32_e32 v91, 0xbfb8aa3b, v87
	v_exp_f32_e32 v90, v90
	v_exp_f32_e32 v91, v91
	v_pk_mul_f32 v[66:67], v[96:97], v[66:67]
	v_pk_fma_f32 v[96:97], v[0:1], v[112:113], v[24:25]
	v_add_f32_e32 v90, 1.0, v90
	v_add_f32_e32 v91, 1.0, v91
	v_rcp_f32_e32 v90, v90
	v_rcp_f32_e32 v91, v91
	v_pk_fma_f32 v[96:97], v[8:9], v[110:111], v[96:97]
	v_cvt_pk_bf16_f32 v65, v66, v67
	v_pk_fma_f32 v[96:97], v[16:17], v[100:101], v[96:97]
	v_pk_mul_f32 v[86:87], v[86:87], v[90:91]
	v_mul_f32_e32 v90, 0xbfb8aa3b, v82
	v_mul_f32_e32 v91, 0xbfb8aa3b, v83
	v_exp_f32_e32 v90, v90
	v_exp_f32_e32 v91, v91
	v_pk_mul_f32 v[86:87], v[96:97], v[86:87]
	v_pk_fma_f32 v[96:97], v[2:3], v[108:109], v[26:27]
	v_add_f32_e32 v90, 1.0, v90
	v_add_f32_e32 v91, 1.0, v91
	v_rcp_f32_e32 v90, v90
	v_rcp_f32_e32 v91, v91
	v_pk_fma_f32 v[96:97], v[10:11], v[106:107], v[96:97]
	v_cvt_pk_bf16_f32 v66, v86, v87
	v_pk_fma_f32 v[96:97], v[18:19], v[98:99], v[96:97]
	v_pk_mul_f32 v[82:83], v[82:83], v[90:91]
	s_nop 0
	v_pk_mul_f32 v[82:83], v[96:97], v[82:83]
	s_nop 0
	v_cvt_pk_bf16_f32 v67, v82, v83
	v_mad_i64_i32 v[82:83], s[6:7], v127, s12, v[68:69]
	v_or_b32_e32 v127, 4, v126
	global_store_dwordx4 v[82:83], v[64:67], off
	s_nop 1
	v_mad_i64_i32 v[64:65], s[6:7], v127, s40, v[72:73]
	v_lshl_add_u64 v[108:109], v[64:65], 0, v[70:71]
	s_waitcnt vmcnt(1)
	v_mov_b32_e32 v64, v244
	v_mov_b32_e32 v65, v245
	v_mov_b32_e32 v66, v246
	v_mov_b32_e32 v67, v247
	v_lshlrev_b32_e32 v96, 16, v64
	v_and_b32_e32 v97, 0xffff0000, v64
	v_add_co_u32_e32 v64, vcc, s75, v108
	v_lshlrev_b32_e32 v90, 16, v65
	v_and_b32_e32 v91, 0xffff0000, v65
	v_addc_co_u32_e32 v65, vcc, 0, v109, vcc
	v_lshlrev_b32_e32 v86, 16, v66
	v_and_b32_e32 v87, 0xffff0000, v66
	v_lshlrev_b32_e32 v82, 16, v67
	v_and_b32_e32 v83, 0xffff0000, v67
	v_mov_b32_e32 v64, v248
	v_mov_b32_e32 v65, v249
	v_mov_b32_e32 v66, v250
	v_mov_b32_e32 v67, v251
	v_pk_fma_f32 v[84:85], v[20:21], v[86:87], v[84:85]
	v_pk_fma_f32 v[80:81], v[22:23], v[82:83], v[80:81]
	v_pk_fma_f32 v[76:77], v[12:13], v[86:87], v[76:77]
	v_pk_fma_f32 v[74:75], v[14:15], v[82:83], v[74:75]
	v_pk_fma_f32 v[86:87], v[4:5], v[86:87], v[28:29]
	v_pk_fma_f32 v[82:83], v[6:7], v[82:83], v[30:31]
	v_add_co_u32_e32 v252, vcc, 0x5600, v252
	s_nop 1
	v_addc_co_u32_e32 v253, vcc, 0, v253, vcc
	global_load_dwordx4 v[244:247], v[252:253], off
	v_add_co_u32_e32 v248, vcc, 0x2b00, v252
	s_nop 1
	v_addc_co_u32_e32 v249, vcc, 0, v253, vcc
	global_load_dwordx4 v[248:251], v[248:249], off
	v_lshlrev_b32_e32 v120, 16, v64
	v_and_b32_e32 v121, 0xffff0000, v64
	v_lshlrev_b32_e32 v116, 16, v65
	v_and_b32_e32 v117, 0xffff0000, v65
	v_pk_fma_f32 v[64:65], v[36:37], v[94:95], v[60:61]
	v_lshlrev_b32_e32 v112, 16, v66
	v_pk_fma_f32 v[64:65], v[44:45], v[92:93], v[64:65]
	v_and_b32_e32 v113, 0xffff0000, v66
	v_pk_fma_f32 v[64:65], v[52:53], v[96:97], v[64:65]
	v_lshlrev_b32_e32 v108, 16, v67
	v_and_b32_e32 v109, 0xffff0000, v67
	v_mul_f32_e32 v66, 0xbfb8aa3b, v64
	v_mul_f32_e32 v67, 0xbfb8aa3b, v65
	v_exp_f32_e32 v66, v66
	v_exp_f32_e32 v67, v67
	v_pk_fma_f32 v[94:95], v[32:33], v[118:119], v[56:57]
	v_or_b32_e32 v118, 5, v126
	v_add_f32_e32 v66, 1.0, v66
	v_add_f32_e32 v67, 1.0, v67
	v_rcp_f32_e32 v66, v66
	v_rcp_f32_e32 v67, v67
	v_pk_fma_f32 v[94:95], v[40:41], v[104:105], v[94:95]
	v_pk_fma_f32 v[104:105], v[32:33], v[104:105], v[56:57]
	v_pk_fma_f32 v[94:95], v[48:49], v[120:121], v[94:95]
	v_pk_mul_f32 v[64:65], v[64:65], v[66:67]
	v_pk_fma_f32 v[66:67], v[38:39], v[88:89], v[62:63]
	v_pk_mul_f32 v[64:65], v[94:95], v[64:65]
	v_pk_fma_f32 v[66:67], v[46:47], v[78:79], v[66:67]
	v_pk_fma_f32 v[94:95], v[34:35], v[114:115], v[58:59]
	v_pk_fma_f32 v[66:67], v[54:55], v[90:91], v[66:67]
	v_pk_fma_f32 v[94:95], v[42:43], v[102:103], v[94:95]
	v_mul_f32_e32 v88, 0xbfb8aa3b, v66
	v_mul_f32_e32 v89, 0xbfb8aa3b, v67
	v_exp_f32_e32 v88, v88
	v_exp_f32_e32 v89, v89
	v_pk_fma_f32 v[94:95], v[50:51], v[116:117], v[94:95]
	v_cvt_pk_bf16_f32 v64, v64, v65
	v_add_f32_e32 v88, 1.0, v88
	v_add_f32_e32 v89, 1.0, v89
	v_rcp_f32_e32 v88, v88
	v_rcp_f32_e32 v89, v89
	v_pk_fma_f32 v[78:79], v[38:39], v[78:79], v[62:63]
	v_pk_fma_f32 v[102:103], v[34:35], v[102:103], v[58:59]
	v_pk_fma_f32 v[78:79], v[46:47], v[90:91], v[78:79]
	v_pk_mul_f32 v[66:67], v[66:67], v[88:89]
	v_mul_f32_e32 v88, 0xbfb8aa3b, v84
	v_mul_f32_e32 v89, 0xbfb8aa3b, v85
	v_exp_f32_e32 v88, v88
	v_exp_f32_e32 v89, v89
	v_pk_mul_f32 v[66:67], v[94:95], v[66:67]
	v_pk_fma_f32 v[94:95], v[0:1], v[110:111], v[24:25]
	v_add_f32_e32 v88, 1.0, v88
	v_add_f32_e32 v89, 1.0, v89
	v_rcp_f32_e32 v88, v88
	v_rcp_f32_e32 v89, v89
	v_pk_fma_f32 v[94:95], v[8:9], v[100:101], v[94:95]
	v_cvt_pk_bf16_f32 v65, v66, v67
	v_pk_fma_f32 v[94:95], v[16:17], v[112:113], v[94:95]
	v_pk_mul_f32 v[84:85], v[84:85], v[88:89]
	v_mul_f32_e32 v88, 0xbfb8aa3b, v80
	v_mul_f32_e32 v89, 0xbfb8aa3b, v81
	v_exp_f32_e32 v88, v88
	v_exp_f32_e32 v89, v89
	v_pk_mul_f32 v[84:85], v[94:95], v[84:85]
	v_pk_fma_f32 v[94:95], v[2:3], v[106:107], v[26:27]
	v_add_f32_e32 v88, 1.0, v88
	v_add_f32_e32 v89, 1.0, v89
	v_rcp_f32_e32 v88, v88
	v_rcp_f32_e32 v89, v89
	v_pk_fma_f32 v[94:95], v[10:11], v[98:99], v[94:95]
	v_cvt_pk_bf16_f32 v66, v84, v85
	v_pk_fma_f32 v[94:95], v[18:19], v[108:109], v[94:95]
	v_pk_mul_f32 v[80:81], v[80:81], v[88:89]
	v_pk_fma_f32 v[100:101], v[0:1], v[100:101], v[24:25]
	v_pk_mul_f32 v[80:81], v[94:95], v[80:81]
	v_pk_fma_f32 v[98:99], v[2:3], v[98:99], v[26:27]
	v_cvt_pk_bf16_f32 v67, v80, v81
	v_mad_i64_i32 v[80:81], s[6:7], v127, s12, v[68:69]
	global_store_dwordx4 v[80:81], v[64:67], off
	v_pk_fma_f32 v[104:105], v[40:41], v[120:121], v[104:105]
	v_pk_fma_f32 v[102:103], v[42:43], v[116:117], v[102:103]
	v_mad_i64_i32 v[64:65], s[6:7], v118, s40, v[72:73]
	v_lshl_add_u64 v[106:107], v[64:65], 0, v[70:71]
	s_waitcnt vmcnt(1)
	v_mov_b32_e32 v64, v244
	v_mov_b32_e32 v65, v245
	v_mov_b32_e32 v66, v246
	v_mov_b32_e32 v67, v247
	v_pk_fma_f32 v[100:101], v[8:9], v[112:113], v[100:101]
	v_pk_fma_f32 v[98:99], v[10:11], v[108:109], v[98:99]
	v_or_b32_e32 v127, 6, v126
	v_pk_fma_f32 v[90:91], v[38:39], v[90:91], v[62:63]
	v_pk_fma_f32 v[116:117], v[34:35], v[116:117], v[58:59]
	v_pk_fma_f32 v[112:113], v[0:1], v[112:113], v[24:25]
	v_pk_fma_f32 v[108:109], v[2:3], v[108:109], v[26:27]
	v_lshlrev_b32_e32 v94, 16, v64
	v_and_b32_e32 v95, 0xffff0000, v64
	v_add_co_u32_e32 v64, vcc, s75, v106
	v_lshlrev_b32_e32 v88, 16, v65
	v_and_b32_e32 v89, 0xffff0000, v65
	v_addc_co_u32_e32 v65, vcc, 0, v107, vcc
	v_lshlrev_b32_e32 v84, 16, v66
	v_and_b32_e32 v85, 0xffff0000, v66
	v_lshlrev_b32_e32 v80, 16, v67
	v_and_b32_e32 v81, 0xffff0000, v67
	v_mov_b32_e32 v64, v248
	v_mov_b32_e32 v65, v249
	v_mov_b32_e32 v66, v250
	v_mov_b32_e32 v67, v251
	v_pk_fma_f32 v[78:79], v[54:55], v[88:89], v[78:79]
	v_pk_fma_f32 v[76:77], v[20:21], v[84:85], v[76:77]
	v_pk_fma_f32 v[74:75], v[22:23], v[80:81], v[74:75]
	v_pk_fma_f32 v[90:91], v[46:47], v[88:89], v[90:91]
	v_pk_fma_f32 v[86:87], v[12:13], v[84:85], v[86:87]
	v_pk_fma_f32 v[82:83], v[14:15], v[80:81], v[82:83]
	v_pk_fma_f32 v[4:5], v[4:5], v[84:85], v[28:29]
	v_add_co_u32_e32 v252, vcc, 0x5600, v252
	s_nop 1
	v_addc_co_u32_e32 v253, vcc, 0, v253, vcc
	global_load_dwordx4 v[244:247], v[252:253], off
	v_add_co_u32_e32 v248, vcc, 0x2b00, v252
	s_nop 1
	v_addc_co_u32_e32 v249, vcc, 0, v253, vcc
	global_load_dwordx4 v[248:251], v[248:249], off
	v_lshlrev_b32_e32 v114, 16, v64
	v_and_b32_e32 v115, 0xffff0000, v64
	v_lshlrev_b32_e32 v110, 16, v65
	v_and_b32_e32 v111, 0xffff0000, v65
	v_lshlrev_b32_e32 v106, 16, v66
	v_and_b32_e32 v107, 0xffff0000, v66
	v_lshlrev_b32_e32 v64, 16, v67
	v_and_b32_e32 v65, 0xffff0000, v67
	v_pk_fma_f32 v[66:67], v[36:37], v[92:93], v[60:61]
	v_pk_fma_f32 v[104:105], v[48:49], v[114:115], v[104:105]
	v_pk_fma_f32 v[66:67], v[44:45], v[96:97], v[66:67]
	v_pk_fma_f32 v[102:103], v[50:51], v[110:111], v[102:103]
	v_pk_fma_f32 v[66:67], v[52:53], v[94:95], v[66:67]
	v_pk_fma_f32 v[100:101], v[16:17], v[106:107], v[100:101]
	v_mul_f32_e32 v92, 0xbfb8aa3b, v66
	v_mul_f32_e32 v93, 0xbfb8aa3b, v67
	v_exp_f32_e32 v92, v92
	v_exp_f32_e32 v93, v93
	v_pk_fma_f32 v[98:99], v[18:19], v[64:65], v[98:99]
	v_pk_fma_f32 v[96:97], v[36:37], v[96:97], v[60:61]
	v_add_f32_e32 v92, 1.0, v92
	v_add_f32_e32 v93, 1.0, v93
	v_rcp_f32_e32 v92, v92
	v_rcp_f32_e32 v93, v93
	v_pk_fma_f32 v[96:97], v[44:45], v[94:95], v[96:97]
	v_pk_fma_f32 v[116:117], v[42:43], v[110:111], v[116:117]
	v_pk_fma_f32 v[112:113], v[8:9], v[106:107], v[112:113]
	v_pk_mul_f32 v[66:67], v[66:67], v[92:93]
	v_mul_f32_e32 v92, 0xbfb8aa3b, v78
	v_mul_f32_e32 v93, 0xbfb8aa3b, v79
	v_exp_f32_e32 v92, v92
	v_exp_f32_e32 v93, v93
	v_pk_mul_f32 v[66:67], v[104:105], v[66:67]
	v_pk_fma_f32 v[108:109], v[10:11], v[64:65], v[108:109]
	v_add_f32_e32 v92, 1.0, v92
	v_add_f32_e32 v93, 1.0, v93
	v_rcp_f32_e32 v92, v92
	v_rcp_f32_e32 v93, v93
	v_pk_fma_f32 v[36:37], v[36:37], v[94:95], v[60:61]
	v_pk_fma_f32 v[0:1], v[0:1], v[106:107], v[24:25]
	v_pk_fma_f32 v[34:35], v[34:35], v[110:111], v[58:59]
	v_pk_mul_f32 v[78:79], v[78:79], v[92:93]
	v_mul_f32_e32 v92, 0xbfb8aa3b, v76
	v_mul_f32_e32 v93, 0xbfb8aa3b, v77
	v_exp_f32_e32 v92, v92
	v_exp_f32_e32 v93, v93
	v_pk_mul_f32 v[78:79], v[102:103], v[78:79]
	v_pk_fma_f32 v[2:3], v[2:3], v[64:65], v[26:27]
	v_add_f32_e32 v92, 1.0, v92
	v_add_f32_e32 v93, 1.0, v93
	v_rcp_f32_e32 v92, v92
	v_rcp_f32_e32 v93, v93
	s_nop 0
	v_pk_mul_f32 v[76:77], v[76:77], v[92:93]
	v_mul_f32_e32 v92, 0xbfb8aa3b, v74
	v_mul_f32_e32 v93, 0xbfb8aa3b, v75
	v_exp_f32_e32 v92, v92
	v_exp_f32_e32 v93, v93
	v_pk_mul_f32 v[76:77], v[100:101], v[76:77]
	v_add_f32_e32 v92, 1.0, v92
	v_add_f32_e32 v93, 1.0, v93
	v_rcp_f32_e32 v92, v92
	v_rcp_f32_e32 v93, v93
	v_cvt_pk_bf16_f32 v76, v76, v77
	v_pk_mul_f32 v[74:75], v[74:75], v[92:93]
	s_nop 0
	v_pk_mul_f32 v[92:93], v[98:99], v[74:75]
	v_cvt_pk_bf16_f32 v74, v66, v67
	v_cvt_pk_bf16_f32 v75, v78, v79
	v_cvt_pk_bf16_f32 v77, v92, v93
	v_mad_i64_i32 v[66:67], s[6:7], v118, s12, v[68:69]
	global_store_dwordx4 v[66:67], v[74:77], off
	v_mad_i64_i32 v[66:67], s[6:7], v127, s40, v[72:73]
	v_lshl_add_u64 v[92:93], v[66:67], 0, v[70:71]
	s_waitcnt vmcnt(1)
	v_mov_b32_e32 v74, v244
	v_mov_b32_e32 v75, v245
	v_mov_b32_e32 v76, v246
	v_mov_b32_e32 v77, v247
	v_pk_fma_f32 v[118:119], v[32:33], v[120:121], v[56:57]
	v_pk_fma_f32 v[32:33], v[32:33], v[114:115], v[56:57]
	v_pk_fma_f32 v[118:119], v[40:41], v[114:115], v[118:119]
	v_lshlrev_b32_e32 v98, 16, v74
	v_and_b32_e32 v99, 0xffff0000, v74
	v_lshlrev_b32_e32 v78, 16, v75
	v_and_b32_e32 v79, 0xffff0000, v75
	v_lshlrev_b32_e32 v74, 16, v76
	v_and_b32_e32 v75, 0xffff0000, v76
	v_add_co_u32_e32 v76, vcc, s75, v92
	v_lshlrev_b32_e32 v66, 16, v77
	v_and_b32_e32 v67, 0xffff0000, v77
	v_addc_co_u32_e32 v77, vcc, 0, v93, vcc
	v_mov_b32_e32 v128, v248
	v_mov_b32_e32 v129, v249
	v_mov_b32_e32 v130, v250
	v_mov_b32_e32 v131, v251
	v_pk_fma_f32 v[96:97], v[52:53], v[98:99], v[96:97]
	v_pk_fma_f32 v[90:91], v[54:55], v[78:79], v[90:91]
	v_mul_f32_e32 v104, 0xbfb8aa3b, v96
	v_mul_f32_e32 v105, 0xbfb8aa3b, v97
	v_exp_f32_e32 v104, v104
	v_exp_f32_e32 v105, v105
	v_pk_fma_f32 v[86:87], v[20:21], v[74:75], v[86:87]
	v_pk_fma_f32 v[82:83], v[22:23], v[66:67], v[82:83]
	v_add_f32_e32 v104, 1.0, v104
	v_add_f32_e32 v105, 1.0, v105
	v_rcp_f32_e32 v104, v104
	v_rcp_f32_e32 v105, v105
	v_pk_fma_f32 v[36:37], v[44:45], v[98:99], v[36:37]
	v_pk_fma_f32 v[4:5], v[12:13], v[74:75], v[4:5]
	v_pk_mul_f32 v[96:97], v[96:97], v[104:105]
	v_mul_f32_e32 v104, 0xbfb8aa3b, v90
	v_mul_f32_e32 v105, 0xbfb8aa3b, v91
	v_exp_f32_e32 v104, v104
	v_exp_f32_e32 v105, v105
	v_add_f32_e32 v104, 1.0, v104
	v_add_f32_e32 v105, 1.0, v105
	v_rcp_f32_e32 v104, v104
	v_rcp_f32_e32 v105, v105
	v_add_co_u32_e32 v252, vcc, 0x5600, v252
	s_nop 1
	v_addc_co_u32_e32 v253, vcc, 0, v253, vcc
	global_load_dwordx4 v[244:247], v[252:253], off
	v_add_co_u32_e32 v248, vcc, 0x2b00, v252
	s_nop 1
	v_addc_co_u32_e32 v249, vcc, 0, v253, vcc
	global_load_dwordx4 v[248:251], v[248:249], off
	v_lshlrev_b32_e32 v102, 16, v128
	v_pk_mul_f32 v[90:91], v[90:91], v[104:105]
	v_mul_f32_e32 v104, 0xbfb8aa3b, v86
	v_mul_f32_e32 v105, 0xbfb8aa3b, v87
	v_exp_f32_e32 v104, v104
	v_exp_f32_e32 v105, v105
	v_and_b32_e32 v103, 0xffff0000, v128
	v_lshlrev_b32_e32 v100, 16, v129
	v_add_f32_e32 v104, 1.0, v104
	v_add_f32_e32 v105, 1.0, v105
	v_rcp_f32_e32 v104, v104
	v_rcp_f32_e32 v105, v105
	v_and_b32_e32 v101, 0xffff0000, v129
	v_lshlrev_b32_e32 v92, 16, v130
	v_and_b32_e32 v93, 0xffff0000, v130
	v_pk_mul_f32 v[86:87], v[86:87], v[104:105]
	v_mul_f32_e32 v104, 0xbfb8aa3b, v82
	v_mul_f32_e32 v105, 0xbfb8aa3b, v83
	v_exp_f32_e32 v104, v104
	v_exp_f32_e32 v105, v105
	v_lshlrev_b32_e32 v76, 16, v131
	v_and_b32_e32 v77, 0xffff0000, v131
	v_add_f32_e32 v104, 1.0, v104
	v_add_f32_e32 v105, 1.0, v105
	v_rcp_f32_e32 v104, v104
	v_rcp_f32_e32 v105, v105
	v_pk_fma_f32 v[118:119], v[48:49], v[102:103], v[118:119]
	v_pk_fma_f32 v[116:117], v[50:51], v[100:101], v[116:117]
	v_pk_fma_f32 v[112:113], v[16:17], v[92:93], v[112:113]
	v_pk_fma_f32 v[108:109], v[18:19], v[76:77], v[108:109]
	v_pk_mul_f32 v[82:83], v[82:83], v[104:105]
	v_pk_mul_f32 v[96:97], v[118:119], v[96:97]
	v_pk_mul_f32 v[90:91], v[116:117], v[90:91]
	v_pk_mul_f32 v[86:87], v[112:113], v[86:87]
	v_pk_mul_f32 v[82:83], v[108:109], v[82:83]
	v_or_b32_e32 v112, 7, v126
	v_cvt_pk_bf16_f32 v116, v96, v97
	v_cvt_pk_bf16_f32 v117, v90, v91
	v_cvt_pk_bf16_f32 v118, v86, v87
	v_cvt_pk_bf16_f32 v119, v82, v83
	v_mad_i64_i32 v[82:83], s[6:7], v127, s12, v[68:69]
	v_mad_i64_i32 v[72:73], s[6:7], v112, s40, v[72:73]
	global_store_dwordx4 v[82:83], v[116:119], off
	v_lshl_add_u64 v[82:83], v[72:73], 0, v[70:71]
	s_waitcnt vmcnt(1)
	v_mov_b32_e32 v70, v244
	v_mov_b32_e32 v71, v245
	v_mov_b32_e32 v72, v246
	v_mov_b32_e32 v73, v247
	v_pk_fma_f32 v[32:33], v[40:41], v[102:103], v[32:33]
	v_pk_fma_f32 v[0:1], v[8:9], v[92:93], v[0:1]
	v_pk_fma_f32 v[34:35], v[42:43], v[100:101], v[34:35]
	v_pk_fma_f32 v[2:3], v[10:11], v[76:77], v[2:3]
	v_lshlrev_b32_e32 v96, 16, v72
	v_and_b32_e32 v97, 0xffff0000, v72
	v_add_co_u32_e32 v72, vcc, s75, v82
	v_lshlrev_b32_e32 v86, 16, v70
	v_and_b32_e32 v87, 0xffff0000, v70
	v_lshlrev_b32_e32 v90, 16, v71
	v_and_b32_e32 v91, 0xffff0000, v71
	v_lshlrev_b32_e32 v70, 16, v73
	v_and_b32_e32 v71, 0xffff0000, v73
	v_addc_co_u32_e32 v73, vcc, 0, v83, vcc
	v_mov_b32_e32 v116, v248
	v_mov_b32_e32 v117, v249
	v_mov_b32_e32 v118, v250
	v_mov_b32_e32 v119, v251
	v_pk_fma_f32 v[36:37], v[52:53], v[86:87], v[36:37]
	v_pk_fma_f32 v[4:5], v[20:21], v[96:97], v[4:5]
	v_mul_f32_e32 v44, 0xbfb8aa3b, v36
	v_mul_f32_e32 v40, 0xbfb8aa3b, v37
	v_mul_f32_e32 v12, 0xbfb8aa3b, v4
	v_mul_f32_e32 v8, 0xbfb8aa3b, v5
	v_exp_f32_e32 v44, v44
	v_exp_f32_e32 v40, v40
	v_exp_f32_e32 v12, v12
	v_exp_f32_e32 v8, v8
	v_add_f32_e32 v44, 1.0, v44
	v_add_f32_e32 v40, 1.0, v40
	v_add_f32_e32 v12, 1.0, v12
	v_add_f32_e32 v8, 1.0, v8
	v_rcp_f32_e32 v44, v44
	v_rcp_f32_e32 v45, v40
	v_rcp_f32_e32 v12, v12
	v_rcp_f32_e32 v13, v8
	v_pk_mul_f32 v[36:37], v[36:37], v[44:45]
	v_pk_mul_f32 v[4:5], v[4:5], v[12:13]
	v_lshlrev_b32_e32 v72, 16, v116
	v_and_b32_e32 v73, 0xffff0000, v116
	v_lshlrev_b32_e32 v104, 16, v118
	v_and_b32_e32 v105, 0xffff0000, v118
	v_pk_fma_f32 v[32:33], v[48:49], v[72:73], v[32:33]
	v_pk_fma_f32 v[0:1], v[16:17], v[104:105], v[0:1]
	v_pk_mul_f32 v[32:33], v[32:33], v[36:37]
	v_pk_fma_f32 v[36:37], v[38:39], v[88:89], v[62:63]
	v_pk_mul_f32 v[4:5], v[0:1], v[4:5]
	v_pk_fma_f32 v[0:1], v[6:7], v[80:81], v[30:31]
	v_pk_fma_f32 v[36:37], v[46:47], v[78:79], v[36:37]
	v_pk_fma_f32 v[0:1], v[14:15], v[66:67], v[0:1]
	v_pk_fma_f32 v[36:37], v[54:55], v[90:91], v[36:37]
	v_pk_fma_f32 v[0:1], v[22:23], v[70:71], v[0:1]
	v_mul_f32_e32 v38, 0xbfb8aa3b, v36
	v_mul_f32_e32 v39, 0xbfb8aa3b, v37
	v_mul_f32_e32 v6, 0xbfb8aa3b, v0
	v_mul_f32_e32 v7, 0xbfb8aa3b, v1
	v_exp_f32_e32 v38, v38
	v_exp_f32_e32 v39, v39
	v_exp_f32_e32 v6, v6
	v_exp_f32_e32 v7, v7
	v_add_f32_e32 v38, 1.0, v38
	v_add_f32_e32 v39, 1.0, v39
	v_add_f32_e32 v6, 1.0, v6
	v_add_f32_e32 v7, 1.0, v7
	v_rcp_f32_e32 v38, v38
	v_rcp_f32_e32 v39, v39
	v_rcp_f32_e32 v6, v6
	v_rcp_f32_e32 v7, v7
	v_lshlrev_b32_e32 v82, 16, v117
	v_and_b32_e32 v83, 0xffff0000, v117
	v_lshlrev_b32_e32 v108, 16, v119
	v_and_b32_e32 v109, 0xffff0000, v119
	v_pk_fma_f32 v[34:35], v[50:51], v[82:83], v[34:35]
	v_pk_mul_f32 v[36:37], v[36:37], v[38:39]
	v_pk_fma_f32 v[2:3], v[18:19], v[108:109], v[2:3]
	v_pk_mul_f32 v[0:1], v[0:1], v[6:7]
	v_pk_mul_f32 v[34:35], v[34:35], v[36:37]
	v_pk_mul_f32 v[6:7], v[2:3], v[0:1]
	v_cvt_pk_bf16_f32 v2, v4, v5
	v_mad_i64_i32 v[4:5], s[6:7], v112, s12, v[68:69]
	v_cvt_pk_bf16_f32 v0, v32, v33
	v_cvt_pk_bf16_f32 v1, v34, v35
	v_cvt_pk_bf16_f32 v3, v6, v7
	s_mov_b32 s6, 0x8d7ff
	global_store_dwordx4 v[4:5], v[0:3], off
	v_cmp_lt_i32_e32 vcc, s6, v125
	s_or_b64 s[4:5], vcc, s[4:5]
	v_add_u32_e32 v0, 0x1e800, v125
	v_mov_b32_e32 v125, v0
	s_andn2_b64 exec, exec, s[4:5]
	s_cbranch_execz .LBB0_1407

.LBB0_1474:
	s_or_b64 exec, exec, s[8:9]
	v_readlane_b32 s2, v240, 46
	v_readlane_b32 s3, v240, 47
	v_mov_b64_e32 v[100:101], s[94:95]
	s_waitcnt vmcnt(2)
	v_pk_fma_f32 v[92:93], v[36:37], v[92:93], v[60:61]
	v_lshl_add_u64 v[98:99], s[2:3], 0, v[96:97]
	v_mad_i64_i32 v[102:103], s[2:3], v137, s40, v[100:101]
	v_lshl_add_u64 v[112:113], v[102:103], 0, v[96:97]
	global_load_dwordx4 v[106:109], v[112:113], off
	v_mov_b32_e32 v252, v112
	v_mov_b32_e32 v253, v113
	v_pk_fma_f32 v[92:93], v[44:45], v[68:69], v[92:93]
	s_waitcnt vmcnt(1)
	v_pk_fma_f32 v[88:89], v[32:33], v[88:89], v[56:57]
	v_pk_fma_f32 v[90:91], v[34:35], v[90:91], v[58:59]
	v_pk_fma_f32 v[88:89], v[40:41], v[76:77], v[88:89]
	v_pk_fma_f32 v[84:85], v[4:5], v[84:85], v[28:29]
	v_pk_fma_f32 v[90:91], v[42:43], v[78:79], v[90:91]
	v_pk_fma_f32 v[84:85], v[12:13], v[64:65], v[84:85]
	v_pk_fma_f32 v[80:81], v[0:1], v[80:81], v[24:25]
	v_pk_fma_f32 v[82:83], v[2:3], v[82:83], v[26:27]
	v_pk_fma_f32 v[80:81], v[8:9], v[72:73], v[80:81]
	v_pk_fma_f32 v[82:83], v[10:11], v[74:75], v[82:83]
	s_movk_i32 s8, 0x2b00
	v_pk_fma_f32 v[68:69], v[36:37], v[68:69], v[60:61]
	v_pk_fma_f32 v[76:77], v[32:33], v[76:77], v[56:57]
	v_pk_fma_f32 v[64:65], v[4:5], v[64:65], v[28:29]
	v_pk_fma_f32 v[72:73], v[0:1], v[72:73], v[24:25]
	v_pk_fma_f32 v[78:79], v[34:35], v[78:79], v[58:59]
	v_pk_fma_f32 v[74:75], v[2:3], v[74:75], v[26:27]
	v_add_u32_e32 v135, s15, v135
	v_add_u32_e32 v136, s28, v136
	s_waitcnt vmcnt(0)
	v_lshlrev_b32_e32 v104, 16, v108
	v_and_b32_e32 v105, 0xffff0000, v108
	v_add_co_u32_e32 v108, vcc, s75, v112
	v_lshlrev_b32_e32 v102, 16, v109
	v_and_b32_e32 v103, 0xffff0000, v109
	v_addc_co_u32_e32 v109, vcc, 0, v113, vcc
	global_load_dwordx4 v[118:121], v[108:109], off offset:2816
	v_add_co_u32_e32 v252, vcc, 0x5600, v252
	s_nop 1
	v_addc_co_u32_e32 v253, vcc, 0, v253, vcc
	global_load_dwordx4 v[244:247], v[252:253], off
	v_add_co_u32_e32 v248, vcc, 0x2b00, v252
	s_nop 1
	v_addc_co_u32_e32 v249, vcc, 0, v253, vcc
	global_load_dwordx4 v[248:251], v[248:249], off
	v_lshlrev_b32_e32 v110, 16, v106
	v_and_b32_e32 v111, 0xffff0000, v106
	v_pk_fma_f32 v[92:93], v[52:53], v[110:111], v[92:93]
	v_lshlrev_b32_e32 v106, 16, v107
	v_and_b32_e32 v107, 0xffff0000, v107
	v_pk_fma_f32 v[84:85], v[20:21], v[104:105], v[84:85]
	v_pk_fma_f32 v[68:69], v[44:45], v[110:111], v[68:69]
	v_pk_fma_f32 v[64:65], v[12:13], v[104:105], v[64:65]
	s_waitcnt vmcnt(0)
	v_lshlrev_b32_e32 v116, 16, v118
	v_and_b32_e32 v117, 0xffff0000, v118
	v_lshlrev_b32_e32 v114, 16, v119
	v_and_b32_e32 v115, 0xffff0000, v119
	v_mul_f32_e32 v118, 0xbfb8aa3b, v92
	v_mul_f32_e32 v119, 0xbfb8aa3b, v93
	v_exp_f32_e32 v118, v118
	v_exp_f32_e32 v119, v119
	v_pk_fma_f32 v[88:89], v[48:49], v[116:117], v[88:89]
	v_pk_fma_f32 v[90:91], v[50:51], v[114:115], v[90:91]
	v_add_f32_e32 v118, 1.0, v118
	v_add_f32_e32 v119, 1.0, v119
	v_rcp_f32_e32 v118, v118
	v_rcp_f32_e32 v119, v119
	v_lshlrev_b32_e32 v112, 16, v120
	v_and_b32_e32 v113, 0xffff0000, v120
	v_pk_fma_f32 v[80:81], v[16:17], v[112:113], v[80:81]
	v_pk_mul_f32 v[92:93], v[92:93], v[118:119]
	v_lshlrev_b32_e32 v108, 16, v121
	v_pk_mul_f32 v[88:89], v[88:89], v[92:93]
	v_pk_fma_f32 v[92:93], v[38:39], v[94:95], v[62:63]
	v_and_b32_e32 v109, 0xffff0000, v121
	v_pk_fma_f32 v[92:93], v[46:47], v[70:71], v[92:93]
	v_pk_fma_f32 v[82:83], v[18:19], v[108:109], v[82:83]
	v_pk_fma_f32 v[92:93], v[54:55], v[106:107], v[92:93]
	v_pk_fma_f32 v[70:71], v[38:39], v[70:71], v[62:63]
	v_mul_f32_e32 v94, 0xbfb8aa3b, v92
	v_mul_f32_e32 v95, 0xbfb8aa3b, v93
	v_exp_f32_e32 v94, v94
	v_exp_f32_e32 v95, v95
	v_pk_fma_f32 v[76:77], v[40:41], v[116:117], v[76:77]
	v_pk_fma_f32 v[70:71], v[46:47], v[106:107], v[70:71]
	v_add_f32_e32 v94, 1.0, v94
	v_add_f32_e32 v95, 1.0, v95
	v_rcp_f32_e32 v94, v94
	v_rcp_f32_e32 v95, v95
	v_pk_fma_f32 v[72:73], v[8:9], v[112:113], v[72:73]
	v_pk_fma_f32 v[78:79], v[42:43], v[114:115], v[78:79]
	v_pk_fma_f32 v[74:75], v[10:11], v[108:109], v[74:75]
	v_pk_mul_f32 v[92:93], v[92:93], v[94:95]
	v_or_b32_e32 v94, 1, v137
	v_pk_mul_f32 v[90:91], v[90:91], v[92:93]
	v_mul_f32_e32 v92, 0xbfb8aa3b, v84
	v_mul_f32_e32 v93, 0xbfb8aa3b, v85
	v_exp_f32_e32 v92, v92
	v_exp_f32_e32 v93, v93
	v_add_f32_e32 v92, 1.0, v92
	v_add_f32_e32 v93, 1.0, v93
	v_rcp_f32_e32 v92, v92
	v_rcp_f32_e32 v93, v93
	s_nop 0
	v_pk_mul_f32 v[84:85], v[84:85], v[92:93]
	s_nop 0
	v_pk_mul_f32 v[84:85], v[80:81], v[84:85]
	v_pk_fma_f32 v[80:81], v[6:7], v[86:87], v[30:31]
	s_nop 0
	v_pk_fma_f32 v[80:81], v[14:15], v[66:67], v[80:81]
	s_nop 0
	v_pk_fma_f32 v[80:81], v[22:23], v[102:103], v[80:81]
	s_nop 0
	v_mul_f32_e32 v86, 0xbfb8aa3b, v80
	v_mul_f32_e32 v87, 0xbfb8aa3b, v81
	v_exp_f32_e32 v86, v86
	v_exp_f32_e32 v87, v87
	v_add_f32_e32 v86, 1.0, v86
	v_add_f32_e32 v87, 1.0, v87
	v_rcp_f32_e32 v86, v86
	v_rcp_f32_e32 v87, v87
	s_nop 0
	v_pk_mul_f32 v[80:81], v[80:81], v[86:87]
	s_nop 0
	v_pk_mul_f32 v[86:87], v[82:83], v[80:81]
	v_cvt_pk_bf16_f32 v80, v88, v89
	v_cvt_pk_bf16_f32 v81, v90, v91
	v_cvt_pk_bf16_f32 v82, v84, v85
	v_cvt_pk_bf16_f32 v83, v86, v87
	v_mad_i64_i32 v[84:85], s[2:3], v137, s8, v[98:99]
	global_store_dwordx4 v[84:85], v[80:83], off
	s_nop 1
	v_mad_i64_i32 v[80:81], s[2:3], v94, s40, v[100:101]
	v_lshl_add_u64 v[92:93], v[80:81], 0, v[96:97]
	s_waitcnt vmcnt(1)
	v_mov_b32_e32 v80, v244
	v_mov_b32_e32 v81, v245
	v_mov_b32_e32 v82, v246
	v_mov_b32_e32 v83, v247
	v_lshlrev_b32_e32 v90, 16, v80
	v_and_b32_e32 v91, 0xffff0000, v80
	v_add_co_u32_e32 v80, vcc, s75, v92
	v_lshlrev_b32_e32 v88, 16, v81
	v_and_b32_e32 v89, 0xffff0000, v81
	v_addc_co_u32_e32 v81, vcc, 0, v93, vcc
	v_lshlrev_b32_e32 v86, 16, v82
	v_and_b32_e32 v87, 0xffff0000, v82
	v_lshlrev_b32_e32 v84, 16, v83
	v_and_b32_e32 v85, 0xffff0000, v83
	v_mov_b32_e32 v80, v248
	v_mov_b32_e32 v81, v249
	v_mov_b32_e32 v82, v250
	v_mov_b32_e32 v83, v251
	v_pk_fma_f32 v[68:69], v[52:53], v[90:91], v[68:69]
	v_pk_fma_f32 v[70:71], v[54:55], v[88:89], v[70:71]
	v_pk_fma_f32 v[64:65], v[20:21], v[86:87], v[64:65]
	v_or_b32_e32 v92, 2, v137
	v_add_co_u32_e32 v252, vcc, 0x5600, v252
	s_nop 1
	v_addc_co_u32_e32 v253, vcc, 0, v253, vcc
	global_load_dwordx4 v[244:247], v[252:253], off
	v_add_co_u32_e32 v248, vcc, 0x2b00, v252
	s_nop 1
	v_addc_co_u32_e32 v249, vcc, 0, v253, vcc
	global_load_dwordx4 v[248:251], v[248:249], off
	v_lshlrev_b32_e32 v132, 16, v80
	v_and_b32_e32 v133, 0xffff0000, v80
	v_lshlrev_b32_e32 v128, 16, v81
	v_and_b32_e32 v129, 0xffff0000, v81
	v_mul_f32_e32 v80, 0xbfb8aa3b, v68
	v_mul_f32_e32 v81, 0xbfb8aa3b, v69
	v_exp_f32_e32 v80, v80
	v_exp_f32_e32 v81, v81
	v_pk_fma_f32 v[76:77], v[48:49], v[132:133], v[76:77]
	v_lshlrev_b32_e32 v124, 16, v82
	v_add_f32_e32 v80, 1.0, v80
	v_add_f32_e32 v81, 1.0, v81
	v_rcp_f32_e32 v80, v80
	v_rcp_f32_e32 v81, v81
	v_and_b32_e32 v125, 0xffff0000, v82
	v_pk_fma_f32 v[72:73], v[16:17], v[124:125], v[72:73]
	v_lshlrev_b32_e32 v120, 16, v83
	v_pk_mul_f32 v[68:69], v[68:69], v[80:81]
	v_and_b32_e32 v121, 0xffff0000, v83
	v_pk_mul_f32 v[68:69], v[76:77], v[68:69]
	v_mul_f32_e32 v76, 0xbfb8aa3b, v70
	v_mul_f32_e32 v77, 0xbfb8aa3b, v71
	v_exp_f32_e32 v76, v76
	v_exp_f32_e32 v77, v77
	v_pk_fma_f32 v[78:79], v[50:51], v[128:129], v[78:79]
	v_pk_fma_f32 v[74:75], v[18:19], v[120:121], v[74:75]
	v_add_f32_e32 v76, 1.0, v76
	v_add_f32_e32 v77, 1.0, v77
	v_rcp_f32_e32 v76, v76
	v_rcp_f32_e32 v77, v77
	v_pk_fma_f32 v[80:81], v[2:3], v[108:109], v[26:27]
	v_pk_mul_f32 v[70:71], v[70:71], v[76:77]
	v_mul_f32_e32 v76, 0xbfb8aa3b, v64
	v_mul_f32_e32 v77, 0xbfb8aa3b, v65
	v_exp_f32_e32 v76, v76
	v_exp_f32_e32 v77, v77
	v_pk_mul_f32 v[70:71], v[78:79], v[70:71]
	v_pk_fma_f32 v[80:81], v[10:11], v[120:121], v[80:81]
	v_add_f32_e32 v76, 1.0, v76
	v_add_f32_e32 v77, 1.0, v77
	v_rcp_f32_e32 v76, v76
	v_rcp_f32_e32 v77, v77
	s_nop 0
	v_pk_mul_f32 v[64:65], v[64:65], v[76:77]
	s_nop 0
	v_pk_mul_f32 v[72:73], v[72:73], v[64:65]
	v_pk_fma_f32 v[64:65], v[6:7], v[66:67], v[30:31]
	s_nop 0
	v_pk_fma_f32 v[64:65], v[14:15], v[102:103], v[64:65]
	s_nop 0
	v_pk_fma_f32 v[64:65], v[22:23], v[84:85], v[64:65]
	s_nop 0
	v_mul_f32_e32 v66, 0xbfb8aa3b, v64
	v_mul_f32_e32 v67, 0xbfb8aa3b, v65
	v_exp_f32_e32 v66, v66
	v_exp_f32_e32 v67, v67
	v_add_f32_e32 v66, 1.0, v66
	v_add_f32_e32 v67, 1.0, v67
	v_rcp_f32_e32 v66, v66
	v_rcp_f32_e32 v67, v67
	s_nop 0
	v_pk_mul_f32 v[64:65], v[64:65], v[66:67]
	s_nop 0
	v_pk_mul_f32 v[74:75], v[74:75], v[64:65]
	v_cvt_pk_bf16_f32 v64, v68, v69
	v_cvt_pk_bf16_f32 v65, v70, v71
	v_cvt_pk_bf16_f32 v66, v72, v73
	v_cvt_pk_bf16_f32 v67, v74, v75
	v_mad_i64_i32 v[68:69], s[2:3], v94, s8, v[98:99]
	global_store_dwordx4 v[68:69], v[64:67], off
	v_pk_fma_f32 v[70:71], v[34:35], v[114:115], v[58:59]
	v_pk_fma_f32 v[72:73], v[0:1], v[112:113], v[24:25]
	v_mad_i64_i32 v[64:65], s[2:3], v92, s40, v[100:101]
	v_lshl_add_u64 v[68:69], v[64:65], 0, v[96:97]
	s_waitcnt vmcnt(1)
	v_mov_b32_e32 v64, v244
	v_mov_b32_e32 v65, v245
	v_mov_b32_e32 v66, v246
	v_mov_b32_e32 v67, v247
	v_pk_fma_f32 v[70:71], v[42:43], v[128:129], v[70:71]
	v_pk_fma_f32 v[72:73], v[8:9], v[124:125], v[72:73]
	v_or_b32_e32 v114, 4, v137
	v_lshlrev_b32_e32 v82, 16, v64
	v_and_b32_e32 v83, 0xffff0000, v64
	v_add_co_u32_e32 v64, vcc, s75, v68
	v_lshlrev_b32_e32 v78, 16, v65
	v_and_b32_e32 v79, 0xffff0000, v65
	v_addc_co_u32_e32 v65, vcc, 0, v69, vcc
	v_lshlrev_b32_e32 v76, 16, v66
	v_and_b32_e32 v77, 0xffff0000, v66
	v_lshlrev_b32_e32 v74, 16, v67
	v_and_b32_e32 v75, 0xffff0000, v67
	v_mov_b32_e32 v64, v248
	v_mov_b32_e32 v65, v249
	v_mov_b32_e32 v66, v250
	v_mov_b32_e32 v67, v251
	v_pk_fma_f32 v[68:69], v[32:33], v[116:117], v[56:57]
	v_add_co_u32_e32 v252, vcc, 0x5600, v252
	s_nop 1
	v_addc_co_u32_e32 v253, vcc, 0, v253, vcc
	global_load_dwordx4 v[244:247], v[252:253], off
	v_add_co_u32_e32 v248, vcc, 0x2b00, v252
	s_nop 1
	v_addc_co_u32_e32 v249, vcc, 0, v253, vcc
	global_load_dwordx4 v[248:251], v[248:249], off
	v_lshlrev_b32_e32 v130, 16, v64
	v_and_b32_e32 v131, 0xffff0000, v64
	v_lshlrev_b32_e32 v126, 16, v65
	v_and_b32_e32 v127, 0xffff0000, v65
	v_pk_fma_f32 v[64:65], v[36:37], v[110:111], v[60:61]
	v_lshlrev_b32_e32 v122, 16, v66
	v_pk_fma_f32 v[64:65], v[44:45], v[90:91], v[64:65]
	v_and_b32_e32 v123, 0xffff0000, v66
	v_pk_fma_f32 v[64:65], v[52:53], v[82:83], v[64:65]
	v_lshlrev_b32_e32 v118, 16, v67
	v_and_b32_e32 v119, 0xffff0000, v67
	v_mul_f32_e32 v66, 0xbfb8aa3b, v64
	v_mul_f32_e32 v67, 0xbfb8aa3b, v65
	v_exp_f32_e32 v66, v66
	v_exp_f32_e32 v67, v67
	v_pk_fma_f32 v[68:69], v[40:41], v[132:133], v[68:69]
	v_pk_fma_f32 v[70:71], v[50:51], v[126:127], v[70:71]
	v_add_f32_e32 v66, 1.0, v66
	v_add_f32_e32 v67, 1.0, v67
	v_rcp_f32_e32 v66, v66
	v_rcp_f32_e32 v67, v67
	v_pk_fma_f32 v[68:69], v[48:49], v[130:131], v[68:69]
	v_pk_fma_f32 v[72:73], v[16:17], v[122:123], v[72:73]
	v_pk_fma_f32 v[80:81], v[18:19], v[118:119], v[80:81]
	v_pk_mul_f32 v[64:65], v[64:65], v[66:67]
	v_pk_fma_f32 v[66:67], v[38:39], v[106:107], v[62:63]
	v_pk_mul_f32 v[64:65], v[68:69], v[64:65]
	v_pk_fma_f32 v[66:67], v[46:47], v[88:89], v[66:67]
	v_cvt_pk_bf16_f32 v64, v64, v65
	v_pk_fma_f32 v[66:67], v[54:55], v[78:79], v[66:67]
	v_or_b32_e32 v106, 3, v137
	v_mul_f32_e32 v68, 0xbfb8aa3b, v66
	v_mul_f32_e32 v69, 0xbfb8aa3b, v67
	v_exp_f32_e32 v68, v68
	v_exp_f32_e32 v69, v69
	v_add_f32_e32 v68, 1.0, v68
	v_add_f32_e32 v69, 1.0, v69
	v_rcp_f32_e32 v68, v68
	v_rcp_f32_e32 v69, v69
	s_nop 0
	v_pk_mul_f32 v[66:67], v[66:67], v[68:69]
	v_pk_fma_f32 v[68:69], v[4:5], v[104:105], v[28:29]
	v_pk_mul_f32 v[66:67], v[70:71], v[66:67]
	v_pk_fma_f32 v[68:69], v[12:13], v[86:87], v[68:69]
	v_cvt_pk_bf16_f32 v65, v66, v67
	v_pk_fma_f32 v[68:69], v[20:21], v[76:77], v[68:69]
	v_pk_fma_f32 v[86:87], v[4:5], v[86:87], v[28:29]
	v_mul_f32_e32 v70, 0xbfb8aa3b, v68
	v_mul_f32_e32 v71, 0xbfb8aa3b, v69
	v_exp_f32_e32 v70, v70
	v_exp_f32_e32 v71, v71
	v_pk_fma_f32 v[86:87], v[12:13], v[76:77], v[86:87]
	v_pk_fma_f32 v[76:77], v[4:5], v[76:77], v[28:29]
	v_add_f32_e32 v70, 1.0, v70
	v_add_f32_e32 v71, 1.0, v71
	v_rcp_f32_e32 v70, v70
	v_rcp_f32_e32 v71, v71
	s_nop 0
	v_pk_mul_f32 v[68:69], v[68:69], v[70:71]
	v_pk_fma_f32 v[70:71], v[6:7], v[102:103], v[30:31]
	v_pk_mul_f32 v[68:69], v[72:73], v[68:69]
	v_pk_fma_f32 v[70:71], v[14:15], v[84:85], v[70:71]
	v_cvt_pk_bf16_f32 v66, v68, v69
	v_pk_fma_f32 v[70:71], v[22:23], v[74:75], v[70:71]
	v_mad_i64_i32 v[68:69], s[2:3], v92, s8, v[98:99]
	v_mul_f32_e32 v72, 0xbfb8aa3b, v70
	v_mul_f32_e32 v73, 0xbfb8aa3b, v71
	v_exp_f32_e32 v72, v72
	v_exp_f32_e32 v73, v73
	v_pk_fma_f32 v[84:85], v[6:7], v[84:85], v[30:31]
	v_add_f32_e32 v72, 1.0, v72
	v_add_f32_e32 v73, 1.0, v73
	v_rcp_f32_e32 v72, v72
	v_rcp_f32_e32 v73, v73
	v_pk_fma_f32 v[84:85], v[14:15], v[74:75], v[84:85]
	v_pk_fma_f32 v[74:75], v[6:7], v[74:75], v[30:31]
	v_pk_mul_f32 v[70:71], v[70:71], v[72:73]
	s_nop 0
	v_pk_mul_f32 v[70:71], v[80:81], v[70:71]
	s_nop 0
	v_cvt_pk_bf16_f32 v67, v70, v71
	global_store_dwordx4 v[68:69], v[64:67], off
	s_nop 1
	v_mad_i64_i32 v[64:65], s[2:3], v106, s40, v[100:101]
	v_lshl_add_u64 v[92:93], v[64:65], 0, v[96:97]
	s_waitcnt vmcnt(1)
	v_mov_b32_e32 v64, v244
	v_mov_b32_e32 v65, v245
	v_mov_b32_e32 v66, v246
	v_mov_b32_e32 v67, v247
	v_lshlrev_b32_e32 v80, 16, v64
	v_and_b32_e32 v81, 0xffff0000, v64
	v_add_co_u32_e32 v64, vcc, s75, v92
	v_lshlrev_b32_e32 v72, 16, v65
	v_and_b32_e32 v73, 0xffff0000, v65
	v_addc_co_u32_e32 v65, vcc, 0, v93, vcc
	v_lshlrev_b32_e32 v70, 16, v66
	v_and_b32_e32 v71, 0xffff0000, v66
	v_lshlrev_b32_e32 v68, 16, v67
	v_and_b32_e32 v69, 0xffff0000, v67
	v_mov_b32_e32 v64, v248
	v_mov_b32_e32 v65, v249
	v_mov_b32_e32 v66, v250
	v_mov_b32_e32 v67, v251
	v_pk_fma_f32 v[86:87], v[20:21], v[70:71], v[86:87]
	v_pk_fma_f32 v[84:85], v[22:23], v[68:69], v[84:85]
	v_pk_fma_f32 v[76:77], v[12:13], v[70:71], v[76:77]
	v_pk_fma_f32 v[74:75], v[14:15], v[68:69], v[74:75]
	v_pk_fma_f32 v[70:71], v[4:5], v[70:71], v[28:29]
	v_pk_fma_f32 v[68:69], v[6:7], v[68:69], v[30:31]
	v_add_co_u32_e32 v252, vcc, 0x5600, v252
	s_nop 1
	v_addc_co_u32_e32 v253, vcc, 0, v253, vcc
	global_load_dwordx4 v[244:247], v[252:253], off
	v_add_co_u32_e32 v248, vcc, 0x2b00, v252
	s_nop 1
	v_addc_co_u32_e32 v249, vcc, 0, v253, vcc
	global_load_dwordx4 v[248:251], v[248:249], off
	v_lshlrev_b32_e32 v104, 16, v64
	v_and_b32_e32 v105, 0xffff0000, v64
	v_lshlrev_b32_e32 v102, 16, v65
	v_and_b32_e32 v103, 0xffff0000, v65
	v_pk_fma_f32 v[64:65], v[36:37], v[90:91], v[60:61]
	v_lshlrev_b32_e32 v94, 16, v66
	v_pk_fma_f32 v[64:65], v[44:45], v[82:83], v[64:65]
	v_and_b32_e32 v95, 0xffff0000, v66
	v_pk_fma_f32 v[64:65], v[52:53], v[80:81], v[64:65]
	v_lshlrev_b32_e32 v92, 16, v67
	v_and_b32_e32 v93, 0xffff0000, v67
	v_mul_f32_e32 v66, 0xbfb8aa3b, v64
	v_mul_f32_e32 v67, 0xbfb8aa3b, v65
	v_exp_f32_e32 v66, v66
	v_exp_f32_e32 v67, v67
	v_pk_fma_f32 v[90:91], v[32:33], v[132:133], v[56:57]
	v_add_f32_e32 v66, 1.0, v66
	v_add_f32_e32 v67, 1.0, v67
	v_rcp_f32_e32 v66, v66
	v_rcp_f32_e32 v67, v67
	v_pk_fma_f32 v[90:91], v[40:41], v[130:131], v[90:91]
	v_pk_mul_f32 v[64:65], v[64:65], v[66:67]
	v_pk_fma_f32 v[66:67], v[38:39], v[88:89], v[62:63]
	v_pk_fma_f32 v[90:91], v[48:49], v[104:105], v[90:91]
	v_pk_fma_f32 v[66:67], v[46:47], v[78:79], v[66:67]
	v_pk_mul_f32 v[64:65], v[90:91], v[64:65]
	v_pk_fma_f32 v[66:67], v[54:55], v[72:73], v[66:67]
	v_pk_fma_f32 v[90:91], v[34:35], v[128:129], v[58:59]
	v_mul_f32_e32 v88, 0xbfb8aa3b, v66
	v_mul_f32_e32 v89, 0xbfb8aa3b, v67
	v_exp_f32_e32 v88, v88
	v_exp_f32_e32 v89, v89
	v_pk_fma_f32 v[90:91], v[42:43], v[126:127], v[90:91]
	v_cvt_pk_bf16_f32 v64, v64, v65
	v_add_f32_e32 v88, 1.0, v88
	v_add_f32_e32 v89, 1.0, v89
	v_rcp_f32_e32 v88, v88
	v_rcp_f32_e32 v89, v89
	v_pk_fma_f32 v[90:91], v[50:51], v[102:103], v[90:91]
	v_pk_mul_f32 v[66:67], v[66:67], v[88:89]
	v_mul_f32_e32 v88, 0xbfb8aa3b, v86
	v_mul_f32_e32 v89, 0xbfb8aa3b, v87
	v_exp_f32_e32 v88, v88
	v_exp_f32_e32 v89, v89
	v_pk_mul_f32 v[66:67], v[90:91], v[66:67]
	v_pk_fma_f32 v[90:91], v[0:1], v[124:125], v[24:25]
	v_add_f32_e32 v88, 1.0, v88
	v_add_f32_e32 v89, 1.0, v89
	v_rcp_f32_e32 v88, v88
	v_rcp_f32_e32 v89, v89
	v_pk_fma_f32 v[90:91], v[8:9], v[122:123], v[90:91]
	v_cvt_pk_bf16_f32 v65, v66, v67
	v_pk_fma_f32 v[90:91], v[16:17], v[94:95], v[90:91]
	v_pk_mul_f32 v[86:87], v[86:87], v[88:89]
	v_mul_f32_e32 v88, 0xbfb8aa3b, v84
	v_mul_f32_e32 v89, 0xbfb8aa3b, v85
	v_exp_f32_e32 v88, v88
	v_exp_f32_e32 v89, v89
	v_pk_mul_f32 v[86:87], v[90:91], v[86:87]
	v_pk_fma_f32 v[90:91], v[2:3], v[120:121], v[26:27]
	v_add_f32_e32 v88, 1.0, v88
	v_add_f32_e32 v89, 1.0, v89
	v_rcp_f32_e32 v88, v88
	v_rcp_f32_e32 v89, v89
	v_pk_fma_f32 v[90:91], v[10:11], v[118:119], v[90:91]
	v_cvt_pk_bf16_f32 v66, v86, v87
	v_pk_fma_f32 v[90:91], v[18:19], v[92:93], v[90:91]
	v_pk_mul_f32 v[84:85], v[84:85], v[88:89]
	v_or_b32_e32 v120, 5, v137
	v_pk_mul_f32 v[84:85], v[90:91], v[84:85]
	v_or_b32_e32 v124, 6, v137
	v_cvt_pk_bf16_f32 v67, v84, v85
	v_mad_i64_i32 v[84:85], s[2:3], v106, s8, v[98:99]
	global_store_dwordx4 v[84:85], v[64:67], off
	s_nop 1
	v_mad_i64_i32 v[64:65], s[2:3], v114, s40, v[100:101]
	v_lshl_add_u64 v[106:107], v[64:65], 0, v[96:97]
	s_waitcnt vmcnt(1)
	v_mov_b32_e32 v64, v244
	v_mov_b32_e32 v65, v245
	v_mov_b32_e32 v66, v246
	v_mov_b32_e32 v67, v247
	v_lshlrev_b32_e32 v90, 16, v64
	v_and_b32_e32 v91, 0xffff0000, v64
	v_add_co_u32_e32 v64, vcc, s75, v106
	v_lshlrev_b32_e32 v88, 16, v65
	v_and_b32_e32 v89, 0xffff0000, v65
	v_addc_co_u32_e32 v65, vcc, 0, v107, vcc
	v_lshlrev_b32_e32 v86, 16, v66
	v_and_b32_e32 v87, 0xffff0000, v66
	v_lshlrev_b32_e32 v84, 16, v67
	v_and_b32_e32 v85, 0xffff0000, v67
	v_mov_b32_e32 v64, v248
	v_mov_b32_e32 v65, v249
	v_mov_b32_e32 v66, v250
	v_mov_b32_e32 v67, v251
	v_pk_fma_f32 v[76:77], v[20:21], v[86:87], v[76:77]
	v_pk_fma_f32 v[74:75], v[22:23], v[84:85], v[74:75]
	v_pk_fma_f32 v[70:71], v[12:13], v[86:87], v[70:71]
	v_pk_fma_f32 v[68:69], v[14:15], v[84:85], v[68:69]
	v_pk_fma_f32 v[86:87], v[4:5], v[86:87], v[28:29]
	v_pk_fma_f32 v[84:85], v[6:7], v[84:85], v[30:31]
	v_add_co_u32_e32 v252, vcc, 0x5600, v252
	s_nop 1
	v_addc_co_u32_e32 v253, vcc, 0, v253, vcc
	global_load_dwordx4 v[244:247], v[252:253], off
	v_add_co_u32_e32 v248, vcc, 0x2b00, v252
	s_nop 1
	v_addc_co_u32_e32 v249, vcc, 0, v253, vcc
	global_load_dwordx4 v[248:251], v[248:249], off
	v_lshlrev_b32_e32 v112, 16, v64
	v_and_b32_e32 v113, 0xffff0000, v64
	v_lshlrev_b32_e32 v110, 16, v65
	v_and_b32_e32 v111, 0xffff0000, v65
	v_pk_fma_f32 v[64:65], v[36:37], v[82:83], v[60:61]
	v_lshlrev_b32_e32 v108, 16, v66
	v_pk_fma_f32 v[64:65], v[44:45], v[80:81], v[64:65]
	v_and_b32_e32 v109, 0xffff0000, v66
	v_pk_fma_f32 v[64:65], v[52:53], v[90:91], v[64:65]
	v_lshlrev_b32_e32 v106, 16, v67
	v_and_b32_e32 v107, 0xffff0000, v67
	v_mul_f32_e32 v66, 0xbfb8aa3b, v64
	v_mul_f32_e32 v67, 0xbfb8aa3b, v65
	v_exp_f32_e32 v66, v66
	v_exp_f32_e32 v67, v67
	v_pk_fma_f32 v[82:83], v[32:33], v[130:131], v[56:57]
	v_add_f32_e32 v66, 1.0, v66
	v_add_f32_e32 v67, 1.0, v67
	v_rcp_f32_e32 v66, v66
	v_rcp_f32_e32 v67, v67
	v_pk_fma_f32 v[82:83], v[40:41], v[104:105], v[82:83]
	v_pk_fma_f32 v[104:105], v[32:33], v[104:105], v[56:57]
	v_pk_fma_f32 v[82:83], v[48:49], v[112:113], v[82:83]
	v_pk_mul_f32 v[64:65], v[64:65], v[66:67]
	v_pk_fma_f32 v[66:67], v[38:39], v[78:79], v[62:63]
	v_pk_mul_f32 v[64:65], v[82:83], v[64:65]
	v_pk_fma_f32 v[66:67], v[46:47], v[72:73], v[66:67]
	v_pk_fma_f32 v[82:83], v[34:35], v[126:127], v[58:59]
	v_pk_fma_f32 v[66:67], v[54:55], v[88:89], v[66:67]
	v_pk_fma_f32 v[82:83], v[42:43], v[102:103], v[82:83]
	v_mul_f32_e32 v78, 0xbfb8aa3b, v66
	v_mul_f32_e32 v79, 0xbfb8aa3b, v67
	v_exp_f32_e32 v78, v78
	v_exp_f32_e32 v79, v79
	v_pk_fma_f32 v[82:83], v[50:51], v[110:111], v[82:83]
	v_cvt_pk_bf16_f32 v64, v64, v65
	v_add_f32_e32 v78, 1.0, v78
	v_add_f32_e32 v79, 1.0, v79
	v_rcp_f32_e32 v78, v78
	v_rcp_f32_e32 v79, v79
	v_pk_fma_f32 v[72:73], v[38:39], v[72:73], v[62:63]
	v_pk_fma_f32 v[102:103], v[34:35], v[102:103], v[58:59]
	v_pk_fma_f32 v[72:73], v[46:47], v[88:89], v[72:73]
	v_pk_mul_f32 v[66:67], v[66:67], v[78:79]
	v_mul_f32_e32 v78, 0xbfb8aa3b, v76
	v_mul_f32_e32 v79, 0xbfb8aa3b, v77
	v_exp_f32_e32 v78, v78
	v_exp_f32_e32 v79, v79
	v_pk_mul_f32 v[66:67], v[82:83], v[66:67]
	v_pk_fma_f32 v[82:83], v[0:1], v[122:123], v[24:25]
	v_add_f32_e32 v78, 1.0, v78
	v_add_f32_e32 v79, 1.0, v79
	v_rcp_f32_e32 v78, v78
	v_rcp_f32_e32 v79, v79
	v_pk_fma_f32 v[82:83], v[8:9], v[94:95], v[82:83]
	v_cvt_pk_bf16_f32 v65, v66, v67
	v_pk_fma_f32 v[82:83], v[16:17], v[108:109], v[82:83]
	v_pk_mul_f32 v[76:77], v[76:77], v[78:79]
	v_mul_f32_e32 v78, 0xbfb8aa3b, v74
	v_mul_f32_e32 v79, 0xbfb8aa3b, v75
	v_exp_f32_e32 v78, v78
	v_exp_f32_e32 v79, v79
	v_pk_mul_f32 v[76:77], v[82:83], v[76:77]
	v_pk_fma_f32 v[82:83], v[2:3], v[118:119], v[26:27]
	v_add_f32_e32 v78, 1.0, v78
	v_add_f32_e32 v79, 1.0, v79
	v_rcp_f32_e32 v78, v78
	v_rcp_f32_e32 v79, v79
	v_pk_fma_f32 v[82:83], v[10:11], v[92:93], v[82:83]
	v_cvt_pk_bf16_f32 v66, v76, v77
	v_pk_fma_f32 v[82:83], v[18:19], v[106:107], v[82:83]
	v_pk_mul_f32 v[74:75], v[74:75], v[78:79]
	v_pk_fma_f32 v[94:95], v[0:1], v[94:95], v[24:25]
	v_pk_mul_f32 v[74:75], v[82:83], v[74:75]
	v_pk_fma_f32 v[92:93], v[2:3], v[92:93], v[26:27]
	v_cvt_pk_bf16_f32 v67, v74, v75
	v_mad_i64_i32 v[74:75], s[2:3], v114, s8, v[98:99]
	global_store_dwordx4 v[74:75], v[64:67], off
	v_pk_fma_f32 v[104:105], v[40:41], v[112:113], v[104:105]
	v_pk_fma_f32 v[102:103], v[42:43], v[110:111], v[102:103]
	v_mad_i64_i32 v[64:65], s[2:3], v120, s40, v[100:101]
	v_lshl_add_u64 v[114:115], v[64:65], 0, v[96:97]
	s_waitcnt vmcnt(1)
	v_mov_b32_e32 v64, v244
	v_mov_b32_e32 v65, v245
	v_mov_b32_e32 v66, v246
	v_mov_b32_e32 v67, v247
	v_pk_fma_f32 v[94:95], v[8:9], v[108:109], v[94:95]
	v_pk_fma_f32 v[92:93], v[10:11], v[106:107], v[92:93]
	v_pk_fma_f32 v[88:89], v[38:39], v[88:89], v[62:63]
	v_pk_fma_f32 v[112:113], v[32:33], v[112:113], v[56:57]
	v_pk_fma_f32 v[110:111], v[34:35], v[110:111], v[58:59]
	v_pk_fma_f32 v[108:109], v[0:1], v[108:109], v[24:25]
	v_pk_fma_f32 v[106:107], v[2:3], v[106:107], v[26:27]
	v_lshlrev_b32_e32 v82, 16, v64
	v_and_b32_e32 v83, 0xffff0000, v64
	v_add_co_u32_e32 v64, vcc, s75, v114
	v_lshlrev_b32_e32 v78, 16, v65
	v_and_b32_e32 v79, 0xffff0000, v65
	v_addc_co_u32_e32 v65, vcc, 0, v115, vcc
	v_lshlrev_b32_e32 v76, 16, v66
	v_and_b32_e32 v77, 0xffff0000, v66
	v_lshlrev_b32_e32 v74, 16, v67
	v_and_b32_e32 v75, 0xffff0000, v67
	v_mov_b32_e32 v64, v248
	v_mov_b32_e32 v65, v249
	v_mov_b32_e32 v66, v250
	v_mov_b32_e32 v67, v251
	v_pk_fma_f32 v[72:73], v[54:55], v[78:79], v[72:73]
	v_pk_fma_f32 v[70:71], v[20:21], v[76:77], v[70:71]
	v_pk_fma_f32 v[68:69], v[22:23], v[74:75], v[68:69]
	v_pk_fma_f32 v[88:89], v[46:47], v[78:79], v[88:89]
	v_pk_fma_f32 v[86:87], v[12:13], v[76:77], v[86:87]
	v_pk_fma_f32 v[84:85], v[14:15], v[74:75], v[84:85]
	v_pk_fma_f32 v[4:5], v[4:5], v[76:77], v[28:29]
	v_add_co_u32_e32 v252, vcc, 0x5600, v252
	s_nop 1
	v_addc_co_u32_e32 v253, vcc, 0, v253, vcc
	global_load_dwordx4 v[244:247], v[252:253], off
	v_add_co_u32_e32 v248, vcc, 0x2b00, v252
	s_nop 1
	v_addc_co_u32_e32 v249, vcc, 0, v253, vcc
	global_load_dwordx4 v[248:251], v[248:249], off
	v_lshlrev_b32_e32 v118, 16, v64
	v_and_b32_e32 v119, 0xffff0000, v64
	v_lshlrev_b32_e32 v116, 16, v65
	v_and_b32_e32 v117, 0xffff0000, v65
	v_lshlrev_b32_e32 v114, 16, v66
	v_and_b32_e32 v115, 0xffff0000, v66
	v_lshlrev_b32_e32 v64, 16, v67
	v_and_b32_e32 v65, 0xffff0000, v67
	v_pk_fma_f32 v[66:67], v[36:37], v[80:81], v[60:61]
	v_pk_fma_f32 v[104:105], v[48:49], v[118:119], v[104:105]
	v_pk_fma_f32 v[66:67], v[44:45], v[90:91], v[66:67]
	v_pk_fma_f32 v[102:103], v[50:51], v[116:117], v[102:103]
	v_pk_fma_f32 v[66:67], v[52:53], v[82:83], v[66:67]
	v_pk_fma_f32 v[94:95], v[16:17], v[114:115], v[94:95]
	v_mul_f32_e32 v80, 0xbfb8aa3b, v66
	v_mul_f32_e32 v81, 0xbfb8aa3b, v67
	v_exp_f32_e32 v80, v80
	v_exp_f32_e32 v81, v81
	v_pk_fma_f32 v[92:93], v[18:19], v[64:65], v[92:93]
	v_pk_fma_f32 v[90:91], v[36:37], v[90:91], v[60:61]
	v_add_f32_e32 v80, 1.0, v80
	v_add_f32_e32 v81, 1.0, v81
	v_rcp_f32_e32 v80, v80
	v_rcp_f32_e32 v81, v81
	v_pk_fma_f32 v[90:91], v[44:45], v[82:83], v[90:91]
	v_pk_fma_f32 v[112:113], v[40:41], v[118:119], v[112:113]
	v_pk_fma_f32 v[110:111], v[42:43], v[116:117], v[110:111]
	v_pk_mul_f32 v[66:67], v[66:67], v[80:81]
	v_mul_f32_e32 v80, 0xbfb8aa3b, v72
	v_mul_f32_e32 v81, 0xbfb8aa3b, v73
	v_exp_f32_e32 v80, v80
	v_exp_f32_e32 v81, v81
	v_pk_mul_f32 v[66:67], v[104:105], v[66:67]
	v_pk_fma_f32 v[108:109], v[8:9], v[114:115], v[108:109]
	v_add_f32_e32 v80, 1.0, v80
	v_add_f32_e32 v81, 1.0, v81
	v_rcp_f32_e32 v80, v80
	v_rcp_f32_e32 v81, v81
	v_cvt_pk_bf16_f32 v66, v66, v67
	v_pk_fma_f32 v[106:107], v[10:11], v[64:65], v[106:107]
	v_pk_fma_f32 v[36:37], v[36:37], v[82:83], v[60:61]
	v_pk_mul_f32 v[72:73], v[72:73], v[80:81]
	v_mul_f32_e32 v80, 0xbfb8aa3b, v70
	v_mul_f32_e32 v81, 0xbfb8aa3b, v71
	v_exp_f32_e32 v80, v80
	v_exp_f32_e32 v81, v81
	v_pk_mul_f32 v[72:73], v[102:103], v[72:73]
	v_pk_fma_f32 v[0:1], v[0:1], v[114:115], v[24:25]
	v_add_f32_e32 v80, 1.0, v80
	v_add_f32_e32 v81, 1.0, v81
	v_rcp_f32_e32 v80, v80
	v_rcp_f32_e32 v81, v81
	v_cvt_pk_bf16_f32 v67, v72, v73
	v_pk_fma_f32 v[32:33], v[32:33], v[118:119], v[56:57]
	v_pk_fma_f32 v[2:3], v[2:3], v[64:65], v[26:27]
	v_pk_mul_f32 v[70:71], v[70:71], v[80:81]
	v_mul_f32_e32 v80, 0xbfb8aa3b, v68
	v_mul_f32_e32 v81, 0xbfb8aa3b, v69
	v_exp_f32_e32 v80, v80
	v_exp_f32_e32 v81, v81
	v_pk_mul_f32 v[70:71], v[94:95], v[70:71]
	v_pk_fma_f32 v[34:35], v[34:35], v[116:117], v[58:59]
	v_add_f32_e32 v80, 1.0, v80
	v_add_f32_e32 v81, 1.0, v81
	v_rcp_f32_e32 v80, v80
	v_rcp_f32_e32 v81, v81
	s_nop 0
	v_pk_mul_f32 v[68:69], v[68:69], v[80:81]
	s_nop 0
	v_pk_mul_f32 v[80:81], v[92:93], v[68:69]
	v_cvt_pk_bf16_f32 v68, v70, v71
	v_cvt_pk_bf16_f32 v69, v80, v81
	v_mad_i64_i32 v[70:71], s[2:3], v120, s8, v[98:99]
	global_store_dwordx4 v[70:71], v[66:69], off
	s_nop 1
	v_mad_i64_i32 v[66:67], s[2:3], v124, s40, v[100:101]
	v_lshl_add_u64 v[80:81], v[66:67], 0, v[96:97]
	s_waitcnt vmcnt(1)
	v_mov_b32_e32 v68, v244
	v_mov_b32_e32 v69, v245
	v_mov_b32_e32 v70, v246
	v_mov_b32_e32 v71, v247
	v_lshlrev_b32_e32 v92, 16, v68
	v_and_b32_e32 v93, 0xffff0000, v68
	v_lshlrev_b32_e32 v72, 16, v69
	v_and_b32_e32 v73, 0xffff0000, v69
	v_lshlrev_b32_e32 v68, 16, v70
	v_and_b32_e32 v69, 0xffff0000, v70
	v_add_co_u32_e32 v70, vcc, s75, v80
	v_lshlrev_b32_e32 v66, 16, v71
	v_and_b32_e32 v67, 0xffff0000, v71
	v_addc_co_u32_e32 v71, vcc, 0, v81, vcc
	v_mov_b32_e32 v120, v248
	v_mov_b32_e32 v121, v249
	v_mov_b32_e32 v122, v250
	v_mov_b32_e32 v123, v251
	v_pk_fma_f32 v[90:91], v[52:53], v[92:93], v[90:91]
	v_pk_fma_f32 v[88:89], v[54:55], v[72:73], v[88:89]
	v_mul_f32_e32 v104, 0xbfb8aa3b, v90
	v_mul_f32_e32 v105, 0xbfb8aa3b, v91
	v_exp_f32_e32 v104, v104
	v_exp_f32_e32 v105, v105
	v_pk_fma_f32 v[86:87], v[20:21], v[68:69], v[86:87]
	v_pk_fma_f32 v[84:85], v[22:23], v[66:67], v[84:85]
	v_add_f32_e32 v104, 1.0, v104
	v_add_f32_e32 v105, 1.0, v105
	v_rcp_f32_e32 v104, v104
	v_rcp_f32_e32 v105, v105
	v_pk_fma_f32 v[4:5], v[12:13], v[68:69], v[4:5]
	v_pk_fma_f32 v[36:37], v[44:45], v[92:93], v[36:37]
	v_pk_mul_f32 v[90:91], v[90:91], v[104:105]
	v_mul_f32_e32 v104, 0xbfb8aa3b, v88
	v_mul_f32_e32 v105, 0xbfb8aa3b, v89
	v_exp_f32_e32 v104, v104
	v_exp_f32_e32 v105, v105
	v_add_f32_e32 v104, 1.0, v104
	v_add_f32_e32 v105, 1.0, v105
	v_rcp_f32_e32 v104, v104
	v_rcp_f32_e32 v105, v105
	v_add_co_u32_e32 v252, vcc, 0x5600, v252
	s_nop 1
	v_addc_co_u32_e32 v253, vcc, 0, v253, vcc
	global_load_dwordx4 v[244:247], v[252:253], off
	v_add_co_u32_e32 v248, vcc, 0x2b00, v252
	s_nop 1
	v_addc_co_u32_e32 v249, vcc, 0, v253, vcc
	global_load_dwordx4 v[248:251], v[248:249], off
	v_lshlrev_b32_e32 v102, 16, v120
	v_pk_mul_f32 v[88:89], v[88:89], v[104:105]
	v_mul_f32_e32 v104, 0xbfb8aa3b, v86
	v_mul_f32_e32 v105, 0xbfb8aa3b, v87
	v_exp_f32_e32 v104, v104
	v_exp_f32_e32 v105, v105
	v_and_b32_e32 v103, 0xffff0000, v120
	v_lshlrev_b32_e32 v94, 16, v121
	v_add_f32_e32 v104, 1.0, v104
	v_add_f32_e32 v105, 1.0, v105
	v_rcp_f32_e32 v104, v104
	v_rcp_f32_e32 v105, v105
	v_and_b32_e32 v95, 0xffff0000, v121
	v_lshlrev_b32_e32 v80, 16, v122
	v_and_b32_e32 v81, 0xffff0000, v122
	v_pk_mul_f32 v[86:87], v[86:87], v[104:105]
	v_mul_f32_e32 v104, 0xbfb8aa3b, v84
	v_mul_f32_e32 v105, 0xbfb8aa3b, v85
	v_exp_f32_e32 v104, v104
	v_exp_f32_e32 v105, v105
	v_lshlrev_b32_e32 v70, 16, v123
	v_and_b32_e32 v71, 0xffff0000, v123
	v_add_f32_e32 v104, 1.0, v104
	v_add_f32_e32 v105, 1.0, v105
	v_rcp_f32_e32 v104, v104
	v_rcp_f32_e32 v105, v105
	v_pk_fma_f32 v[112:113], v[48:49], v[102:103], v[112:113]
	v_pk_fma_f32 v[110:111], v[50:51], v[94:95], v[110:111]
	v_pk_fma_f32 v[108:109], v[16:17], v[80:81], v[108:109]
	v_pk_fma_f32 v[106:107], v[18:19], v[70:71], v[106:107]
	v_pk_mul_f32 v[84:85], v[84:85], v[104:105]
	v_pk_mul_f32 v[90:91], v[112:113], v[90:91]
	v_pk_mul_f32 v[88:89], v[110:111], v[88:89]
	v_pk_mul_f32 v[86:87], v[108:109], v[86:87]
	v_pk_mul_f32 v[104:105], v[106:107], v[84:85]
	v_cvt_pk_bf16_f32 v84, v90, v91
	v_cvt_pk_bf16_f32 v85, v88, v89
	v_cvt_pk_bf16_f32 v86, v86, v87
	v_cvt_pk_bf16_f32 v87, v104, v105
	v_mad_i64_i32 v[88:89], s[2:3], v124, s8, v[98:99]
	v_or_b32_e32 v108, 7, v137
	global_store_dwordx4 v[88:89], v[84:87], off
	v_pk_fma_f32 v[0:1], v[8:9], v[80:81], v[0:1]
	v_pk_fma_f32 v[32:33], v[40:41], v[102:103], v[32:33]
	v_mad_i64_i32 v[84:85], s[2:3], v108, s40, v[100:101]
	v_lshl_add_u64 v[88:89], v[84:85], 0, v[96:97]
	s_waitcnt vmcnt(1)
	v_mov_b32_e32 v84, v244
	v_mov_b32_e32 v85, v245
	v_mov_b32_e32 v86, v246
	v_mov_b32_e32 v87, v247
	v_pk_fma_f32 v[2:3], v[10:11], v[70:71], v[2:3]
	v_pk_fma_f32 v[34:35], v[42:43], v[94:95], v[34:35]
	v_lshlrev_b32_e32 v100, 16, v86
	v_and_b32_e32 v101, 0xffff0000, v86
	v_add_co_u32_e32 v86, vcc, s75, v88
	v_lshlrev_b32_e32 v90, 16, v84
	v_and_b32_e32 v91, 0xffff0000, v84
	v_lshlrev_b32_e32 v96, 16, v85
	v_and_b32_e32 v97, 0xffff0000, v85
	v_lshlrev_b32_e32 v84, 16, v87
	v_and_b32_e32 v85, 0xffff0000, v87
	v_addc_co_u32_e32 v87, vcc, 0, v89, vcc
	v_mov_b32_e32 v86, v248
	v_mov_b32_e32 v87, v249
	v_mov_b32_e32 v88, v250
	v_mov_b32_e32 v89, v251
	v_pk_fma_f32 v[4:5], v[20:21], v[100:101], v[4:5]
	v_pk_fma_f32 v[36:37], v[52:53], v[90:91], v[36:37]
	v_mul_f32_e32 v12, 0xbfb8aa3b, v4
	v_mul_f32_e32 v8, 0xbfb8aa3b, v5
	v_exp_f32_e32 v12, v12
	v_exp_f32_e32 v8, v8
	v_mul_f32_e32 v44, 0xbfb8aa3b, v36
	v_mul_f32_e32 v40, 0xbfb8aa3b, v37
	v_exp_f32_e32 v44, v44
	v_exp_f32_e32 v40, v40
	v_add_f32_e32 v12, 1.0, v12
	v_add_f32_e32 v8, 1.0, v8
	v_rcp_f32_e32 v12, v12
	v_rcp_f32_e32 v13, v8
	v_add_f32_e32 v44, 1.0, v44
	v_add_f32_e32 v40, 1.0, v40
	v_rcp_f32_e32 v44, v44
	v_rcp_f32_e32 v45, v40
	v_pk_mul_f32 v[4:5], v[4:5], v[12:13]
	v_pk_mul_f32 v[36:37], v[36:37], v[44:45]
	v_lshlrev_b32_e32 v106, 16, v88
	v_and_b32_e32 v107, 0xffff0000, v88
	v_pk_fma_f32 v[0:1], v[16:17], v[106:107], v[0:1]
	v_lshlrev_b32_e32 v104, 16, v86
	v_and_b32_e32 v105, 0xffff0000, v86
	v_pk_mul_f32 v[4:5], v[0:1], v[4:5]
	v_pk_fma_f32 v[0:1], v[6:7], v[74:75], v[30:31]
	v_pk_fma_f32 v[32:33], v[48:49], v[104:105], v[32:33]
	v_pk_fma_f32 v[0:1], v[14:15], v[66:67], v[0:1]
	v_pk_mul_f32 v[32:33], v[32:33], v[36:37]
	v_pk_fma_f32 v[36:37], v[38:39], v[78:79], v[62:63]
	v_pk_fma_f32 v[0:1], v[22:23], v[84:85], v[0:1]
	v_pk_fma_f32 v[36:37], v[46:47], v[72:73], v[36:37]
	v_mul_f32_e32 v6, 0xbfb8aa3b, v0
	v_mul_f32_e32 v7, 0xbfb8aa3b, v1
	v_pk_fma_f32 v[36:37], v[54:55], v[96:97], v[36:37]
	v_exp_f32_e32 v6, v6
	v_exp_f32_e32 v7, v7
	v_mul_f32_e32 v38, 0xbfb8aa3b, v36
	v_mul_f32_e32 v39, 0xbfb8aa3b, v37
	v_exp_f32_e32 v38, v38
	v_exp_f32_e32 v39, v39
	v_add_f32_e32 v6, 1.0, v6
	v_add_f32_e32 v7, 1.0, v7
	v_rcp_f32_e32 v6, v6
	v_rcp_f32_e32 v7, v7
	v_add_f32_e32 v38, 1.0, v38
	v_add_f32_e32 v39, 1.0, v39
	v_rcp_f32_e32 v38, v38
	v_rcp_f32_e32 v39, v39
	v_lshlrev_b32_e32 v88, 16, v89
	v_and_b32_e32 v89, 0xffff0000, v89
	v_pk_fma_f32 v[2:3], v[18:19], v[88:89], v[2:3]
	v_pk_mul_f32 v[0:1], v[0:1], v[6:7]
	v_lshlrev_b32_e32 v86, 16, v87
	v_and_b32_e32 v87, 0xffff0000, v87
	v_pk_mul_f32 v[6:7], v[2:3], v[0:1]
	v_cvt_pk_bf16_f32 v2, v4, v5
	v_mad_i64_i32 v[4:5], s[2:3], v108, s8, v[98:99]
	v_pk_fma_f32 v[34:35], v[50:51], v[86:87], v[34:35]
	v_pk_mul_f32 v[36:37], v[36:37], v[38:39]
	s_mov_b32 s2, 0xc17ff
	v_pk_mul_f32 v[34:35], v[34:35], v[36:37]
	v_cmp_lt_i32_e32 vcc, s2, v135
	v_cvt_pk_bf16_f32 v0, v32, v33
	v_cvt_pk_bf16_f32 v1, v34, v35
	v_cvt_pk_bf16_f32 v3, v6, v7
	s_or_b64 s[6:7], vcc, s[6:7]
	global_store_dwordx4 v[4:5], v[0:3], off
	s_andn2_b64 exec, exec, s[6:7]
	s_cbranch_execz .LBB0_1480
